# v12 + last k-iteration of a blocks final GEMM unit runs from a copy without the 14 dummy next-unit LDS-DMA prefetch loads (all 4 GEMM kinds)
# baseline (speedup 1.0000x reference)
.LBB0_211:
	s_add_i32 s60, s60, 1
	s_mov_b64 s[36:37], s[18:19]
	s_mul_i32 s18, s60, s26
	s_add_i32 s38, s18, s2
	s_cmpk_gt_i32 s38, 0x1ff
	s_cselect_b64 s[44:45], -1, 0
	s_cselect_b32 s32, 11, 13
	s_lshl_b32 s18, s38, 3
	s_and_b32 s18, s18, 56
	s_bfe_u32 s19, s38, 0x30003
	s_mov_b32 s27, s61
	s_or_b32 s61, s18, s19
	s_mov_b32 s3, s42
	s_ashr_i32 s42, s38, 6
	s_lshl_b32 s18, s61, 19
	s_mov_b64 s[4:5], s[20:21]
	s_add_u32 s20, s14, s18
	s_addc_u32 s21, s15, 0
	s_ashr_i32 s43, s42, 31
	s_lshl_b64 s[18:19], s[42:43], 19
	s_add_u32 s18, s16, s18
	s_addc_u32 s19, s17, s19
	s_cmpk_lt_i32 s38, 0x200
	s_cselect_b32 s38, s21, s5
	s_cselect_b32 s43, s20, s4
	s_cselect_b32 s62, s19, s37
	s_cselect_b32 s63, s18, s36
	s_add_u32 s64, s36, 0x100
	s_addc_u32 s65, s37, 0
	s_mov_b32 s66, -2
	s_waitcnt lgkmcnt(0)
	s_add_u32 s36, s4, 0x100
	s_addc_u32 s37, s5, 0
	s_add_i32 s67, 0, 0x10000
	v_add_u32_e32 v1, s67, v191
	ds_read_b128 v[34:37], v1
	ds_read_b128 v[38:41], v1 offset:1024
	ds_read_b128 v[42:45], v1 offset:2048
	ds_read_b128 v[46:49], v1 offset:3072
	s_cmp_eq_u32 s66, 12
	s_cselect_b32 s49, s38, s37
	s_cselect_b32 s48, s43, s36
	s_cselect_b32 s47, s62, s65
	s_cselect_b32 s46, s63, s64
	v_lshl_add_u64 v[186:187], s[4:5], 0, v[168:169]
	s_add_i32 m0, s53, 0xc000
	ds_read_b128 v[50:53], v206
	ds_read_b128 v[58:61], v206 offset:1024
	ds_read_b128 v[62:65], v206 offset:2048
	ds_read_b128 v[66:69], v206 offset:3072
	ds_read_b128 v[170:173], v206 offset:4096
	ds_read_b128 v[174:177], v206 offset:5120
	ds_read_b128 v[178:181], v206 offset:6144
	ds_read_b128 v[182:185], v206 offset:7168
	global_load_lds_dwordx4 v[186:187], off
	v_lshl_add_u64 v[186:187], s[4:5], 0, v[166:167]
	s_add_i32 m0, s53, 0xe000
	s_nop 0
	global_load_lds_dwordx4 v[186:187], off
	s_waitcnt lgkmcnt(8)
	s_barrier
	s_waitcnt lgkmcnt(0)
	s_setprio 1
	s_waitcnt lgkmcnt(0)
	v_mfma_f32_16x16x32_bf16 v[158:161], v[34:37], v[50:53], 0
	v_mfma_f32_16x16x32_bf16 v[154:157], v[42:45], v[50:53], 0
	v_mfma_f32_16x16x32_bf16 v[142:145], v[34:37], v[62:65], 0
	v_mfma_f32_16x16x32_bf16 v[138:141], v[42:45], v[62:65], 0
	v_mfma_f32_16x16x32_bf16 v[126:129], v[34:37], v[170:173], 0
	v_mfma_f32_16x16x32_bf16 v[122:125], v[42:45], v[170:173], 0
	v_mfma_f32_16x16x32_bf16 v[110:113], v[34:37], v[178:181], 0
	v_mfma_f32_16x16x32_bf16 v[106:109], v[42:45], v[178:181], 0
	v_mfma_f32_16x16x32_bf16 v[158:161], v[38:41], v[58:61], v[158:161]
	v_mfma_f32_16x16x32_bf16 v[154:157], v[46:49], v[58:61], v[154:157]
	v_mfma_f32_16x16x32_bf16 v[142:145], v[38:41], v[66:69], v[142:145]
	v_mfma_f32_16x16x32_bf16 v[138:141], v[46:49], v[66:69], v[138:141]
	v_mfma_f32_16x16x32_bf16 v[126:129], v[38:41], v[174:177], v[126:129]
	v_mfma_f32_16x16x32_bf16 v[122:125], v[46:49], v[174:177], v[122:125]
	v_mfma_f32_16x16x32_bf16 v[110:113], v[38:41], v[182:185], v[110:113]
	v_mfma_f32_16x16x32_bf16 v[106:109], v[46:49], v[182:185], v[106:109]
	s_setprio 0
	s_barrier
	s_add_i32 s68, 0, 0x14000
	s_add_i32 s4, s67, s52
	v_add_u32_e32 v1, s68, v191
	v_lshl_add_u64 v[214:215], s[46:47], 0, v[164:165]
	s_mov_b32 m0, s4
	ds_read_b128 v[186:189], v1
	ds_read_b128 v[208:211], v1 offset:1024
	ds_read_b128 v[222:225], v1 offset:2048
	ds_read_b128 v[226:229], v1 offset:3072
	global_load_lds_dwordx4 v[214:215], off
	v_lshl_add_u64 v[238:239], s[46:47], 0, v[162:163]
	s_add_i32 m0, s4, 0x2000
	s_nop 0
	global_load_lds_dwordx4 v[238:239], off
	s_barrier
	s_waitcnt lgkmcnt(0)
	s_setprio 1
	s_waitcnt lgkmcnt(0)
	v_mfma_f32_16x16x32_bf16 v[150:153], v[186:189], v[50:53], 0
	v_mfma_f32_16x16x32_bf16 v[50:53], v[222:225], v[50:53], 0
	v_mfma_f32_16x16x32_bf16 v[150:153], v[208:211], v[58:61], v[150:153]
	v_mfma_f32_16x16x32_bf16 v[50:53], v[226:229], v[58:61], v[50:53]
	v_mfma_f32_16x16x32_bf16 v[58:61], v[186:189], v[62:65], 0
	v_mfma_f32_16x16x32_bf16 v[62:65], v[222:225], v[62:65], 0
	v_mfma_f32_16x16x32_bf16 v[114:117], v[222:225], v[170:173], 0
	v_mfma_f32_16x16x32_bf16 v[102:105], v[186:189], v[178:181], 0
	v_mfma_f32_16x16x32_bf16 v[98:101], v[222:225], v[178:181], 0
	v_mfma_f32_16x16x32_bf16 v[58:61], v[208:211], v[66:69], v[58:61]
	v_mfma_f32_16x16x32_bf16 v[62:65], v[226:229], v[66:69], v[62:65]
	v_mfma_f32_16x16x32_bf16 v[66:69], v[186:189], v[170:173], 0
	v_mfma_f32_16x16x32_bf16 v[114:117], v[226:229], v[174:177], v[114:117]
	v_mfma_f32_16x16x32_bf16 v[102:105], v[208:211], v[182:185], v[102:105]
	v_mfma_f32_16x16x32_bf16 v[98:101], v[226:229], v[182:185], v[98:101]
	v_mfma_f32_16x16x32_bf16 v[66:69], v[208:211], v[174:177], v[66:69]
	s_setprio 0
	s_mov_b32 m0, s53
	v_lshl_add_u64 v[240:241], s[48:49], 0, v[164:165]
	s_barrier
	ds_read_b128 v[118:121], v206 offset:16384
	ds_read_b128 v[130:133], v206 offset:17408
	ds_read_b128 v[134:137], v206 offset:18432
	ds_read_b128 v[146:149], v206 offset:19456
	ds_read_b128 v[170:173], v206 offset:20480
	ds_read_b128 v[174:177], v206 offset:21504
	ds_read_b128 v[178:181], v206 offset:22528
	ds_read_b128 v[182:185], v206 offset:23552
	global_load_lds_dwordx4 v[240:241], off
	v_lshl_add_u64 v[242:243], s[48:49], 0, v[162:163]
	s_mov_b32 m0, s54
	s_nop 0
	global_load_lds_dwordx4 v[242:243], off
	s_barrier
	s_waitcnt lgkmcnt(0)
	s_setprio 1
	s_waitcnt lgkmcnt(0)
	v_mfma_f32_16x16x32_bf16 v[94:97], v[34:37], v[118:121], 0
	v_mfma_f32_16x16x32_bf16 v[90:93], v[42:45], v[118:121], 0
	v_mfma_f32_16x16x32_bf16 v[78:81], v[34:37], v[134:137], 0
	v_mfma_f32_16x16x32_bf16 v[74:77], v[42:45], v[134:137], 0
	v_mfma_f32_16x16x32_bf16 v[30:33], v[34:37], v[170:173], 0
	v_mfma_f32_16x16x32_bf16 v[26:29], v[42:45], v[170:173], 0
	v_mfma_f32_16x16x32_bf16 v[14:17], v[34:37], v[178:181], 0
	v_mfma_f32_16x16x32_bf16 v[10:13], v[42:45], v[178:181], 0
	v_mfma_f32_16x16x32_bf16 v[94:97], v[38:41], v[130:133], v[94:97]
	v_mfma_f32_16x16x32_bf16 v[90:93], v[46:49], v[130:133], v[90:93]
	v_mfma_f32_16x16x32_bf16 v[78:81], v[38:41], v[146:149], v[78:81]
	v_mfma_f32_16x16x32_bf16 v[74:77], v[46:49], v[146:149], v[74:77]
	v_mfma_f32_16x16x32_bf16 v[30:33], v[38:41], v[174:177], v[30:33]
	v_mfma_f32_16x16x32_bf16 v[26:29], v[46:49], v[174:177], v[26:29]
	v_mfma_f32_16x16x32_bf16 v[14:17], v[38:41], v[182:185], v[14:17]
	v_mfma_f32_16x16x32_bf16 v[10:13], v[46:49], v[182:185], v[10:13]
	s_setprio 0
	s_barrier
	s_add_u32 s4, s46, 0x40000
	s_addc_u32 s5, s47, 0
	s_add_i32 s67, s68, s52
	v_lshl_add_u64 v[34:35], s[4:5], 0, v[164:165]
	s_mov_b32 m0, s67
	s_nop 0
	global_load_lds_dwordx4 v[34:35], off
	v_lshl_add_u64 v[34:35], s[4:5], 0, v[162:163]
	s_add_i32 m0, s67, 0x2000
	s_nop 0
	global_load_lds_dwordx4 v[34:35], off
	s_waitcnt vmcnt(6)
	s_barrier
	s_setprio 1
	v_mfma_f32_16x16x32_bf16 v[22:25], v[186:189], v[170:173], 0
	v_mfma_f32_16x16x32_bf16 v[18:21], v[222:225], v[170:173], 0
	v_mfma_f32_16x16x32_bf16 v[6:9], v[186:189], v[178:181], 0
	v_mfma_f32_16x16x32_bf16 v[2:5], v[222:225], v[178:181], 0
	v_mfma_f32_16x16x32_bf16 v[34:37], v[186:189], v[118:121], 0
	v_mfma_f32_16x16x32_bf16 v[38:41], v[222:225], v[118:121], 0
	v_mfma_f32_16x16x32_bf16 v[42:45], v[186:189], v[134:137], 0
	v_mfma_f32_16x16x32_bf16 v[46:49], v[222:225], v[134:137], 0
	v_mfma_f32_16x16x32_bf16 v[22:25], v[208:211], v[174:177], v[22:25]
	v_mfma_f32_16x16x32_bf16 v[18:21], v[226:229], v[174:177], v[18:21]
	v_mfma_f32_16x16x32_bf16 v[6:9], v[208:211], v[182:185], v[6:9]
	v_mfma_f32_16x16x32_bf16 v[2:5], v[226:229], v[182:185], v[2:5]
	v_mfma_f32_16x16x32_bf16 v[34:37], v[208:211], v[130:133], v[34:37]
	v_mfma_f32_16x16x32_bf16 v[38:41], v[226:229], v[130:133], v[38:41]
	v_mfma_f32_16x16x32_bf16 v[42:45], v[208:211], v[146:149], v[42:45]
	v_mfma_f32_16x16x32_bf16 v[46:49], v[226:229], v[146:149], v[46:49]
	s_setprio 0
	s_add_i32 s67, 0, 0x18000
	v_add_u32_e32 v1, s67, v191
	s_barrier
	ds_read_b128 v[54:57], v1
	ds_read_b128 v[70:73], v1 offset:1024
	ds_read_b128 v[82:85], v1 offset:2048
	ds_read_b128 v[86:89], v1 offset:3072
	s_add_u32 s4, s48, 0x40000
	s_addc_u32 s5, s49, 0
	s_mov_b32 m0, s55
	v_lshl_add_u64 v[134:135], s[4:5], 0, v[164:165]
	ds_read_b128 v[118:121], v206 offset:32768
	ds_read_b128 v[130:133], v206 offset:33792
	ds_read_b128 v[170:173], v206 offset:34816
	ds_read_b128 v[174:177], v206 offset:35840
	ds_read_b128 v[178:181], v206 offset:36864
	ds_read_b128 v[182:185], v206 offset:37888
	ds_read_b128 v[186:189], v206 offset:38912
	ds_read_b128 v[208:211], v206 offset:39936
	global_load_lds_dwordx4 v[134:135], off
	v_lshl_add_u64 v[134:135], s[4:5], 0, v[162:163]
	s_mov_b32 m0, s56
	s_nop 0
	global_load_lds_dwordx4 v[134:135], off
	s_waitcnt lgkmcnt(8)
	s_barrier
	s_waitcnt lgkmcnt(0)
	s_setprio 1
	s_waitcnt lgkmcnt(0)
	v_mfma_f32_16x16x32_bf16 v[134:137], v[54:57], v[118:121], v[158:161]
	v_mfma_f32_16x16x32_bf16 v[158:161], v[70:73], v[130:133], v[134:137]
	v_mfma_f32_16x16x32_bf16 v[134:137], v[82:85], v[118:121], v[154:157]
	v_mfma_f32_16x16x32_bf16 v[154:157], v[86:89], v[130:133], v[134:137]
	v_mfma_f32_16x16x32_bf16 v[134:137], v[54:57], v[170:173], v[142:145]
	v_mfma_f32_16x16x32_bf16 v[142:145], v[70:73], v[174:177], v[134:137]
	v_mfma_f32_16x16x32_bf16 v[134:137], v[82:85], v[170:173], v[138:141]
	v_mfma_f32_16x16x32_bf16 v[126:129], v[54:57], v[178:181], v[126:129]
	v_mfma_f32_16x16x32_bf16 v[122:125], v[82:85], v[178:181], v[122:125]
	v_mfma_f32_16x16x32_bf16 v[110:113], v[54:57], v[186:189], v[110:113]
	v_mfma_f32_16x16x32_bf16 v[106:109], v[82:85], v[186:189], v[106:109]
	v_mfma_f32_16x16x32_bf16 v[138:141], v[86:89], v[174:177], v[134:137]
	v_mfma_f32_16x16x32_bf16 v[126:129], v[70:73], v[182:185], v[126:129]
	v_mfma_f32_16x16x32_bf16 v[122:125], v[86:89], v[182:185], v[122:125]
	v_mfma_f32_16x16x32_bf16 v[110:113], v[70:73], v[208:211], v[110:113]
	v_mfma_f32_16x16x32_bf16 v[106:109], v[86:89], v[208:211], v[106:109]
	s_setprio 0
	s_barrier
	s_add_i32 s48, 0, 0x1c000
	s_add_i32 s4, s67, s52
	v_add_u32_e32 v1, s48, v191
	v_lshl_add_u64 v[134:135], v[214:215], 0, s[22:23]
	s_mov_b32 m0, s4
	ds_read_b128 v[222:225], v1
	ds_read_b128 v[226:229], v1 offset:1024
	ds_read_b128 v[230:233], v1 offset:2048
	ds_read_b128 v[234:237], v1 offset:3072
	global_load_lds_dwordx4 v[134:135], off
	v_lshl_add_u64 v[134:135], v[238:239], 0, s[22:23]
	s_add_i32 m0, s4, 0x2000
	s_nop 0
	global_load_lds_dwordx4 v[134:135], off
	s_barrier
	s_waitcnt lgkmcnt(0)
	s_setprio 1
	s_waitcnt lgkmcnt(0)
	v_mfma_f32_16x16x32_bf16 v[50:53], v[230:233], v[118:121], v[50:53]
	v_mfma_f32_16x16x32_bf16 v[134:137], v[222:225], v[118:121], v[150:153]
	v_mfma_f32_16x16x32_bf16 v[146:149], v[234:237], v[130:133], v[50:53]
	v_mfma_f32_16x16x32_bf16 v[50:53], v[222:225], v[170:173], v[58:61]
	v_mfma_f32_16x16x32_bf16 v[150:153], v[226:229], v[130:133], v[134:137]
	v_mfma_f32_16x16x32_bf16 v[134:137], v[226:229], v[174:177], v[50:53]
	v_mfma_f32_16x16x32_bf16 v[50:53], v[230:233], v[170:173], v[62:65]
	v_mfma_f32_16x16x32_bf16 v[130:133], v[234:237], v[174:177], v[50:53]
	v_mfma_f32_16x16x32_bf16 v[50:53], v[222:225], v[178:181], v[66:69]
	v_mfma_f32_16x16x32_bf16 v[118:121], v[226:229], v[182:185], v[50:53]
	v_mfma_f32_16x16x32_bf16 v[50:53], v[230:233], v[178:181], v[114:117]
	v_mfma_f32_16x16x32_bf16 v[114:117], v[234:237], v[182:185], v[50:53]
	v_mfma_f32_16x16x32_bf16 v[50:53], v[222:225], v[186:189], v[102:105]
	v_mfma_f32_16x16x32_bf16 v[102:105], v[226:229], v[208:211], v[50:53]
	v_mfma_f32_16x16x32_bf16 v[50:53], v[230:233], v[186:189], v[98:101]
	v_mfma_f32_16x16x32_bf16 v[98:101], v[234:237], v[208:211], v[50:53]
	s_setprio 0
	s_mov_b32 m0, s58
	v_lshl_add_u64 v[186:187], v[240:241], 0, s[22:23]
	s_barrier
	s_nop 2
	ds_read_b128 v[50:53], v206 offset:49152
	ds_read_b128 v[58:61], v206 offset:50176
	ds_read_b128 v[62:65], v206 offset:51200
	ds_read_b128 v[66:69], v206 offset:52224
	ds_read_b128 v[170:173], v206 offset:53248
	ds_read_b128 v[174:177], v206 offset:54272
	ds_read_b128 v[178:181], v206 offset:55296
	ds_read_b128 v[182:185], v206 offset:56320
	global_load_lds_dwordx4 v[186:187], off
	v_lshl_add_u64 v[186:187], v[242:243], 0, s[22:23]
	s_mov_b32 m0, s59
	s_nop 0
	global_load_lds_dwordx4 v[186:187], off
	s_barrier
	s_waitcnt lgkmcnt(0)
	s_setprio 1
	s_waitcnt lgkmcnt(0)
	v_mfma_f32_16x16x32_bf16 v[94:97], v[54:57], v[50:53], v[94:97]
	v_mfma_f32_16x16x32_bf16 v[90:93], v[82:85], v[50:53], v[90:93]
	v_mfma_f32_16x16x32_bf16 v[78:81], v[54:57], v[62:65], v[78:81]
	v_mfma_f32_16x16x32_bf16 v[74:77], v[82:85], v[62:65], v[74:77]
	v_mfma_f32_16x16x32_bf16 v[30:33], v[54:57], v[170:173], v[30:33]
	v_mfma_f32_16x16x32_bf16 v[26:29], v[82:85], v[170:173], v[26:29]
	v_mfma_f32_16x16x32_bf16 v[14:17], v[54:57], v[178:181], v[14:17]
	v_mfma_f32_16x16x32_bf16 v[10:13], v[82:85], v[178:181], v[10:13]
	v_mfma_f32_16x16x32_bf16 v[94:97], v[70:73], v[58:61], v[94:97]
	v_mfma_f32_16x16x32_bf16 v[90:93], v[86:89], v[58:61], v[90:93]
	v_mfma_f32_16x16x32_bf16 v[78:81], v[70:73], v[66:69], v[78:81]
	v_mfma_f32_16x16x32_bf16 v[74:77], v[86:89], v[66:69], v[74:77]
	v_mfma_f32_16x16x32_bf16 v[30:33], v[70:73], v[174:177], v[30:33]
	v_mfma_f32_16x16x32_bf16 v[26:29], v[86:89], v[174:177], v[26:29]
	v_mfma_f32_16x16x32_bf16 v[14:17], v[70:73], v[182:185], v[14:17]
	v_mfma_f32_16x16x32_bf16 v[10:13], v[86:89], v[182:185], v[10:13]
	s_setprio 0
	s_barrier
	s_add_u32 s4, s46, 0x40080
	s_addc_u32 s5, s47, 0
	s_add_i32 s46, s48, s52
	v_lshl_add_u64 v[54:55], s[4:5], 0, v[164:165]
	s_mov_b32 m0, s46
	s_nop 0
	global_load_lds_dwordx4 v[54:55], off
	v_lshl_add_u64 v[54:55], s[4:5], 0, v[162:163]
	s_add_i32 m0, s46, 0x2000
	s_nop 0
	global_load_lds_dwordx4 v[54:55], off
	s_waitcnt vmcnt(6)
	s_barrier
	s_setprio 1
	v_mfma_f32_16x16x32_bf16 v[34:37], v[222:225], v[50:53], v[34:37]
	v_mfma_f32_16x16x32_bf16 v[86:89], v[226:229], v[58:61], v[34:37]
	v_mfma_f32_16x16x32_bf16 v[34:37], v[230:233], v[50:53], v[38:41]
	v_mfma_f32_16x16x32_bf16 v[82:85], v[234:237], v[58:61], v[34:37]
	v_mfma_f32_16x16x32_bf16 v[34:37], v[222:225], v[62:65], v[42:45]
	v_mfma_f32_16x16x32_bf16 v[70:73], v[226:229], v[66:69], v[34:37]
	v_mfma_f32_16x16x32_bf16 v[34:37], v[230:233], v[62:65], v[46:49]
	v_mfma_f32_16x16x32_bf16 v[22:25], v[222:225], v[170:173], v[22:25]
	v_mfma_f32_16x16x32_bf16 v[18:21], v[230:233], v[170:173], v[18:21]
	v_mfma_f32_16x16x32_bf16 v[6:9], v[222:225], v[178:181], v[6:9]
	v_mfma_f32_16x16x32_bf16 v[2:5], v[230:233], v[178:181], v[2:5]
	v_mfma_f32_16x16x32_bf16 v[54:57], v[234:237], v[66:69], v[34:37]
	v_mfma_f32_16x16x32_bf16 v[22:25], v[226:229], v[174:177], v[22:25]
	v_mfma_f32_16x16x32_bf16 v[18:21], v[234:237], v[174:177], v[18:21]
	v_mfma_f32_16x16x32_bf16 v[6:9], v[226:229], v[182:185], v[6:9]
	v_mfma_f32_16x16x32_bf16 v[2:5], v[234:237], v[182:185], v[2:5]
	s_setprio 0
	s_add_i32 s66, s66, 2
	s_add_u32 s64, s64, 0x100
	s_addc_u32 s65, s65, 0
	s_cmp_gt_u32 s66, 13
	s_mov_b64 s[4:5], s[36:37]
	s_barrier
.LBB0_212:
	s_add_u32 s36, s4, 0x100
	s_addc_u32 s37, s5, 0
	s_add_i32 s67, 0, 0x10000
	v_add_u32_e32 v1, s67, v191
	ds_read_b128 v[34:37], v1
	ds_read_b128 v[38:41], v1 offset:1024
	ds_read_b128 v[42:45], v1 offset:2048
	ds_read_b128 v[46:49], v1 offset:3072
	s_cmp_eq_u32 s66, 12
	s_cselect_b32 s49, s38, s37
	s_cselect_b32 s48, s43, s36
	s_cselect_b32 s47, s62, s65
	s_cselect_b32 s46, s63, s64
	v_lshl_add_u64 v[186:187], s[4:5], 0, v[168:169]
	s_add_i32 m0, s53, 0xc000
	ds_read_b128 v[50:53], v206
	ds_read_b128 v[58:61], v206 offset:1024
	ds_read_b128 v[62:65], v206 offset:2048
	ds_read_b128 v[66:69], v206 offset:3072
	ds_read_b128 v[170:173], v206 offset:4096
	ds_read_b128 v[174:177], v206 offset:5120
	ds_read_b128 v[178:181], v206 offset:6144
	ds_read_b128 v[182:185], v206 offset:7168
	global_load_lds_dwordx4 v[186:187], off
	v_lshl_add_u64 v[186:187], s[4:5], 0, v[166:167]
	s_add_i32 m0, s53, 0xe000
	s_nop 0
	global_load_lds_dwordx4 v[186:187], off
	s_waitcnt lgkmcnt(8)
	s_barrier
	s_waitcnt lgkmcnt(0)
	s_setprio 1
	s_waitcnt lgkmcnt(0)
	v_mfma_f32_16x16x32_bf16 v[158:161], v[34:37], v[50:53], v[158:161]
	v_mfma_f32_16x16x32_bf16 v[154:157], v[42:45], v[50:53], v[154:157]
	v_mfma_f32_16x16x32_bf16 v[142:145], v[34:37], v[62:65], v[142:145]
	v_mfma_f32_16x16x32_bf16 v[138:141], v[42:45], v[62:65], v[138:141]
	v_mfma_f32_16x16x32_bf16 v[126:129], v[34:37], v[170:173], v[126:129]
	v_mfma_f32_16x16x32_bf16 v[122:125], v[42:45], v[170:173], v[122:125]
	v_mfma_f32_16x16x32_bf16 v[110:113], v[34:37], v[178:181], v[110:113]
	v_mfma_f32_16x16x32_bf16 v[106:109], v[42:45], v[178:181], v[106:109]
	v_mfma_f32_16x16x32_bf16 v[158:161], v[38:41], v[58:61], v[158:161]
	v_mfma_f32_16x16x32_bf16 v[154:157], v[46:49], v[58:61], v[154:157]
	v_mfma_f32_16x16x32_bf16 v[142:145], v[38:41], v[66:69], v[142:145]
	v_mfma_f32_16x16x32_bf16 v[138:141], v[46:49], v[66:69], v[138:141]
	v_mfma_f32_16x16x32_bf16 v[126:129], v[38:41], v[174:177], v[126:129]
	v_mfma_f32_16x16x32_bf16 v[122:125], v[46:49], v[174:177], v[122:125]
	v_mfma_f32_16x16x32_bf16 v[110:113], v[38:41], v[182:185], v[110:113]
	v_mfma_f32_16x16x32_bf16 v[106:109], v[46:49], v[182:185], v[106:109]
	s_setprio 0
	s_barrier
	s_add_i32 s68, 0, 0x14000
	s_add_i32 s4, s67, s52
	v_add_u32_e32 v1, s68, v191
	v_lshl_add_u64 v[214:215], s[46:47], 0, v[164:165]
	s_mov_b32 m0, s4
	ds_read_b128 v[186:189], v1
	ds_read_b128 v[208:211], v1 offset:1024
	ds_read_b128 v[222:225], v1 offset:2048
	ds_read_b128 v[226:229], v1 offset:3072
	global_load_lds_dwordx4 v[214:215], off
	v_lshl_add_u64 v[238:239], s[46:47], 0, v[162:163]
	s_add_i32 m0, s4, 0x2000
	s_nop 0
	global_load_lds_dwordx4 v[238:239], off
	s_barrier
	s_waitcnt lgkmcnt(0)
	s_setprio 1
	s_waitcnt lgkmcnt(0)
	v_mfma_f32_16x16x32_bf16 v[150:153], v[186:189], v[50:53], v[150:153]
	v_mfma_f32_16x16x32_bf16 v[50:53], v[222:225], v[50:53], v[146:149]
	v_mfma_f32_16x16x32_bf16 v[150:153], v[208:211], v[58:61], v[150:153]
	v_mfma_f32_16x16x32_bf16 v[50:53], v[226:229], v[58:61], v[50:53]
	v_mfma_f32_16x16x32_bf16 v[58:61], v[186:189], v[62:65], v[134:137]
	v_mfma_f32_16x16x32_bf16 v[62:65], v[222:225], v[62:65], v[130:133]
	v_mfma_f32_16x16x32_bf16 v[114:117], v[222:225], v[170:173], v[114:117]
	v_mfma_f32_16x16x32_bf16 v[102:105], v[186:189], v[178:181], v[102:105]
	v_mfma_f32_16x16x32_bf16 v[98:101], v[222:225], v[178:181], v[98:101]
	v_mfma_f32_16x16x32_bf16 v[58:61], v[208:211], v[66:69], v[58:61]
	v_mfma_f32_16x16x32_bf16 v[62:65], v[226:229], v[66:69], v[62:65]
	v_mfma_f32_16x16x32_bf16 v[66:69], v[186:189], v[170:173], v[118:121]
	v_mfma_f32_16x16x32_bf16 v[114:117], v[226:229], v[174:177], v[114:117]
	v_mfma_f32_16x16x32_bf16 v[102:105], v[208:211], v[182:185], v[102:105]
	v_mfma_f32_16x16x32_bf16 v[98:101], v[226:229], v[182:185], v[98:101]
	v_mfma_f32_16x16x32_bf16 v[66:69], v[208:211], v[174:177], v[66:69]
	s_setprio 0
	s_mov_b32 m0, s53
	v_lshl_add_u64 v[240:241], s[48:49], 0, v[164:165]
	s_barrier
	ds_read_b128 v[118:121], v206 offset:16384
	ds_read_b128 v[130:133], v206 offset:17408
	ds_read_b128 v[134:137], v206 offset:18432
	ds_read_b128 v[146:149], v206 offset:19456
	ds_read_b128 v[170:173], v206 offset:20480
	ds_read_b128 v[174:177], v206 offset:21504
	ds_read_b128 v[178:181], v206 offset:22528
	ds_read_b128 v[182:185], v206 offset:23552
	global_load_lds_dwordx4 v[240:241], off
	v_lshl_add_u64 v[242:243], s[48:49], 0, v[162:163]
	s_mov_b32 m0, s54
	s_nop 0
	global_load_lds_dwordx4 v[242:243], off
	s_barrier
	s_waitcnt lgkmcnt(0)
	s_setprio 1
	s_waitcnt lgkmcnt(0)
	v_mfma_f32_16x16x32_bf16 v[94:97], v[34:37], v[118:121], v[94:97]
	v_mfma_f32_16x16x32_bf16 v[90:93], v[42:45], v[118:121], v[90:93]
	v_mfma_f32_16x16x32_bf16 v[78:81], v[34:37], v[134:137], v[78:81]
	v_mfma_f32_16x16x32_bf16 v[74:77], v[42:45], v[134:137], v[74:77]
	v_mfma_f32_16x16x32_bf16 v[30:33], v[34:37], v[170:173], v[30:33]
	v_mfma_f32_16x16x32_bf16 v[26:29], v[42:45], v[170:173], v[26:29]
	v_mfma_f32_16x16x32_bf16 v[14:17], v[34:37], v[178:181], v[14:17]
	v_mfma_f32_16x16x32_bf16 v[10:13], v[42:45], v[178:181], v[10:13]
	v_mfma_f32_16x16x32_bf16 v[94:97], v[38:41], v[130:133], v[94:97]
	v_mfma_f32_16x16x32_bf16 v[90:93], v[46:49], v[130:133], v[90:93]
	v_mfma_f32_16x16x32_bf16 v[78:81], v[38:41], v[146:149], v[78:81]
	v_mfma_f32_16x16x32_bf16 v[74:77], v[46:49], v[146:149], v[74:77]
	v_mfma_f32_16x16x32_bf16 v[30:33], v[38:41], v[174:177], v[30:33]
	v_mfma_f32_16x16x32_bf16 v[26:29], v[46:49], v[174:177], v[26:29]
	v_mfma_f32_16x16x32_bf16 v[14:17], v[38:41], v[182:185], v[14:17]
	v_mfma_f32_16x16x32_bf16 v[10:13], v[46:49], v[182:185], v[10:13]
	s_setprio 0
	s_barrier
	s_add_u32 s4, s46, 0x40000
	s_addc_u32 s5, s47, 0
	s_add_i32 s67, s68, s52
	v_lshl_add_u64 v[34:35], s[4:5], 0, v[164:165]
	s_mov_b32 m0, s67
	s_nop 0
	global_load_lds_dwordx4 v[34:35], off
	v_lshl_add_u64 v[34:35], s[4:5], 0, v[162:163]
	s_add_i32 m0, s67, 0x2000
	s_nop 0
	global_load_lds_dwordx4 v[34:35], off
	s_waitcnt vmcnt(6)
	s_barrier
	s_setprio 1
	v_mfma_f32_16x16x32_bf16 v[22:25], v[186:189], v[170:173], v[22:25]
	v_mfma_f32_16x16x32_bf16 v[18:21], v[222:225], v[170:173], v[18:21]
	v_mfma_f32_16x16x32_bf16 v[6:9], v[186:189], v[178:181], v[6:9]
	v_mfma_f32_16x16x32_bf16 v[2:5], v[222:225], v[178:181], v[2:5]
	v_mfma_f32_16x16x32_bf16 v[34:37], v[186:189], v[118:121], v[86:89]
	v_mfma_f32_16x16x32_bf16 v[38:41], v[222:225], v[118:121], v[82:85]
	v_mfma_f32_16x16x32_bf16 v[42:45], v[186:189], v[134:137], v[70:73]
	v_mfma_f32_16x16x32_bf16 v[46:49], v[222:225], v[134:137], v[54:57]
	v_mfma_f32_16x16x32_bf16 v[22:25], v[208:211], v[174:177], v[22:25]
	v_mfma_f32_16x16x32_bf16 v[18:21], v[226:229], v[174:177], v[18:21]
	v_mfma_f32_16x16x32_bf16 v[6:9], v[208:211], v[182:185], v[6:9]
	v_mfma_f32_16x16x32_bf16 v[2:5], v[226:229], v[182:185], v[2:5]
	v_mfma_f32_16x16x32_bf16 v[34:37], v[208:211], v[130:133], v[34:37]
	v_mfma_f32_16x16x32_bf16 v[38:41], v[226:229], v[130:133], v[38:41]
	v_mfma_f32_16x16x32_bf16 v[42:45], v[208:211], v[146:149], v[42:45]
	v_mfma_f32_16x16x32_bf16 v[46:49], v[226:229], v[146:149], v[46:49]
	s_setprio 0
	s_add_i32 s67, 0, 0x18000
	v_add_u32_e32 v1, s67, v191
	s_barrier
	ds_read_b128 v[54:57], v1
	ds_read_b128 v[70:73], v1 offset:1024
	ds_read_b128 v[82:85], v1 offset:2048
	ds_read_b128 v[86:89], v1 offset:3072
	s_add_u32 s4, s48, 0x40000
	s_addc_u32 s5, s49, 0
	s_mov_b32 m0, s55
	v_lshl_add_u64 v[134:135], s[4:5], 0, v[164:165]
	ds_read_b128 v[118:121], v206 offset:32768
	ds_read_b128 v[130:133], v206 offset:33792
	ds_read_b128 v[170:173], v206 offset:34816
	ds_read_b128 v[174:177], v206 offset:35840
	ds_read_b128 v[178:181], v206 offset:36864
	ds_read_b128 v[182:185], v206 offset:37888
	ds_read_b128 v[186:189], v206 offset:38912
	ds_read_b128 v[208:211], v206 offset:39936
	global_load_lds_dwordx4 v[134:135], off
	v_lshl_add_u64 v[134:135], s[4:5], 0, v[162:163]
	s_mov_b32 m0, s56
	s_nop 0
	global_load_lds_dwordx4 v[134:135], off
	s_waitcnt lgkmcnt(8)
	s_barrier
	s_waitcnt lgkmcnt(0)
	s_setprio 1
	s_waitcnt lgkmcnt(0)
	v_mfma_f32_16x16x32_bf16 v[134:137], v[54:57], v[118:121], v[158:161]
	v_mfma_f32_16x16x32_bf16 v[158:161], v[70:73], v[130:133], v[134:137]
	v_mfma_f32_16x16x32_bf16 v[134:137], v[82:85], v[118:121], v[154:157]
	v_mfma_f32_16x16x32_bf16 v[154:157], v[86:89], v[130:133], v[134:137]
	v_mfma_f32_16x16x32_bf16 v[134:137], v[54:57], v[170:173], v[142:145]
	v_mfma_f32_16x16x32_bf16 v[142:145], v[70:73], v[174:177], v[134:137]
	v_mfma_f32_16x16x32_bf16 v[134:137], v[82:85], v[170:173], v[138:141]
	v_mfma_f32_16x16x32_bf16 v[126:129], v[54:57], v[178:181], v[126:129]
	v_mfma_f32_16x16x32_bf16 v[122:125], v[82:85], v[178:181], v[122:125]
	v_mfma_f32_16x16x32_bf16 v[110:113], v[54:57], v[186:189], v[110:113]
	v_mfma_f32_16x16x32_bf16 v[106:109], v[82:85], v[186:189], v[106:109]
	v_mfma_f32_16x16x32_bf16 v[138:141], v[86:89], v[174:177], v[134:137]
	v_mfma_f32_16x16x32_bf16 v[126:129], v[70:73], v[182:185], v[126:129]
	v_mfma_f32_16x16x32_bf16 v[122:125], v[86:89], v[182:185], v[122:125]
	v_mfma_f32_16x16x32_bf16 v[110:113], v[70:73], v[208:211], v[110:113]
	v_mfma_f32_16x16x32_bf16 v[106:109], v[86:89], v[208:211], v[106:109]
	s_setprio 0
	s_barrier
	s_add_i32 s48, 0, 0x1c000
	s_add_i32 s4, s67, s52
	v_add_u32_e32 v1, s48, v191
	v_lshl_add_u64 v[134:135], v[214:215], 0, s[22:23]
	s_mov_b32 m0, s4
	ds_read_b128 v[222:225], v1
	ds_read_b128 v[226:229], v1 offset:1024
	ds_read_b128 v[230:233], v1 offset:2048
	ds_read_b128 v[234:237], v1 offset:3072
	global_load_lds_dwordx4 v[134:135], off
	v_lshl_add_u64 v[134:135], v[238:239], 0, s[22:23]
	s_add_i32 m0, s4, 0x2000
	s_nop 0
	global_load_lds_dwordx4 v[134:135], off
	s_barrier
	s_waitcnt lgkmcnt(0)
	s_setprio 1
	s_waitcnt lgkmcnt(0)
	v_mfma_f32_16x16x32_bf16 v[50:53], v[230:233], v[118:121], v[50:53]
	v_mfma_f32_16x16x32_bf16 v[134:137], v[222:225], v[118:121], v[150:153]
	v_mfma_f32_16x16x32_bf16 v[146:149], v[234:237], v[130:133], v[50:53]
	v_mfma_f32_16x16x32_bf16 v[50:53], v[222:225], v[170:173], v[58:61]
	v_mfma_f32_16x16x32_bf16 v[150:153], v[226:229], v[130:133], v[134:137]
	v_mfma_f32_16x16x32_bf16 v[134:137], v[226:229], v[174:177], v[50:53]
	v_mfma_f32_16x16x32_bf16 v[50:53], v[230:233], v[170:173], v[62:65]
	v_mfma_f32_16x16x32_bf16 v[130:133], v[234:237], v[174:177], v[50:53]
	v_mfma_f32_16x16x32_bf16 v[50:53], v[222:225], v[178:181], v[66:69]
	v_mfma_f32_16x16x32_bf16 v[118:121], v[226:229], v[182:185], v[50:53]
	v_mfma_f32_16x16x32_bf16 v[50:53], v[230:233], v[178:181], v[114:117]
	v_mfma_f32_16x16x32_bf16 v[114:117], v[234:237], v[182:185], v[50:53]
	v_mfma_f32_16x16x32_bf16 v[50:53], v[222:225], v[186:189], v[102:105]
	v_mfma_f32_16x16x32_bf16 v[102:105], v[226:229], v[208:211], v[50:53]
	v_mfma_f32_16x16x32_bf16 v[50:53], v[230:233], v[186:189], v[98:101]
	v_mfma_f32_16x16x32_bf16 v[98:101], v[234:237], v[208:211], v[50:53]
	s_setprio 0
	s_mov_b32 m0, s58
	v_lshl_add_u64 v[186:187], v[240:241], 0, s[22:23]
	s_barrier
	s_nop 2
	ds_read_b128 v[50:53], v206 offset:49152
	ds_read_b128 v[58:61], v206 offset:50176
	ds_read_b128 v[62:65], v206 offset:51200
	ds_read_b128 v[66:69], v206 offset:52224
	ds_read_b128 v[170:173], v206 offset:53248
	ds_read_b128 v[174:177], v206 offset:54272
	ds_read_b128 v[178:181], v206 offset:55296
	ds_read_b128 v[182:185], v206 offset:56320
	global_load_lds_dwordx4 v[186:187], off
	v_lshl_add_u64 v[186:187], v[242:243], 0, s[22:23]
	s_mov_b32 m0, s59
	s_nop 0
	global_load_lds_dwordx4 v[186:187], off
	s_barrier
	s_waitcnt lgkmcnt(0)
	s_setprio 1
	s_waitcnt lgkmcnt(0)
	v_mfma_f32_16x16x32_bf16 v[94:97], v[54:57], v[50:53], v[94:97]
	v_mfma_f32_16x16x32_bf16 v[90:93], v[82:85], v[50:53], v[90:93]
	v_mfma_f32_16x16x32_bf16 v[78:81], v[54:57], v[62:65], v[78:81]
	v_mfma_f32_16x16x32_bf16 v[74:77], v[82:85], v[62:65], v[74:77]
	v_mfma_f32_16x16x32_bf16 v[30:33], v[54:57], v[170:173], v[30:33]
	v_mfma_f32_16x16x32_bf16 v[26:29], v[82:85], v[170:173], v[26:29]
	v_mfma_f32_16x16x32_bf16 v[14:17], v[54:57], v[178:181], v[14:17]
	v_mfma_f32_16x16x32_bf16 v[10:13], v[82:85], v[178:181], v[10:13]
	v_mfma_f32_16x16x32_bf16 v[94:97], v[70:73], v[58:61], v[94:97]
	v_mfma_f32_16x16x32_bf16 v[90:93], v[86:89], v[58:61], v[90:93]
	v_mfma_f32_16x16x32_bf16 v[78:81], v[70:73], v[66:69], v[78:81]
	v_mfma_f32_16x16x32_bf16 v[74:77], v[86:89], v[66:69], v[74:77]
	v_mfma_f32_16x16x32_bf16 v[30:33], v[70:73], v[174:177], v[30:33]
	v_mfma_f32_16x16x32_bf16 v[26:29], v[86:89], v[174:177], v[26:29]
	v_mfma_f32_16x16x32_bf16 v[14:17], v[70:73], v[182:185], v[14:17]
	v_mfma_f32_16x16x32_bf16 v[10:13], v[86:89], v[182:185], v[10:13]
	s_setprio 0
	s_barrier
	s_add_u32 s4, s46, 0x40080
	s_addc_u32 s5, s47, 0
	s_add_i32 s46, s48, s52
	v_lshl_add_u64 v[54:55], s[4:5], 0, v[164:165]
	s_mov_b32 m0, s46
	s_nop 0
	global_load_lds_dwordx4 v[54:55], off
	v_lshl_add_u64 v[54:55], s[4:5], 0, v[162:163]
	s_add_i32 m0, s46, 0x2000
	s_nop 0
	global_load_lds_dwordx4 v[54:55], off
	s_waitcnt vmcnt(6)
	s_barrier
	s_setprio 1
	v_mfma_f32_16x16x32_bf16 v[34:37], v[222:225], v[50:53], v[34:37]
	v_mfma_f32_16x16x32_bf16 v[86:89], v[226:229], v[58:61], v[34:37]
	v_mfma_f32_16x16x32_bf16 v[34:37], v[230:233], v[50:53], v[38:41]
	v_mfma_f32_16x16x32_bf16 v[82:85], v[234:237], v[58:61], v[34:37]
	v_mfma_f32_16x16x32_bf16 v[34:37], v[222:225], v[62:65], v[42:45]
	v_mfma_f32_16x16x32_bf16 v[70:73], v[226:229], v[66:69], v[34:37]
	v_mfma_f32_16x16x32_bf16 v[34:37], v[230:233], v[62:65], v[46:49]
	v_mfma_f32_16x16x32_bf16 v[22:25], v[222:225], v[170:173], v[22:25]
	v_mfma_f32_16x16x32_bf16 v[18:21], v[230:233], v[170:173], v[18:21]
	v_mfma_f32_16x16x32_bf16 v[6:9], v[222:225], v[178:181], v[6:9]
	v_mfma_f32_16x16x32_bf16 v[2:5], v[230:233], v[178:181], v[2:5]
	v_mfma_f32_16x16x32_bf16 v[54:57], v[234:237], v[66:69], v[34:37]
	v_mfma_f32_16x16x32_bf16 v[22:25], v[226:229], v[174:177], v[22:25]
	v_mfma_f32_16x16x32_bf16 v[18:21], v[234:237], v[174:177], v[18:21]
	v_mfma_f32_16x16x32_bf16 v[6:9], v[226:229], v[182:185], v[6:9]
	v_mfma_f32_16x16x32_bf16 v[2:5], v[234:237], v[182:185], v[2:5]
	s_setprio 0
	s_add_i32 s66, s66, 2
	s_add_u32 s64, s64, 0x100
	s_addc_u32 s65, s65, 0
	s_cmp_gt_u32 s66, s32
	s_mov_b64 s[4:5], s[36:37]
	s_barrier
	s_cbranch_scc0 .LBB0_212
	s_cmp_eq_u32 s32, 13
	s_cbranch_scc1 .Ltail_done_3
	s_add_u32 s36, s4, 0x100
	s_addc_u32 s37, s5, 0
	s_add_i32 s67, 0, 0x10000
	v_add_u32_e32 v1, s67, v191
	ds_read_b128 v[34:37], v1
	ds_read_b128 v[38:41], v1 offset:1024
	ds_read_b128 v[42:45], v1 offset:2048
	ds_read_b128 v[46:49], v1 offset:3072
	s_cmp_eq_u32 s66, 12
	s_cselect_b32 s49, s38, s37
	s_cselect_b32 s48, s43, s36
	s_cselect_b32 s47, s62, s65
	s_cselect_b32 s46, s63, s64
	v_lshl_add_u64 v[186:187], s[4:5], 0, v[168:169]
	s_add_i32 m0, s53, 0xc000
	ds_read_b128 v[50:53], v206
	ds_read_b128 v[58:61], v206 offset:1024
	ds_read_b128 v[62:65], v206 offset:2048
	ds_read_b128 v[66:69], v206 offset:3072
	ds_read_b128 v[170:173], v206 offset:4096
	ds_read_b128 v[174:177], v206 offset:5120
	ds_read_b128 v[178:181], v206 offset:6144
	ds_read_b128 v[182:185], v206 offset:7168
	global_load_lds_dwordx4 v[186:187], off
	v_lshl_add_u64 v[186:187], s[4:5], 0, v[166:167]
	s_add_i32 m0, s53, 0xe000
	s_nop 0
	global_load_lds_dwordx4 v[186:187], off
	s_waitcnt lgkmcnt(8)
	s_barrier
	s_waitcnt lgkmcnt(0)
	s_setprio 1
	s_waitcnt lgkmcnt(0)
	v_mfma_f32_16x16x32_bf16 v[158:161], v[34:37], v[50:53], v[158:161]
	v_mfma_f32_16x16x32_bf16 v[154:157], v[42:45], v[50:53], v[154:157]
	v_mfma_f32_16x16x32_bf16 v[142:145], v[34:37], v[62:65], v[142:145]
	v_mfma_f32_16x16x32_bf16 v[138:141], v[42:45], v[62:65], v[138:141]
	v_mfma_f32_16x16x32_bf16 v[126:129], v[34:37], v[170:173], v[126:129]
	v_mfma_f32_16x16x32_bf16 v[122:125], v[42:45], v[170:173], v[122:125]
	v_mfma_f32_16x16x32_bf16 v[110:113], v[34:37], v[178:181], v[110:113]
	v_mfma_f32_16x16x32_bf16 v[106:109], v[42:45], v[178:181], v[106:109]
	v_mfma_f32_16x16x32_bf16 v[158:161], v[38:41], v[58:61], v[158:161]
	v_mfma_f32_16x16x32_bf16 v[154:157], v[46:49], v[58:61], v[154:157]
	v_mfma_f32_16x16x32_bf16 v[142:145], v[38:41], v[66:69], v[142:145]
	v_mfma_f32_16x16x32_bf16 v[138:141], v[46:49], v[66:69], v[138:141]
	v_mfma_f32_16x16x32_bf16 v[126:129], v[38:41], v[174:177], v[126:129]
	v_mfma_f32_16x16x32_bf16 v[122:125], v[46:49], v[174:177], v[122:125]
	v_mfma_f32_16x16x32_bf16 v[110:113], v[38:41], v[182:185], v[110:113]
	v_mfma_f32_16x16x32_bf16 v[106:109], v[46:49], v[182:185], v[106:109]
	s_setprio 0
	s_barrier
	s_add_i32 s68, 0, 0x14000
	s_add_i32 s4, s67, s52
	v_add_u32_e32 v1, s68, v191
	v_lshl_add_u64 v[214:215], s[46:47], 0, v[164:165]
	s_mov_b32 m0, s4
	ds_read_b128 v[186:189], v1
	ds_read_b128 v[208:211], v1 offset:1024
	ds_read_b128 v[222:225], v1 offset:2048
	ds_read_b128 v[226:229], v1 offset:3072
	v_lshl_add_u64 v[238:239], s[46:47], 0, v[162:163]
	s_add_i32 m0, s4, 0x2000
	s_nop 0
	s_barrier
	s_waitcnt lgkmcnt(0)
	s_setprio 1
	s_waitcnt lgkmcnt(0)
	v_mfma_f32_16x16x32_bf16 v[150:153], v[186:189], v[50:53], v[150:153]
	v_mfma_f32_16x16x32_bf16 v[50:53], v[222:225], v[50:53], v[146:149]
	v_mfma_f32_16x16x32_bf16 v[150:153], v[208:211], v[58:61], v[150:153]
	v_mfma_f32_16x16x32_bf16 v[50:53], v[226:229], v[58:61], v[50:53]
	v_mfma_f32_16x16x32_bf16 v[58:61], v[186:189], v[62:65], v[134:137]
	v_mfma_f32_16x16x32_bf16 v[62:65], v[222:225], v[62:65], v[130:133]
	v_mfma_f32_16x16x32_bf16 v[114:117], v[222:225], v[170:173], v[114:117]
	v_mfma_f32_16x16x32_bf16 v[102:105], v[186:189], v[178:181], v[102:105]
	v_mfma_f32_16x16x32_bf16 v[98:101], v[222:225], v[178:181], v[98:101]
	v_mfma_f32_16x16x32_bf16 v[58:61], v[208:211], v[66:69], v[58:61]
	v_mfma_f32_16x16x32_bf16 v[62:65], v[226:229], v[66:69], v[62:65]
	v_mfma_f32_16x16x32_bf16 v[66:69], v[186:189], v[170:173], v[118:121]
	v_mfma_f32_16x16x32_bf16 v[114:117], v[226:229], v[174:177], v[114:117]
	v_mfma_f32_16x16x32_bf16 v[102:105], v[208:211], v[182:185], v[102:105]
	v_mfma_f32_16x16x32_bf16 v[98:101], v[226:229], v[182:185], v[98:101]
	v_mfma_f32_16x16x32_bf16 v[66:69], v[208:211], v[174:177], v[66:69]
	s_setprio 0
	s_mov_b32 m0, s53
	v_lshl_add_u64 v[240:241], s[48:49], 0, v[164:165]
	s_barrier
	ds_read_b128 v[118:121], v206 offset:16384
	ds_read_b128 v[130:133], v206 offset:17408
	ds_read_b128 v[134:137], v206 offset:18432
	ds_read_b128 v[146:149], v206 offset:19456
	ds_read_b128 v[170:173], v206 offset:20480
	ds_read_b128 v[174:177], v206 offset:21504
	ds_read_b128 v[178:181], v206 offset:22528
	ds_read_b128 v[182:185], v206 offset:23552
	v_lshl_add_u64 v[242:243], s[48:49], 0, v[162:163]
	s_mov_b32 m0, s54
	s_nop 0
	s_barrier
	s_waitcnt lgkmcnt(0)
	s_setprio 1
	s_waitcnt lgkmcnt(0)
	v_mfma_f32_16x16x32_bf16 v[94:97], v[34:37], v[118:121], v[94:97]
	v_mfma_f32_16x16x32_bf16 v[90:93], v[42:45], v[118:121], v[90:93]
	v_mfma_f32_16x16x32_bf16 v[78:81], v[34:37], v[134:137], v[78:81]
	v_mfma_f32_16x16x32_bf16 v[74:77], v[42:45], v[134:137], v[74:77]
	v_mfma_f32_16x16x32_bf16 v[30:33], v[34:37], v[170:173], v[30:33]
	v_mfma_f32_16x16x32_bf16 v[26:29], v[42:45], v[170:173], v[26:29]
	v_mfma_f32_16x16x32_bf16 v[14:17], v[34:37], v[178:181], v[14:17]
	v_mfma_f32_16x16x32_bf16 v[10:13], v[42:45], v[178:181], v[10:13]
	v_mfma_f32_16x16x32_bf16 v[94:97], v[38:41], v[130:133], v[94:97]
	v_mfma_f32_16x16x32_bf16 v[90:93], v[46:49], v[130:133], v[90:93]
	v_mfma_f32_16x16x32_bf16 v[78:81], v[38:41], v[146:149], v[78:81]
	v_mfma_f32_16x16x32_bf16 v[74:77], v[46:49], v[146:149], v[74:77]
	v_mfma_f32_16x16x32_bf16 v[30:33], v[38:41], v[174:177], v[30:33]
	v_mfma_f32_16x16x32_bf16 v[26:29], v[46:49], v[174:177], v[26:29]
	v_mfma_f32_16x16x32_bf16 v[14:17], v[38:41], v[182:185], v[14:17]
	v_mfma_f32_16x16x32_bf16 v[10:13], v[46:49], v[182:185], v[10:13]
	s_setprio 0
	s_barrier
	s_add_u32 s4, s46, 0x40000
	s_addc_u32 s5, s47, 0
	s_add_i32 s67, s68, s52
	v_lshl_add_u64 v[34:35], s[4:5], 0, v[164:165]
	s_mov_b32 m0, s67
	s_nop 0
	v_lshl_add_u64 v[34:35], s[4:5], 0, v[162:163]
	s_add_i32 m0, s67, 0x2000
	s_nop 0
	s_waitcnt vmcnt(0)
	s_barrier
	s_setprio 1
	v_mfma_f32_16x16x32_bf16 v[22:25], v[186:189], v[170:173], v[22:25]
	v_mfma_f32_16x16x32_bf16 v[18:21], v[222:225], v[170:173], v[18:21]
	v_mfma_f32_16x16x32_bf16 v[6:9], v[186:189], v[178:181], v[6:9]
	v_mfma_f32_16x16x32_bf16 v[2:5], v[222:225], v[178:181], v[2:5]
	v_mfma_f32_16x16x32_bf16 v[34:37], v[186:189], v[118:121], v[86:89]
	v_mfma_f32_16x16x32_bf16 v[38:41], v[222:225], v[118:121], v[82:85]
	v_mfma_f32_16x16x32_bf16 v[42:45], v[186:189], v[134:137], v[70:73]
	v_mfma_f32_16x16x32_bf16 v[46:49], v[222:225], v[134:137], v[54:57]
	v_mfma_f32_16x16x32_bf16 v[22:25], v[208:211], v[174:177], v[22:25]
	v_mfma_f32_16x16x32_bf16 v[18:21], v[226:229], v[174:177], v[18:21]
	v_mfma_f32_16x16x32_bf16 v[6:9], v[208:211], v[182:185], v[6:9]
	v_mfma_f32_16x16x32_bf16 v[2:5], v[226:229], v[182:185], v[2:5]
	v_mfma_f32_16x16x32_bf16 v[34:37], v[208:211], v[130:133], v[34:37]
	v_mfma_f32_16x16x32_bf16 v[38:41], v[226:229], v[130:133], v[38:41]
	v_mfma_f32_16x16x32_bf16 v[42:45], v[208:211], v[146:149], v[42:45]
	v_mfma_f32_16x16x32_bf16 v[46:49], v[226:229], v[146:149], v[46:49]
	s_setprio 0
	s_add_i32 s67, 0, 0x18000
	v_add_u32_e32 v1, s67, v191
	s_barrier
	ds_read_b128 v[54:57], v1
	ds_read_b128 v[70:73], v1 offset:1024
	ds_read_b128 v[82:85], v1 offset:2048
	ds_read_b128 v[86:89], v1 offset:3072
	s_add_u32 s4, s48, 0x40000
	s_addc_u32 s5, s49, 0
	s_mov_b32 m0, s55
	v_lshl_add_u64 v[134:135], s[4:5], 0, v[164:165]
	ds_read_b128 v[118:121], v206 offset:32768
	ds_read_b128 v[130:133], v206 offset:33792
	ds_read_b128 v[170:173], v206 offset:34816
	ds_read_b128 v[174:177], v206 offset:35840
	ds_read_b128 v[178:181], v206 offset:36864
	ds_read_b128 v[182:185], v206 offset:37888
	ds_read_b128 v[186:189], v206 offset:38912
	ds_read_b128 v[208:211], v206 offset:39936
	v_lshl_add_u64 v[134:135], s[4:5], 0, v[162:163]
	s_mov_b32 m0, s56
	s_nop 0
	s_waitcnt lgkmcnt(8)
	s_barrier
	s_waitcnt lgkmcnt(0)
	s_setprio 1
	s_waitcnt lgkmcnt(0)
	v_mfma_f32_16x16x32_bf16 v[134:137], v[54:57], v[118:121], v[158:161]
	v_mfma_f32_16x16x32_bf16 v[158:161], v[70:73], v[130:133], v[134:137]
	v_mfma_f32_16x16x32_bf16 v[134:137], v[82:85], v[118:121], v[154:157]
	v_mfma_f32_16x16x32_bf16 v[154:157], v[86:89], v[130:133], v[134:137]
	v_mfma_f32_16x16x32_bf16 v[134:137], v[54:57], v[170:173], v[142:145]
	v_mfma_f32_16x16x32_bf16 v[142:145], v[70:73], v[174:177], v[134:137]
	v_mfma_f32_16x16x32_bf16 v[134:137], v[82:85], v[170:173], v[138:141]
	v_mfma_f32_16x16x32_bf16 v[126:129], v[54:57], v[178:181], v[126:129]
	v_mfma_f32_16x16x32_bf16 v[122:125], v[82:85], v[178:181], v[122:125]
	v_mfma_f32_16x16x32_bf16 v[110:113], v[54:57], v[186:189], v[110:113]
	v_mfma_f32_16x16x32_bf16 v[106:109], v[82:85], v[186:189], v[106:109]
	v_mfma_f32_16x16x32_bf16 v[138:141], v[86:89], v[174:177], v[134:137]
	v_mfma_f32_16x16x32_bf16 v[126:129], v[70:73], v[182:185], v[126:129]
	v_mfma_f32_16x16x32_bf16 v[122:125], v[86:89], v[182:185], v[122:125]
	v_mfma_f32_16x16x32_bf16 v[110:113], v[70:73], v[208:211], v[110:113]
	v_mfma_f32_16x16x32_bf16 v[106:109], v[86:89], v[208:211], v[106:109]
	s_setprio 0
	s_barrier
	s_add_i32 s48, 0, 0x1c000
	s_add_i32 s4, s67, s52
	v_add_u32_e32 v1, s48, v191
	v_lshl_add_u64 v[134:135], v[214:215], 0, s[22:23]
	s_mov_b32 m0, s4
	ds_read_b128 v[222:225], v1
	ds_read_b128 v[226:229], v1 offset:1024
	ds_read_b128 v[230:233], v1 offset:2048
	ds_read_b128 v[234:237], v1 offset:3072
	v_lshl_add_u64 v[134:135], v[238:239], 0, s[22:23]
	s_add_i32 m0, s4, 0x2000
	s_nop 0
	s_barrier
	s_waitcnt lgkmcnt(0)
	s_setprio 1
	s_waitcnt lgkmcnt(0)
	v_mfma_f32_16x16x32_bf16 v[50:53], v[230:233], v[118:121], v[50:53]
	v_mfma_f32_16x16x32_bf16 v[134:137], v[222:225], v[118:121], v[150:153]
	v_mfma_f32_16x16x32_bf16 v[146:149], v[234:237], v[130:133], v[50:53]
	v_mfma_f32_16x16x32_bf16 v[50:53], v[222:225], v[170:173], v[58:61]
	v_mfma_f32_16x16x32_bf16 v[150:153], v[226:229], v[130:133], v[134:137]
	v_mfma_f32_16x16x32_bf16 v[134:137], v[226:229], v[174:177], v[50:53]
	v_mfma_f32_16x16x32_bf16 v[50:53], v[230:233], v[170:173], v[62:65]
	v_mfma_f32_16x16x32_bf16 v[130:133], v[234:237], v[174:177], v[50:53]
	v_mfma_f32_16x16x32_bf16 v[50:53], v[222:225], v[178:181], v[66:69]
	v_mfma_f32_16x16x32_bf16 v[118:121], v[226:229], v[182:185], v[50:53]
	v_mfma_f32_16x16x32_bf16 v[50:53], v[230:233], v[178:181], v[114:117]
	v_mfma_f32_16x16x32_bf16 v[114:117], v[234:237], v[182:185], v[50:53]
	v_mfma_f32_16x16x32_bf16 v[50:53], v[222:225], v[186:189], v[102:105]
	v_mfma_f32_16x16x32_bf16 v[102:105], v[226:229], v[208:211], v[50:53]
	v_mfma_f32_16x16x32_bf16 v[50:53], v[230:233], v[186:189], v[98:101]
	v_mfma_f32_16x16x32_bf16 v[98:101], v[234:237], v[208:211], v[50:53]
	s_setprio 0
	s_mov_b32 m0, s58
	v_lshl_add_u64 v[186:187], v[240:241], 0, s[22:23]
	s_barrier
	s_nop 2
	ds_read_b128 v[50:53], v206 offset:49152
	ds_read_b128 v[58:61], v206 offset:50176
	ds_read_b128 v[62:65], v206 offset:51200
	ds_read_b128 v[66:69], v206 offset:52224
	ds_read_b128 v[170:173], v206 offset:53248
	ds_read_b128 v[174:177], v206 offset:54272
	ds_read_b128 v[178:181], v206 offset:55296
	ds_read_b128 v[182:185], v206 offset:56320
	v_lshl_add_u64 v[186:187], v[242:243], 0, s[22:23]
	s_mov_b32 m0, s59
	s_nop 0
	s_barrier
	s_waitcnt lgkmcnt(0)
	s_setprio 1
	s_waitcnt lgkmcnt(0)
	v_mfma_f32_16x16x32_bf16 v[94:97], v[54:57], v[50:53], v[94:97]
	v_mfma_f32_16x16x32_bf16 v[90:93], v[82:85], v[50:53], v[90:93]
	v_mfma_f32_16x16x32_bf16 v[78:81], v[54:57], v[62:65], v[78:81]
	v_mfma_f32_16x16x32_bf16 v[74:77], v[82:85], v[62:65], v[74:77]
	v_mfma_f32_16x16x32_bf16 v[30:33], v[54:57], v[170:173], v[30:33]
	v_mfma_f32_16x16x32_bf16 v[26:29], v[82:85], v[170:173], v[26:29]
	v_mfma_f32_16x16x32_bf16 v[14:17], v[54:57], v[178:181], v[14:17]
	v_mfma_f32_16x16x32_bf16 v[10:13], v[82:85], v[178:181], v[10:13]
	v_mfma_f32_16x16x32_bf16 v[94:97], v[70:73], v[58:61], v[94:97]
	v_mfma_f32_16x16x32_bf16 v[90:93], v[86:89], v[58:61], v[90:93]
	v_mfma_f32_16x16x32_bf16 v[78:81], v[70:73], v[66:69], v[78:81]
	v_mfma_f32_16x16x32_bf16 v[74:77], v[86:89], v[66:69], v[74:77]
	v_mfma_f32_16x16x32_bf16 v[30:33], v[70:73], v[174:177], v[30:33]
	v_mfma_f32_16x16x32_bf16 v[26:29], v[86:89], v[174:177], v[26:29]
	v_mfma_f32_16x16x32_bf16 v[14:17], v[70:73], v[182:185], v[14:17]
	v_mfma_f32_16x16x32_bf16 v[10:13], v[86:89], v[182:185], v[10:13]
	s_setprio 0
	s_barrier
	s_add_u32 s4, s46, 0x40080
	s_addc_u32 s5, s47, 0
	s_add_i32 s46, s48, s52
	v_lshl_add_u64 v[54:55], s[4:5], 0, v[164:165]
	s_mov_b32 m0, s46
	s_nop 0
	v_lshl_add_u64 v[54:55], s[4:5], 0, v[162:163]
	s_add_i32 m0, s46, 0x2000
	s_nop 0
	s_barrier
	s_setprio 1
	v_mfma_f32_16x16x32_bf16 v[34:37], v[222:225], v[50:53], v[34:37]
	v_mfma_f32_16x16x32_bf16 v[86:89], v[226:229], v[58:61], v[34:37]
	v_mfma_f32_16x16x32_bf16 v[34:37], v[230:233], v[50:53], v[38:41]
	v_mfma_f32_16x16x32_bf16 v[82:85], v[234:237], v[58:61], v[34:37]
	v_mfma_f32_16x16x32_bf16 v[34:37], v[222:225], v[62:65], v[42:45]
	v_mfma_f32_16x16x32_bf16 v[70:73], v[226:229], v[66:69], v[34:37]
	v_mfma_f32_16x16x32_bf16 v[34:37], v[230:233], v[62:65], v[46:49]
	v_mfma_f32_16x16x32_bf16 v[22:25], v[222:225], v[170:173], v[22:25]
	v_mfma_f32_16x16x32_bf16 v[18:21], v[230:233], v[170:173], v[18:21]
	v_mfma_f32_16x16x32_bf16 v[6:9], v[222:225], v[178:181], v[6:9]
	v_mfma_f32_16x16x32_bf16 v[2:5], v[230:233], v[178:181], v[2:5]
	v_mfma_f32_16x16x32_bf16 v[54:57], v[234:237], v[66:69], v[34:37]
	v_mfma_f32_16x16x32_bf16 v[22:25], v[226:229], v[174:177], v[22:25]
	v_mfma_f32_16x16x32_bf16 v[18:21], v[234:237], v[174:177], v[18:21]
	v_mfma_f32_16x16x32_bf16 v[6:9], v[226:229], v[182:185], v[6:9]
	v_mfma_f32_16x16x32_bf16 v[2:5], v[234:237], v[182:185], v[2:5]
	s_setprio 0
	s_add_i32 s66, s66, 2
	s_add_u32 s64, s64, 0x100
	s_addc_u32 s65, s65, 0
	s_cmp_gt_u32 s66, 13
	s_mov_b64 s[4:5], s[36:37]
	s_barrier

.LBB0_395:
	s_add_i32 s66, s66, 1
	s_mov_b64 s[36:37], s[20:21]
	s_mul_i32 s20, s66, s26
	s_add_i32 s42, s20, s2
	s_cmpk_gt_i32 s42, 0x3ff
	s_cselect_b64 s[52:53], -1, 0
	s_cselect_b32 s32, 11, 13
	s_lshl_b32 s20, s42, 3
	s_and_b32 s20, s20, 56
	s_bfe_u32 s21, s42, 0x30003
	s_mov_b32 s3, s67
	s_or_b32 s67, s20, s21
	s_mov_b32 s27, s50
	s_ashr_i32 s50, s42, 6
	s_lshl_b32 s20, s67, 19
	s_mov_b64 s[4:5], s[48:49]
	s_add_u32 s48, s18, s20
	s_addc_u32 s49, s19, 0
	s_ashr_i32 s51, s50, 31
	s_lshl_b64 s[20:21], s[50:51], 19
	s_add_u32 s20, s16, s20
	s_addc_u32 s21, s17, s21
	s_cmpk_lt_i32 s42, 0x400
	s_cselect_b32 s46, s49, s5
	s_cselect_b32 s47, s48, s4
	s_cselect_b32 s51, s21, s37
	s_cselect_b32 s54, s20, s36
	s_add_u32 s55, s36, 0x100
	s_addc_u32 s56, s37, 0
	s_mov_b32 s57, -2
	s_add_u32 s36, s4, 0x100
	s_addc_u32 s37, s5, 0
	s_add_i32 s68, 0, 0x10000
	v_add_u32_e32 v30, s68, v204
	ds_read_b128 v[14:17], v30
	ds_read_b128 v[22:25], v30 offset:1024
	ds_read_b128 v[26:29], v30 offset:2048
	ds_read_b128 v[30:33], v30 offset:3072
	s_cmp_eq_u32 s57, 12
	s_cselect_b32 s45, s46, s37
	s_cselect_b32 s44, s47, s36
	s_cselect_b32 s43, s51, s56
	s_cselect_b32 s42, s54, s55
	v_lshl_add_u64 v[178:179], s[4:5], 0, v[188:189]
	s_add_i32 m0, s60, 0xc000
	ds_read_b128 v[38:41], v209
	ds_read_b128 v[42:45], v209 offset:1024
	ds_read_b128 v[46:49], v209 offset:2048
	ds_read_b128 v[54:57], v209 offset:3072
	ds_read_b128 v[58:61], v209 offset:4096
	ds_read_b128 v[62:65], v209 offset:5120
	ds_read_b128 v[66:69], v209 offset:6144
	ds_read_b128 v[70:73], v209 offset:7168
	global_load_lds_dwordx4 v[178:179], off
	v_lshl_add_u64 v[178:179], s[4:5], 0, v[186:187]
	s_add_i32 m0, s60, 0xe000
	s_nop 0
	global_load_lds_dwordx4 v[178:179], off
	s_waitcnt lgkmcnt(8)
	s_barrier
	s_waitcnt lgkmcnt(0)
	s_setprio 1
	s_waitcnt lgkmcnt(0)
	v_mfma_f32_16x16x32_bf16 v[174:177], v[14:17], v[38:41], 0
	v_mfma_f32_16x16x32_bf16 v[170:173], v[26:29], v[38:41], 0
	v_mfma_f32_16x16x32_bf16 v[158:161], v[14:17], v[46:49], 0
	v_mfma_f32_16x16x32_bf16 v[154:157], v[26:29], v[46:49], 0
	v_mfma_f32_16x16x32_bf16 v[142:145], v[14:17], v[58:61], 0
	v_mfma_f32_16x16x32_bf16 v[138:141], v[26:29], v[58:61], 0
	v_mfma_f32_16x16x32_bf16 v[126:129], v[14:17], v[66:69], 0
	v_mfma_f32_16x16x32_bf16 v[122:125], v[26:29], v[66:69], 0
	v_mfma_f32_16x16x32_bf16 v[174:177], v[22:25], v[42:45], v[174:177]
	v_mfma_f32_16x16x32_bf16 v[170:173], v[30:33], v[42:45], v[170:173]
	v_mfma_f32_16x16x32_bf16 v[158:161], v[22:25], v[54:57], v[158:161]
	v_mfma_f32_16x16x32_bf16 v[154:157], v[30:33], v[54:57], v[154:157]
	v_mfma_f32_16x16x32_bf16 v[142:145], v[22:25], v[62:65], v[142:145]
	v_mfma_f32_16x16x32_bf16 v[138:141], v[30:33], v[62:65], v[138:141]
	v_mfma_f32_16x16x32_bf16 v[126:129], v[22:25], v[70:73], v[126:129]
	v_mfma_f32_16x16x32_bf16 v[122:125], v[30:33], v[70:73], v[122:125]
	s_setprio 0
	s_barrier
	s_add_i32 s69, 0, 0x14000
	v_add_u32_e32 v210, s69, v204
	s_add_i32 s4, s68, s59
	ds_read_b128 v[178:181], v210
	ds_read_b128 v[190:193], v210 offset:1024
	ds_read_b128 v[200:203], v210 offset:2048
	ds_read_b128 v[222:225], v210 offset:3072
	v_lshl_add_u64 v[210:211], s[42:43], 0, v[184:185]
	s_mov_b32 m0, s4
	v_lshl_add_u64 v[214:215], s[42:43], 0, v[182:183]
	global_load_lds_dwordx4 v[210:211], off
	s_add_i32 m0, s4, 0x2000
	s_nop 0
	global_load_lds_dwordx4 v[214:215], off
	s_barrier
	s_waitcnt lgkmcnt(0)
	s_setprio 1
	s_waitcnt lgkmcnt(0)
	v_mfma_f32_16x16x32_bf16 v[166:169], v[178:181], v[38:41], 0
	v_mfma_f32_16x16x32_bf16 v[38:41], v[200:203], v[38:41], 0
	v_mfma_f32_16x16x32_bf16 v[166:169], v[190:193], v[42:45], v[166:169]
	v_mfma_f32_16x16x32_bf16 v[38:41], v[222:225], v[42:45], v[38:41]
	v_mfma_f32_16x16x32_bf16 v[42:45], v[178:181], v[46:49], 0
	v_mfma_f32_16x16x32_bf16 v[46:49], v[200:203], v[46:49], 0
	v_mfma_f32_16x16x32_bf16 v[42:45], v[190:193], v[54:57], v[42:45]
	v_mfma_f32_16x16x32_bf16 v[46:49], v[222:225], v[54:57], v[46:49]
	v_mfma_f32_16x16x32_bf16 v[54:57], v[178:181], v[58:61], 0
	v_mfma_f32_16x16x32_bf16 v[58:61], v[200:203], v[58:61], 0
	v_mfma_f32_16x16x32_bf16 v[54:57], v[190:193], v[62:65], v[54:57]
	v_mfma_f32_16x16x32_bf16 v[58:61], v[222:225], v[62:65], v[58:61]
	v_mfma_f32_16x16x32_bf16 v[62:65], v[178:181], v[66:69], 0
	v_mfma_f32_16x16x32_bf16 v[66:69], v[200:203], v[66:69], 0
	v_mfma_f32_16x16x32_bf16 v[62:65], v[190:193], v[70:73], v[62:65]
	v_mfma_f32_16x16x32_bf16 v[66:69], v[222:225], v[70:73], v[66:69]
	s_setprio 0
	s_mov_b32 m0, s60
	v_lshl_add_u64 v[242:243], s[44:45], 0, v[184:185]
	s_barrier
	ds_read_b128 v[70:73], v209 offset:16384
	ds_read_b128 v[114:117], v209 offset:17408
	ds_read_b128 v[118:121], v209 offset:18432
	ds_read_b128 v[130:133], v209 offset:19456
	ds_read_b128 v[134:137], v209 offset:20480
	ds_read_b128 v[146:149], v209 offset:21504
	ds_read_b128 v[150:153], v209 offset:22528
	ds_read_b128 v[162:165], v209 offset:23552
	global_load_lds_dwordx4 v[242:243], off
	v_lshl_add_u64 v[244:245], s[44:45], 0, v[182:183]
	s_mov_b32 m0, s61
	s_nop 0
	global_load_lds_dwordx4 v[244:245], off
	s_barrier
	s_waitcnt lgkmcnt(0)
	s_setprio 1
	s_waitcnt lgkmcnt(0)
	v_mfma_f32_16x16x32_bf16 v[110:113], v[14:17], v[70:73], 0
	v_mfma_f32_16x16x32_bf16 v[106:109], v[26:29], v[70:73], 0
	v_mfma_f32_16x16x32_bf16 v[94:97], v[14:17], v[118:121], 0
	v_mfma_f32_16x16x32_bf16 v[90:93], v[26:29], v[118:121], 0
	v_mfma_f32_16x16x32_bf16 v[78:81], v[14:17], v[134:137], 0
	v_mfma_f32_16x16x32_bf16 v[74:77], v[26:29], v[134:137], 0
	v_mfma_f32_16x16x32_bf16 v[10:13], v[26:29], v[150:153], 0
	v_mfma_f32_16x16x32_bf16 v[110:113], v[22:25], v[114:117], v[110:113]
	v_mfma_f32_16x16x32_bf16 v[106:109], v[30:33], v[114:117], v[106:109]
	v_mfma_f32_16x16x32_bf16 v[94:97], v[22:25], v[130:133], v[94:97]
	v_mfma_f32_16x16x32_bf16 v[90:93], v[30:33], v[130:133], v[90:93]
	v_mfma_f32_16x16x32_bf16 v[78:81], v[22:25], v[146:149], v[78:81]
	v_mfma_f32_16x16x32_bf16 v[74:77], v[30:33], v[146:149], v[74:77]
	v_mfma_f32_16x16x32_bf16 v[14:17], v[14:17], v[150:153], 0
	v_mfma_f32_16x16x32_bf16 v[10:13], v[30:33], v[162:165], v[10:13]
	v_mfma_f32_16x16x32_bf16 v[14:17], v[22:25], v[162:165], v[14:17]
	s_setprio 0
	s_barrier
	s_add_u32 s4, s42, 0x40000
	s_addc_u32 s5, s43, 0
	s_add_i32 s68, s69, s59
	v_lshl_add_u64 v[18:19], s[4:5], 0, v[184:185]
	s_mov_b32 m0, s68
	s_nop 0
	global_load_lds_dwordx4 v[18:19], off
	v_lshl_add_u64 v[18:19], s[4:5], 0, v[182:183]
	s_add_i32 m0, s68, 0x2000
	s_nop 0
	global_load_lds_dwordx4 v[18:19], off
	s_waitcnt vmcnt(6)
	s_barrier
	s_setprio 1
	v_mfma_f32_16x16x32_bf16 v[18:21], v[178:181], v[70:73], 0
	v_mfma_f32_16x16x32_bf16 v[22:25], v[190:193], v[114:117], v[18:21]
	v_mfma_f32_16x16x32_bf16 v[18:21], v[200:203], v[70:73], 0
	v_mfma_f32_16x16x32_bf16 v[26:29], v[222:225], v[114:117], v[18:21]
	v_mfma_f32_16x16x32_bf16 v[18:21], v[178:181], v[118:121], 0
	v_mfma_f32_16x16x32_bf16 v[30:33], v[190:193], v[130:133], v[18:21]
	v_mfma_f32_16x16x32_bf16 v[18:21], v[200:203], v[118:121], 0
	v_mfma_f32_16x16x32_bf16 v[70:73], v[222:225], v[130:133], v[18:21]
	v_mfma_f32_16x16x32_bf16 v[18:21], v[178:181], v[134:137], 0
	v_mfma_f32_16x16x32_bf16 v[50:53], v[190:193], v[146:149], v[18:21]
	v_mfma_f32_16x16x32_bf16 v[18:21], v[200:203], v[134:137], 0
	v_mfma_f32_16x16x32_bf16 v[6:9], v[178:181], v[150:153], 0
	v_mfma_f32_16x16x32_bf16 v[2:5], v[200:203], v[150:153], 0
	v_mfma_f32_16x16x32_bf16 v[34:37], v[222:225], v[146:149], v[18:21]
	v_mfma_f32_16x16x32_bf16 v[6:9], v[190:193], v[162:165], v[6:9]
	v_mfma_f32_16x16x32_bf16 v[2:5], v[222:225], v[162:165], v[2:5]
	s_setprio 0
	s_add_i32 s68, 0, 0x18000
	v_add_u32_e32 v98, s68, v204
	s_barrier
	ds_read_b128 v[18:21], v98
	ds_read_b128 v[82:85], v98 offset:1024
	ds_read_b128 v[86:89], v98 offset:2048
	ds_read_b128 v[98:101], v98 offset:3072
	s_add_u32 s4, s44, 0x40000
	s_addc_u32 s5, s45, 0
	s_mov_b32 m0, s62
	v_lshl_add_u64 v[134:135], s[4:5], 0, v[184:185]
	ds_read_b128 v[102:105], v209 offset:32768
	ds_read_b128 v[114:117], v209 offset:33792
	ds_read_b128 v[118:121], v209 offset:34816
	ds_read_b128 v[130:133], v209 offset:35840
	ds_read_b128 v[178:181], v209 offset:36864
	ds_read_b128 v[190:193], v209 offset:37888
	ds_read_b128 v[200:203], v209 offset:38912
	ds_read_b128 v[222:225], v209 offset:39936
	global_load_lds_dwordx4 v[134:135], off
	v_lshl_add_u64 v[134:135], s[4:5], 0, v[182:183]
	s_mov_b32 m0, s63
	s_nop 0
	global_load_lds_dwordx4 v[134:135], off
	s_waitcnt lgkmcnt(8)
	s_barrier
	s_waitcnt lgkmcnt(0)
	s_setprio 1
	s_waitcnt lgkmcnt(0)
	v_mfma_f32_16x16x32_bf16 v[134:137], v[18:21], v[102:105], v[174:177]
	v_mfma_f32_16x16x32_bf16 v[174:177], v[82:85], v[114:117], v[134:137]
	v_mfma_f32_16x16x32_bf16 v[134:137], v[86:89], v[102:105], v[170:173]
	v_mfma_f32_16x16x32_bf16 v[170:173], v[98:101], v[114:117], v[134:137]
	v_mfma_f32_16x16x32_bf16 v[134:137], v[18:21], v[118:121], v[158:161]
	v_mfma_f32_16x16x32_bf16 v[158:161], v[82:85], v[130:133], v[134:137]
	v_mfma_f32_16x16x32_bf16 v[134:137], v[86:89], v[118:121], v[154:157]
	v_mfma_f32_16x16x32_bf16 v[154:157], v[98:101], v[130:133], v[134:137]
	v_mfma_f32_16x16x32_bf16 v[134:137], v[18:21], v[178:181], v[142:145]
	v_mfma_f32_16x16x32_bf16 v[142:145], v[82:85], v[190:193], v[134:137]
	v_mfma_f32_16x16x32_bf16 v[134:137], v[86:89], v[178:181], v[138:141]
	v_mfma_f32_16x16x32_bf16 v[126:129], v[18:21], v[200:203], v[126:129]
	v_mfma_f32_16x16x32_bf16 v[122:125], v[86:89], v[200:203], v[122:125]
	v_mfma_f32_16x16x32_bf16 v[138:141], v[98:101], v[190:193], v[134:137]
	v_mfma_f32_16x16x32_bf16 v[126:129], v[82:85], v[222:225], v[126:129]
	v_mfma_f32_16x16x32_bf16 v[122:125], v[98:101], v[222:225], v[122:125]
	s_setprio 0
	s_barrier
	s_add_i32 s44, 0, 0x1c000
	v_add_u32_e32 v134, s44, v204
	s_add_i32 s4, s68, s59
	ds_read_b128 v[226:229], v134
	ds_read_b128 v[230:233], v134 offset:1024
	ds_read_b128 v[234:237], v134 offset:2048
	ds_read_b128 v[238:241], v134 offset:3072
	v_lshl_add_u64 v[134:135], v[210:211], 0, s[22:23]
	s_mov_b32 m0, s4
	s_nop 0
	global_load_lds_dwordx4 v[134:135], off
	v_lshl_add_u64 v[134:135], v[214:215], 0, s[22:23]
	s_add_i32 m0, s4, 0x2000
	s_nop 0
	global_load_lds_dwordx4 v[134:135], off
	s_barrier
	s_waitcnt lgkmcnt(0)
	s_setprio 1
	s_waitcnt lgkmcnt(0)
	v_mfma_f32_16x16x32_bf16 v[38:41], v[234:237], v[102:105], v[38:41]
	v_mfma_f32_16x16x32_bf16 v[162:165], v[238:241], v[114:117], v[38:41]
	v_mfma_f32_16x16x32_bf16 v[38:41], v[226:229], v[118:121], v[42:45]
	v_mfma_f32_16x16x32_bf16 v[150:153], v[230:233], v[130:133], v[38:41]
	v_mfma_f32_16x16x32_bf16 v[38:41], v[234:237], v[118:121], v[46:49]
	v_mfma_f32_16x16x32_bf16 v[134:137], v[226:229], v[102:105], v[166:169]
	v_mfma_f32_16x16x32_bf16 v[146:149], v[238:241], v[130:133], v[38:41]
	v_mfma_f32_16x16x32_bf16 v[38:41], v[226:229], v[178:181], v[54:57]
	v_mfma_f32_16x16x32_bf16 v[166:169], v[230:233], v[114:117], v[134:137]
	v_mfma_f32_16x16x32_bf16 v[134:137], v[230:233], v[190:193], v[38:41]
	v_mfma_f32_16x16x32_bf16 v[38:41], v[234:237], v[178:181], v[58:61]
	v_mfma_f32_16x16x32_bf16 v[130:133], v[238:241], v[190:193], v[38:41]
	v_mfma_f32_16x16x32_bf16 v[38:41], v[226:229], v[200:203], v[62:65]
	v_mfma_f32_16x16x32_bf16 v[118:121], v[230:233], v[222:225], v[38:41]
	v_mfma_f32_16x16x32_bf16 v[38:41], v[234:237], v[200:203], v[66:69]
	v_mfma_f32_16x16x32_bf16 v[114:117], v[238:241], v[222:225], v[38:41]
	s_setprio 0
	s_mov_b32 m0, s64
	v_lshl_add_u64 v[102:103], v[242:243], 0, s[22:23]
	s_barrier
	s_nop 2
	ds_read_b128 v[38:41], v209 offset:49152
	ds_read_b128 v[42:45], v209 offset:50176
	ds_read_b128 v[46:49], v209 offset:51200
	ds_read_b128 v[54:57], v209 offset:52224
	ds_read_b128 v[58:61], v209 offset:53248
	ds_read_b128 v[62:65], v209 offset:54272
	ds_read_b128 v[66:69], v209 offset:55296
	ds_read_b128 v[178:181], v209 offset:56320
	global_load_lds_dwordx4 v[102:103], off
	v_lshl_add_u64 v[102:103], v[244:245], 0, s[22:23]
	s_mov_b32 m0, s65
	s_nop 0
	global_load_lds_dwordx4 v[102:103], off
	s_barrier
	s_waitcnt lgkmcnt(0)
	s_setprio 1
	s_waitcnt lgkmcnt(0)
	v_mfma_f32_16x16x32_bf16 v[102:105], v[18:21], v[38:41], v[110:113]
	v_mfma_f32_16x16x32_bf16 v[110:113], v[82:85], v[42:45], v[102:105]
	v_mfma_f32_16x16x32_bf16 v[102:105], v[86:89], v[38:41], v[106:109]
	v_mfma_f32_16x16x32_bf16 v[94:97], v[18:21], v[46:49], v[94:97]
	v_mfma_f32_16x16x32_bf16 v[90:93], v[86:89], v[46:49], v[90:93]
	v_mfma_f32_16x16x32_bf16 v[78:81], v[18:21], v[58:61], v[78:81]
	v_mfma_f32_16x16x32_bf16 v[74:77], v[86:89], v[58:61], v[74:77]
	v_mfma_f32_16x16x32_bf16 v[14:17], v[18:21], v[66:69], v[14:17]
	v_mfma_f32_16x16x32_bf16 v[10:13], v[86:89], v[66:69], v[10:13]
	v_mfma_f32_16x16x32_bf16 v[106:109], v[98:101], v[42:45], v[102:105]
	v_mfma_f32_16x16x32_bf16 v[94:97], v[82:85], v[54:57], v[94:97]
	v_mfma_f32_16x16x32_bf16 v[90:93], v[98:101], v[54:57], v[90:93]
	v_mfma_f32_16x16x32_bf16 v[78:81], v[82:85], v[62:65], v[78:81]
	v_mfma_f32_16x16x32_bf16 v[74:77], v[98:101], v[62:65], v[74:77]
	v_mfma_f32_16x16x32_bf16 v[18:21], v[82:85], v[178:181], v[14:17]
	v_mfma_f32_16x16x32_bf16 v[10:13], v[98:101], v[178:181], v[10:13]
	s_setprio 0
	s_barrier
	s_add_u32 s4, s42, 0x40080
	s_addc_u32 s5, s43, 0
	s_add_i32 s42, s44, s59
	v_lshl_add_u64 v[14:15], s[4:5], 0, v[184:185]
	s_mov_b32 m0, s42
	s_nop 0
	global_load_lds_dwordx4 v[14:15], off
	v_lshl_add_u64 v[14:15], s[4:5], 0, v[182:183]
	s_add_i32 m0, s42, 0x2000
	s_nop 0
	global_load_lds_dwordx4 v[14:15], off
	s_waitcnt vmcnt(6)
	s_barrier
	s_setprio 1
	v_mfma_f32_16x16x32_bf16 v[14:17], v[226:229], v[38:41], v[22:25]
	v_mfma_f32_16x16x32_bf16 v[102:105], v[230:233], v[42:45], v[14:17]
	v_mfma_f32_16x16x32_bf16 v[14:17], v[234:237], v[38:41], v[26:29]
	v_mfma_f32_16x16x32_bf16 v[98:101], v[238:241], v[42:45], v[14:17]
	v_mfma_f32_16x16x32_bf16 v[14:17], v[226:229], v[46:49], v[30:33]
	v_mfma_f32_16x16x32_bf16 v[86:89], v[230:233], v[54:57], v[14:17]
	v_mfma_f32_16x16x32_bf16 v[14:17], v[234:237], v[46:49], v[70:73]
	v_mfma_f32_16x16x32_bf16 v[82:85], v[238:241], v[54:57], v[14:17]
	v_mfma_f32_16x16x32_bf16 v[14:17], v[226:229], v[58:61], v[50:53]
	v_mfma_f32_16x16x32_bf16 v[50:53], v[230:233], v[62:65], v[14:17]
	v_mfma_f32_16x16x32_bf16 v[14:17], v[234:237], v[58:61], v[34:37]
	v_mfma_f32_16x16x32_bf16 v[6:9], v[226:229], v[66:69], v[6:9]
	v_mfma_f32_16x16x32_bf16 v[2:5], v[234:237], v[66:69], v[2:5]
	v_mfma_f32_16x16x32_bf16 v[34:37], v[238:241], v[62:65], v[14:17]
	v_mfma_f32_16x16x32_bf16 v[6:9], v[230:233], v[178:181], v[6:9]
	v_mfma_f32_16x16x32_bf16 v[2:5], v[238:241], v[178:181], v[2:5]
	s_setprio 0
	s_add_i32 s57, s57, 2
	s_add_u32 s55, s55, 0x100
	s_addc_u32 s56, s56, 0
	s_cmp_gt_u32 s57, 13
	s_mov_b64 s[4:5], s[36:37]
	s_barrier
.LBB0_396:
	s_add_u32 s36, s4, 0x100
	s_addc_u32 s37, s5, 0
	s_add_i32 s68, 0, 0x10000
	v_add_u32_e32 v30, s68, v204
	ds_read_b128 v[14:17], v30
	ds_read_b128 v[22:25], v30 offset:1024
	ds_read_b128 v[26:29], v30 offset:2048
	ds_read_b128 v[30:33], v30 offset:3072
	s_cmp_eq_u32 s57, 12
	s_cselect_b32 s45, s46, s37
	s_cselect_b32 s44, s47, s36
	s_cselect_b32 s43, s51, s56
	s_cselect_b32 s42, s54, s55
	v_lshl_add_u64 v[178:179], s[4:5], 0, v[188:189]
	s_add_i32 m0, s60, 0xc000
	ds_read_b128 v[38:41], v209
	ds_read_b128 v[42:45], v209 offset:1024
	ds_read_b128 v[46:49], v209 offset:2048
	ds_read_b128 v[54:57], v209 offset:3072
	ds_read_b128 v[58:61], v209 offset:4096
	ds_read_b128 v[62:65], v209 offset:5120
	ds_read_b128 v[66:69], v209 offset:6144
	ds_read_b128 v[70:73], v209 offset:7168
	global_load_lds_dwordx4 v[178:179], off
	v_lshl_add_u64 v[178:179], s[4:5], 0, v[186:187]
	s_add_i32 m0, s60, 0xe000
	s_nop 0
	global_load_lds_dwordx4 v[178:179], off
	s_waitcnt lgkmcnt(8)
	s_barrier
	s_waitcnt lgkmcnt(0)
	s_setprio 1
	s_waitcnt lgkmcnt(0)
	v_mfma_f32_16x16x32_bf16 v[174:177], v[14:17], v[38:41], v[174:177]
	v_mfma_f32_16x16x32_bf16 v[170:173], v[26:29], v[38:41], v[170:173]
	v_mfma_f32_16x16x32_bf16 v[158:161], v[14:17], v[46:49], v[158:161]
	v_mfma_f32_16x16x32_bf16 v[154:157], v[26:29], v[46:49], v[154:157]
	v_mfma_f32_16x16x32_bf16 v[142:145], v[14:17], v[58:61], v[142:145]
	v_mfma_f32_16x16x32_bf16 v[138:141], v[26:29], v[58:61], v[138:141]
	v_mfma_f32_16x16x32_bf16 v[126:129], v[14:17], v[66:69], v[126:129]
	v_mfma_f32_16x16x32_bf16 v[122:125], v[26:29], v[66:69], v[122:125]
	v_mfma_f32_16x16x32_bf16 v[174:177], v[22:25], v[42:45], v[174:177]
	v_mfma_f32_16x16x32_bf16 v[170:173], v[30:33], v[42:45], v[170:173]
	v_mfma_f32_16x16x32_bf16 v[158:161], v[22:25], v[54:57], v[158:161]
	v_mfma_f32_16x16x32_bf16 v[154:157], v[30:33], v[54:57], v[154:157]
	v_mfma_f32_16x16x32_bf16 v[142:145], v[22:25], v[62:65], v[142:145]
	v_mfma_f32_16x16x32_bf16 v[138:141], v[30:33], v[62:65], v[138:141]
	v_mfma_f32_16x16x32_bf16 v[126:129], v[22:25], v[70:73], v[126:129]
	v_mfma_f32_16x16x32_bf16 v[122:125], v[30:33], v[70:73], v[122:125]
	s_setprio 0
	s_barrier
	s_add_i32 s69, 0, 0x14000
	v_add_u32_e32 v210, s69, v204
	s_add_i32 s4, s68, s59
	ds_read_b128 v[178:181], v210
	ds_read_b128 v[190:193], v210 offset:1024
	ds_read_b128 v[200:203], v210 offset:2048
	ds_read_b128 v[222:225], v210 offset:3072
	v_lshl_add_u64 v[210:211], s[42:43], 0, v[184:185]
	s_mov_b32 m0, s4
	v_lshl_add_u64 v[214:215], s[42:43], 0, v[182:183]
	global_load_lds_dwordx4 v[210:211], off
	s_add_i32 m0, s4, 0x2000
	s_nop 0
	global_load_lds_dwordx4 v[214:215], off
	s_barrier
	s_waitcnt lgkmcnt(0)
	s_setprio 1
	s_waitcnt lgkmcnt(0)
	v_mfma_f32_16x16x32_bf16 v[166:169], v[178:181], v[38:41], v[166:169]
	v_mfma_f32_16x16x32_bf16 v[38:41], v[200:203], v[38:41], v[162:165]
	v_mfma_f32_16x16x32_bf16 v[166:169], v[190:193], v[42:45], v[166:169]
	v_mfma_f32_16x16x32_bf16 v[38:41], v[222:225], v[42:45], v[38:41]
	v_mfma_f32_16x16x32_bf16 v[42:45], v[178:181], v[46:49], v[150:153]
	v_mfma_f32_16x16x32_bf16 v[46:49], v[200:203], v[46:49], v[146:149]
	v_mfma_f32_16x16x32_bf16 v[42:45], v[190:193], v[54:57], v[42:45]
	v_mfma_f32_16x16x32_bf16 v[46:49], v[222:225], v[54:57], v[46:49]
	v_mfma_f32_16x16x32_bf16 v[54:57], v[178:181], v[58:61], v[134:137]
	v_mfma_f32_16x16x32_bf16 v[58:61], v[200:203], v[58:61], v[130:133]
	v_mfma_f32_16x16x32_bf16 v[54:57], v[190:193], v[62:65], v[54:57]
	v_mfma_f32_16x16x32_bf16 v[58:61], v[222:225], v[62:65], v[58:61]
	v_mfma_f32_16x16x32_bf16 v[62:65], v[178:181], v[66:69], v[118:121]
	v_mfma_f32_16x16x32_bf16 v[66:69], v[200:203], v[66:69], v[114:117]
	v_mfma_f32_16x16x32_bf16 v[62:65], v[190:193], v[70:73], v[62:65]
	v_mfma_f32_16x16x32_bf16 v[66:69], v[222:225], v[70:73], v[66:69]
	s_setprio 0
	s_mov_b32 m0, s60
	v_lshl_add_u64 v[242:243], s[44:45], 0, v[184:185]
	s_barrier
	ds_read_b128 v[70:73], v209 offset:16384
	ds_read_b128 v[114:117], v209 offset:17408
	ds_read_b128 v[118:121], v209 offset:18432
	ds_read_b128 v[130:133], v209 offset:19456
	ds_read_b128 v[134:137], v209 offset:20480
	ds_read_b128 v[146:149], v209 offset:21504
	ds_read_b128 v[150:153], v209 offset:22528
	ds_read_b128 v[162:165], v209 offset:23552
	global_load_lds_dwordx4 v[242:243], off
	v_lshl_add_u64 v[244:245], s[44:45], 0, v[182:183]
	s_mov_b32 m0, s61
	s_nop 0
	global_load_lds_dwordx4 v[244:245], off
	s_barrier
	s_waitcnt lgkmcnt(0)
	s_setprio 1
	s_waitcnt lgkmcnt(0)
	v_mfma_f32_16x16x32_bf16 v[110:113], v[14:17], v[70:73], v[110:113]
	v_mfma_f32_16x16x32_bf16 v[106:109], v[26:29], v[70:73], v[106:109]
	v_mfma_f32_16x16x32_bf16 v[94:97], v[14:17], v[118:121], v[94:97]
	v_mfma_f32_16x16x32_bf16 v[90:93], v[26:29], v[118:121], v[90:93]
	v_mfma_f32_16x16x32_bf16 v[78:81], v[14:17], v[134:137], v[78:81]
	v_mfma_f32_16x16x32_bf16 v[74:77], v[26:29], v[134:137], v[74:77]
	v_mfma_f32_16x16x32_bf16 v[10:13], v[26:29], v[150:153], v[10:13]
	v_mfma_f32_16x16x32_bf16 v[110:113], v[22:25], v[114:117], v[110:113]
	v_mfma_f32_16x16x32_bf16 v[106:109], v[30:33], v[114:117], v[106:109]
	v_mfma_f32_16x16x32_bf16 v[94:97], v[22:25], v[130:133], v[94:97]
	v_mfma_f32_16x16x32_bf16 v[90:93], v[30:33], v[130:133], v[90:93]
	v_mfma_f32_16x16x32_bf16 v[78:81], v[22:25], v[146:149], v[78:81]
	v_mfma_f32_16x16x32_bf16 v[74:77], v[30:33], v[146:149], v[74:77]
	v_mfma_f32_16x16x32_bf16 v[14:17], v[14:17], v[150:153], v[18:21]
	v_mfma_f32_16x16x32_bf16 v[10:13], v[30:33], v[162:165], v[10:13]
	v_mfma_f32_16x16x32_bf16 v[14:17], v[22:25], v[162:165], v[14:17]
	s_setprio 0
	s_barrier
	s_add_u32 s4, s42, 0x40000
	s_addc_u32 s5, s43, 0
	s_add_i32 s68, s69, s59
	v_lshl_add_u64 v[18:19], s[4:5], 0, v[184:185]
	s_mov_b32 m0, s68
	s_nop 0
	global_load_lds_dwordx4 v[18:19], off
	v_lshl_add_u64 v[18:19], s[4:5], 0, v[182:183]
	s_add_i32 m0, s68, 0x2000
	s_nop 0
	global_load_lds_dwordx4 v[18:19], off
	s_waitcnt vmcnt(6)
	s_barrier
	s_setprio 1
	v_mfma_f32_16x16x32_bf16 v[18:21], v[178:181], v[70:73], v[102:105]
	v_mfma_f32_16x16x32_bf16 v[22:25], v[190:193], v[114:117], v[18:21]
	v_mfma_f32_16x16x32_bf16 v[18:21], v[200:203], v[70:73], v[98:101]
	v_mfma_f32_16x16x32_bf16 v[26:29], v[222:225], v[114:117], v[18:21]
	v_mfma_f32_16x16x32_bf16 v[18:21], v[178:181], v[118:121], v[86:89]
	v_mfma_f32_16x16x32_bf16 v[30:33], v[190:193], v[130:133], v[18:21]
	v_mfma_f32_16x16x32_bf16 v[18:21], v[200:203], v[118:121], v[82:85]
	v_mfma_f32_16x16x32_bf16 v[70:73], v[222:225], v[130:133], v[18:21]
	v_mfma_f32_16x16x32_bf16 v[18:21], v[178:181], v[134:137], v[50:53]
	v_mfma_f32_16x16x32_bf16 v[50:53], v[190:193], v[146:149], v[18:21]
	v_mfma_f32_16x16x32_bf16 v[18:21], v[200:203], v[134:137], v[34:37]
	v_mfma_f32_16x16x32_bf16 v[6:9], v[178:181], v[150:153], v[6:9]
	v_mfma_f32_16x16x32_bf16 v[2:5], v[200:203], v[150:153], v[2:5]
	v_mfma_f32_16x16x32_bf16 v[34:37], v[222:225], v[146:149], v[18:21]
	v_mfma_f32_16x16x32_bf16 v[6:9], v[190:193], v[162:165], v[6:9]
	v_mfma_f32_16x16x32_bf16 v[2:5], v[222:225], v[162:165], v[2:5]
	s_setprio 0
	s_add_i32 s68, 0, 0x18000
	v_add_u32_e32 v98, s68, v204
	s_barrier
	ds_read_b128 v[18:21], v98
	ds_read_b128 v[82:85], v98 offset:1024
	ds_read_b128 v[86:89], v98 offset:2048
	ds_read_b128 v[98:101], v98 offset:3072
	s_add_u32 s4, s44, 0x40000
	s_addc_u32 s5, s45, 0
	s_mov_b32 m0, s62
	v_lshl_add_u64 v[134:135], s[4:5], 0, v[184:185]
	ds_read_b128 v[102:105], v209 offset:32768
	ds_read_b128 v[114:117], v209 offset:33792
	ds_read_b128 v[118:121], v209 offset:34816
	ds_read_b128 v[130:133], v209 offset:35840
	ds_read_b128 v[178:181], v209 offset:36864
	ds_read_b128 v[190:193], v209 offset:37888
	ds_read_b128 v[200:203], v209 offset:38912
	ds_read_b128 v[222:225], v209 offset:39936
	global_load_lds_dwordx4 v[134:135], off
	v_lshl_add_u64 v[134:135], s[4:5], 0, v[182:183]
	s_mov_b32 m0, s63
	s_nop 0
	global_load_lds_dwordx4 v[134:135], off
	s_waitcnt lgkmcnt(8)
	s_barrier
	s_waitcnt lgkmcnt(0)
	s_setprio 1
	s_waitcnt lgkmcnt(0)
	v_mfma_f32_16x16x32_bf16 v[134:137], v[18:21], v[102:105], v[174:177]
	v_mfma_f32_16x16x32_bf16 v[174:177], v[82:85], v[114:117], v[134:137]
	v_mfma_f32_16x16x32_bf16 v[134:137], v[86:89], v[102:105], v[170:173]
	v_mfma_f32_16x16x32_bf16 v[170:173], v[98:101], v[114:117], v[134:137]
	v_mfma_f32_16x16x32_bf16 v[134:137], v[18:21], v[118:121], v[158:161]
	v_mfma_f32_16x16x32_bf16 v[158:161], v[82:85], v[130:133], v[134:137]
	v_mfma_f32_16x16x32_bf16 v[134:137], v[86:89], v[118:121], v[154:157]
	v_mfma_f32_16x16x32_bf16 v[154:157], v[98:101], v[130:133], v[134:137]
	v_mfma_f32_16x16x32_bf16 v[134:137], v[18:21], v[178:181], v[142:145]
	v_mfma_f32_16x16x32_bf16 v[142:145], v[82:85], v[190:193], v[134:137]
	v_mfma_f32_16x16x32_bf16 v[134:137], v[86:89], v[178:181], v[138:141]
	v_mfma_f32_16x16x32_bf16 v[126:129], v[18:21], v[200:203], v[126:129]
	v_mfma_f32_16x16x32_bf16 v[122:125], v[86:89], v[200:203], v[122:125]
	v_mfma_f32_16x16x32_bf16 v[138:141], v[98:101], v[190:193], v[134:137]
	v_mfma_f32_16x16x32_bf16 v[126:129], v[82:85], v[222:225], v[126:129]
	v_mfma_f32_16x16x32_bf16 v[122:125], v[98:101], v[222:225], v[122:125]
	s_setprio 0
	s_barrier
	s_add_i32 s44, 0, 0x1c000
	v_add_u32_e32 v134, s44, v204
	s_add_i32 s4, s68, s59
	ds_read_b128 v[226:229], v134
	ds_read_b128 v[230:233], v134 offset:1024
	ds_read_b128 v[234:237], v134 offset:2048
	ds_read_b128 v[238:241], v134 offset:3072
	v_lshl_add_u64 v[134:135], v[210:211], 0, s[22:23]
	s_mov_b32 m0, s4
	s_nop 0
	global_load_lds_dwordx4 v[134:135], off
	v_lshl_add_u64 v[134:135], v[214:215], 0, s[22:23]
	s_add_i32 m0, s4, 0x2000
	s_nop 0
	global_load_lds_dwordx4 v[134:135], off
	s_barrier
	s_waitcnt lgkmcnt(0)
	s_setprio 1
	s_waitcnt lgkmcnt(0)
	v_mfma_f32_16x16x32_bf16 v[38:41], v[234:237], v[102:105], v[38:41]
	v_mfma_f32_16x16x32_bf16 v[162:165], v[238:241], v[114:117], v[38:41]
	v_mfma_f32_16x16x32_bf16 v[38:41], v[226:229], v[118:121], v[42:45]
	v_mfma_f32_16x16x32_bf16 v[150:153], v[230:233], v[130:133], v[38:41]
	v_mfma_f32_16x16x32_bf16 v[38:41], v[234:237], v[118:121], v[46:49]
	v_mfma_f32_16x16x32_bf16 v[134:137], v[226:229], v[102:105], v[166:169]
	v_mfma_f32_16x16x32_bf16 v[146:149], v[238:241], v[130:133], v[38:41]
	v_mfma_f32_16x16x32_bf16 v[38:41], v[226:229], v[178:181], v[54:57]
	v_mfma_f32_16x16x32_bf16 v[166:169], v[230:233], v[114:117], v[134:137]
	v_mfma_f32_16x16x32_bf16 v[134:137], v[230:233], v[190:193], v[38:41]
	v_mfma_f32_16x16x32_bf16 v[38:41], v[234:237], v[178:181], v[58:61]
	v_mfma_f32_16x16x32_bf16 v[130:133], v[238:241], v[190:193], v[38:41]
	v_mfma_f32_16x16x32_bf16 v[38:41], v[226:229], v[200:203], v[62:65]
	v_mfma_f32_16x16x32_bf16 v[118:121], v[230:233], v[222:225], v[38:41]
	v_mfma_f32_16x16x32_bf16 v[38:41], v[234:237], v[200:203], v[66:69]
	v_mfma_f32_16x16x32_bf16 v[114:117], v[238:241], v[222:225], v[38:41]
	s_setprio 0
	s_mov_b32 m0, s64
	v_lshl_add_u64 v[102:103], v[242:243], 0, s[22:23]
	s_barrier
	s_nop 2
	ds_read_b128 v[38:41], v209 offset:49152
	ds_read_b128 v[42:45], v209 offset:50176
	ds_read_b128 v[46:49], v209 offset:51200
	ds_read_b128 v[54:57], v209 offset:52224
	ds_read_b128 v[58:61], v209 offset:53248
	ds_read_b128 v[62:65], v209 offset:54272
	ds_read_b128 v[66:69], v209 offset:55296
	ds_read_b128 v[178:181], v209 offset:56320
	global_load_lds_dwordx4 v[102:103], off
	v_lshl_add_u64 v[102:103], v[244:245], 0, s[22:23]
	s_mov_b32 m0, s65
	s_nop 0
	global_load_lds_dwordx4 v[102:103], off
	s_barrier
	s_waitcnt lgkmcnt(0)
	s_setprio 1
	s_waitcnt lgkmcnt(0)
	v_mfma_f32_16x16x32_bf16 v[102:105], v[18:21], v[38:41], v[110:113]
	v_mfma_f32_16x16x32_bf16 v[110:113], v[82:85], v[42:45], v[102:105]
	v_mfma_f32_16x16x32_bf16 v[102:105], v[86:89], v[38:41], v[106:109]
	v_mfma_f32_16x16x32_bf16 v[94:97], v[18:21], v[46:49], v[94:97]
	v_mfma_f32_16x16x32_bf16 v[90:93], v[86:89], v[46:49], v[90:93]
	v_mfma_f32_16x16x32_bf16 v[78:81], v[18:21], v[58:61], v[78:81]
	v_mfma_f32_16x16x32_bf16 v[74:77], v[86:89], v[58:61], v[74:77]
	v_mfma_f32_16x16x32_bf16 v[14:17], v[18:21], v[66:69], v[14:17]
	v_mfma_f32_16x16x32_bf16 v[10:13], v[86:89], v[66:69], v[10:13]
	v_mfma_f32_16x16x32_bf16 v[106:109], v[98:101], v[42:45], v[102:105]
	v_mfma_f32_16x16x32_bf16 v[94:97], v[82:85], v[54:57], v[94:97]
	v_mfma_f32_16x16x32_bf16 v[90:93], v[98:101], v[54:57], v[90:93]
	v_mfma_f32_16x16x32_bf16 v[78:81], v[82:85], v[62:65], v[78:81]
	v_mfma_f32_16x16x32_bf16 v[74:77], v[98:101], v[62:65], v[74:77]
	v_mfma_f32_16x16x32_bf16 v[18:21], v[82:85], v[178:181], v[14:17]
	v_mfma_f32_16x16x32_bf16 v[10:13], v[98:101], v[178:181], v[10:13]
	s_setprio 0
	s_barrier
	s_add_u32 s4, s42, 0x40080
	s_addc_u32 s5, s43, 0
	s_add_i32 s42, s44, s59
	v_lshl_add_u64 v[14:15], s[4:5], 0, v[184:185]
	s_mov_b32 m0, s42
	s_nop 0
	global_load_lds_dwordx4 v[14:15], off
	v_lshl_add_u64 v[14:15], s[4:5], 0, v[182:183]
	s_add_i32 m0, s42, 0x2000
	s_nop 0
	global_load_lds_dwordx4 v[14:15], off
	s_waitcnt vmcnt(6)
	s_barrier
	s_setprio 1
	v_mfma_f32_16x16x32_bf16 v[14:17], v[226:229], v[38:41], v[22:25]
	v_mfma_f32_16x16x32_bf16 v[102:105], v[230:233], v[42:45], v[14:17]
	v_mfma_f32_16x16x32_bf16 v[14:17], v[234:237], v[38:41], v[26:29]
	v_mfma_f32_16x16x32_bf16 v[98:101], v[238:241], v[42:45], v[14:17]
	v_mfma_f32_16x16x32_bf16 v[14:17], v[226:229], v[46:49], v[30:33]
	v_mfma_f32_16x16x32_bf16 v[86:89], v[230:233], v[54:57], v[14:17]
	v_mfma_f32_16x16x32_bf16 v[14:17], v[234:237], v[46:49], v[70:73]
	v_mfma_f32_16x16x32_bf16 v[82:85], v[238:241], v[54:57], v[14:17]
	v_mfma_f32_16x16x32_bf16 v[14:17], v[226:229], v[58:61], v[50:53]
	v_mfma_f32_16x16x32_bf16 v[50:53], v[230:233], v[62:65], v[14:17]
	v_mfma_f32_16x16x32_bf16 v[14:17], v[234:237], v[58:61], v[34:37]
	v_mfma_f32_16x16x32_bf16 v[6:9], v[226:229], v[66:69], v[6:9]
	v_mfma_f32_16x16x32_bf16 v[2:5], v[234:237], v[66:69], v[2:5]
	v_mfma_f32_16x16x32_bf16 v[34:37], v[238:241], v[62:65], v[14:17]
	v_mfma_f32_16x16x32_bf16 v[6:9], v[230:233], v[178:181], v[6:9]
	v_mfma_f32_16x16x32_bf16 v[2:5], v[238:241], v[178:181], v[2:5]
	s_setprio 0
	s_add_i32 s57, s57, 2
	s_add_u32 s55, s55, 0x100
	s_addc_u32 s56, s56, 0
	s_cmp_gt_u32 s57, s32
	s_mov_b64 s[4:5], s[36:37]
	s_barrier
	s_cbranch_scc0 .LBB0_396
	s_cmp_eq_u32 s32, 13
	s_cbranch_scc1 .Ltail_done_0
	s_add_u32 s36, s4, 0x100
	s_addc_u32 s37, s5, 0
	s_add_i32 s68, 0, 0x10000
	v_add_u32_e32 v30, s68, v204
	ds_read_b128 v[14:17], v30
	ds_read_b128 v[22:25], v30 offset:1024
	ds_read_b128 v[26:29], v30 offset:2048
	ds_read_b128 v[30:33], v30 offset:3072
	s_cmp_eq_u32 s57, 12
	s_cselect_b32 s45, s46, s37
	s_cselect_b32 s44, s47, s36
	s_cselect_b32 s43, s51, s56
	s_cselect_b32 s42, s54, s55
	v_lshl_add_u64 v[178:179], s[4:5], 0, v[188:189]
	s_add_i32 m0, s60, 0xc000
	ds_read_b128 v[38:41], v209
	ds_read_b128 v[42:45], v209 offset:1024
	ds_read_b128 v[46:49], v209 offset:2048
	ds_read_b128 v[54:57], v209 offset:3072
	ds_read_b128 v[58:61], v209 offset:4096
	ds_read_b128 v[62:65], v209 offset:5120
	ds_read_b128 v[66:69], v209 offset:6144
	ds_read_b128 v[70:73], v209 offset:7168
	global_load_lds_dwordx4 v[178:179], off
	v_lshl_add_u64 v[178:179], s[4:5], 0, v[186:187]
	s_add_i32 m0, s60, 0xe000
	s_nop 0
	global_load_lds_dwordx4 v[178:179], off
	s_waitcnt lgkmcnt(8)
	s_barrier
	s_waitcnt lgkmcnt(0)
	s_setprio 1
	s_waitcnt lgkmcnt(0)
	v_mfma_f32_16x16x32_bf16 v[174:177], v[14:17], v[38:41], v[174:177]
	v_mfma_f32_16x16x32_bf16 v[170:173], v[26:29], v[38:41], v[170:173]
	v_mfma_f32_16x16x32_bf16 v[158:161], v[14:17], v[46:49], v[158:161]
	v_mfma_f32_16x16x32_bf16 v[154:157], v[26:29], v[46:49], v[154:157]
	v_mfma_f32_16x16x32_bf16 v[142:145], v[14:17], v[58:61], v[142:145]
	v_mfma_f32_16x16x32_bf16 v[138:141], v[26:29], v[58:61], v[138:141]
	v_mfma_f32_16x16x32_bf16 v[126:129], v[14:17], v[66:69], v[126:129]
	v_mfma_f32_16x16x32_bf16 v[122:125], v[26:29], v[66:69], v[122:125]
	v_mfma_f32_16x16x32_bf16 v[174:177], v[22:25], v[42:45], v[174:177]
	v_mfma_f32_16x16x32_bf16 v[170:173], v[30:33], v[42:45], v[170:173]
	v_mfma_f32_16x16x32_bf16 v[158:161], v[22:25], v[54:57], v[158:161]
	v_mfma_f32_16x16x32_bf16 v[154:157], v[30:33], v[54:57], v[154:157]
	v_mfma_f32_16x16x32_bf16 v[142:145], v[22:25], v[62:65], v[142:145]
	v_mfma_f32_16x16x32_bf16 v[138:141], v[30:33], v[62:65], v[138:141]
	v_mfma_f32_16x16x32_bf16 v[126:129], v[22:25], v[70:73], v[126:129]
	v_mfma_f32_16x16x32_bf16 v[122:125], v[30:33], v[70:73], v[122:125]
	s_setprio 0
	s_barrier
	s_add_i32 s69, 0, 0x14000
	v_add_u32_e32 v210, s69, v204
	s_add_i32 s4, s68, s59
	ds_read_b128 v[178:181], v210
	ds_read_b128 v[190:193], v210 offset:1024
	ds_read_b128 v[200:203], v210 offset:2048
	ds_read_b128 v[222:225], v210 offset:3072
	v_lshl_add_u64 v[210:211], s[42:43], 0, v[184:185]
	s_mov_b32 m0, s4
	v_lshl_add_u64 v[214:215], s[42:43], 0, v[182:183]
	s_add_i32 m0, s4, 0x2000
	s_nop 0
	s_barrier
	s_waitcnt lgkmcnt(0)
	s_setprio 1
	s_waitcnt lgkmcnt(0)
	v_mfma_f32_16x16x32_bf16 v[166:169], v[178:181], v[38:41], v[166:169]
	v_mfma_f32_16x16x32_bf16 v[38:41], v[200:203], v[38:41], v[162:165]
	v_mfma_f32_16x16x32_bf16 v[166:169], v[190:193], v[42:45], v[166:169]
	v_mfma_f32_16x16x32_bf16 v[38:41], v[222:225], v[42:45], v[38:41]
	v_mfma_f32_16x16x32_bf16 v[42:45], v[178:181], v[46:49], v[150:153]
	v_mfma_f32_16x16x32_bf16 v[46:49], v[200:203], v[46:49], v[146:149]
	v_mfma_f32_16x16x32_bf16 v[42:45], v[190:193], v[54:57], v[42:45]
	v_mfma_f32_16x16x32_bf16 v[46:49], v[222:225], v[54:57], v[46:49]
	v_mfma_f32_16x16x32_bf16 v[54:57], v[178:181], v[58:61], v[134:137]
	v_mfma_f32_16x16x32_bf16 v[58:61], v[200:203], v[58:61], v[130:133]
	v_mfma_f32_16x16x32_bf16 v[54:57], v[190:193], v[62:65], v[54:57]
	v_mfma_f32_16x16x32_bf16 v[58:61], v[222:225], v[62:65], v[58:61]
	v_mfma_f32_16x16x32_bf16 v[62:65], v[178:181], v[66:69], v[118:121]
	v_mfma_f32_16x16x32_bf16 v[66:69], v[200:203], v[66:69], v[114:117]
	v_mfma_f32_16x16x32_bf16 v[62:65], v[190:193], v[70:73], v[62:65]
	v_mfma_f32_16x16x32_bf16 v[66:69], v[222:225], v[70:73], v[66:69]
	s_setprio 0
	s_mov_b32 m0, s60
	v_lshl_add_u64 v[242:243], s[44:45], 0, v[184:185]
	s_barrier
	ds_read_b128 v[70:73], v209 offset:16384
	ds_read_b128 v[114:117], v209 offset:17408
	ds_read_b128 v[118:121], v209 offset:18432
	ds_read_b128 v[130:133], v209 offset:19456
	ds_read_b128 v[134:137], v209 offset:20480
	ds_read_b128 v[146:149], v209 offset:21504
	ds_read_b128 v[150:153], v209 offset:22528
	ds_read_b128 v[162:165], v209 offset:23552
	v_lshl_add_u64 v[244:245], s[44:45], 0, v[182:183]
	s_mov_b32 m0, s61
	s_nop 0
	s_barrier
	s_waitcnt lgkmcnt(0)
	s_setprio 1
	s_waitcnt lgkmcnt(0)
	v_mfma_f32_16x16x32_bf16 v[110:113], v[14:17], v[70:73], v[110:113]
	v_mfma_f32_16x16x32_bf16 v[106:109], v[26:29], v[70:73], v[106:109]
	v_mfma_f32_16x16x32_bf16 v[94:97], v[14:17], v[118:121], v[94:97]
	v_mfma_f32_16x16x32_bf16 v[90:93], v[26:29], v[118:121], v[90:93]
	v_mfma_f32_16x16x32_bf16 v[78:81], v[14:17], v[134:137], v[78:81]
	v_mfma_f32_16x16x32_bf16 v[74:77], v[26:29], v[134:137], v[74:77]
	v_mfma_f32_16x16x32_bf16 v[10:13], v[26:29], v[150:153], v[10:13]
	v_mfma_f32_16x16x32_bf16 v[110:113], v[22:25], v[114:117], v[110:113]
	v_mfma_f32_16x16x32_bf16 v[106:109], v[30:33], v[114:117], v[106:109]
	v_mfma_f32_16x16x32_bf16 v[94:97], v[22:25], v[130:133], v[94:97]
	v_mfma_f32_16x16x32_bf16 v[90:93], v[30:33], v[130:133], v[90:93]
	v_mfma_f32_16x16x32_bf16 v[78:81], v[22:25], v[146:149], v[78:81]
	v_mfma_f32_16x16x32_bf16 v[74:77], v[30:33], v[146:149], v[74:77]
	v_mfma_f32_16x16x32_bf16 v[14:17], v[14:17], v[150:153], v[18:21]
	v_mfma_f32_16x16x32_bf16 v[10:13], v[30:33], v[162:165], v[10:13]
	v_mfma_f32_16x16x32_bf16 v[14:17], v[22:25], v[162:165], v[14:17]
	s_setprio 0
	s_barrier
	s_add_u32 s4, s42, 0x40000
	s_addc_u32 s5, s43, 0
	s_add_i32 s68, s69, s59
	v_lshl_add_u64 v[18:19], s[4:5], 0, v[184:185]
	s_mov_b32 m0, s68
	s_nop 0
	v_lshl_add_u64 v[18:19], s[4:5], 0, v[182:183]
	s_add_i32 m0, s68, 0x2000
	s_nop 0
	s_waitcnt vmcnt(0)
	s_barrier
	s_setprio 1
	v_mfma_f32_16x16x32_bf16 v[18:21], v[178:181], v[70:73], v[102:105]
	v_mfma_f32_16x16x32_bf16 v[22:25], v[190:193], v[114:117], v[18:21]
	v_mfma_f32_16x16x32_bf16 v[18:21], v[200:203], v[70:73], v[98:101]
	v_mfma_f32_16x16x32_bf16 v[26:29], v[222:225], v[114:117], v[18:21]
	v_mfma_f32_16x16x32_bf16 v[18:21], v[178:181], v[118:121], v[86:89]
	v_mfma_f32_16x16x32_bf16 v[30:33], v[190:193], v[130:133], v[18:21]
	v_mfma_f32_16x16x32_bf16 v[18:21], v[200:203], v[118:121], v[82:85]
	v_mfma_f32_16x16x32_bf16 v[70:73], v[222:225], v[130:133], v[18:21]
	v_mfma_f32_16x16x32_bf16 v[18:21], v[178:181], v[134:137], v[50:53]
	v_mfma_f32_16x16x32_bf16 v[50:53], v[190:193], v[146:149], v[18:21]
	v_mfma_f32_16x16x32_bf16 v[18:21], v[200:203], v[134:137], v[34:37]
	v_mfma_f32_16x16x32_bf16 v[6:9], v[178:181], v[150:153], v[6:9]
	v_mfma_f32_16x16x32_bf16 v[2:5], v[200:203], v[150:153], v[2:5]
	v_mfma_f32_16x16x32_bf16 v[34:37], v[222:225], v[146:149], v[18:21]
	v_mfma_f32_16x16x32_bf16 v[6:9], v[190:193], v[162:165], v[6:9]
	v_mfma_f32_16x16x32_bf16 v[2:5], v[222:225], v[162:165], v[2:5]
	s_setprio 0
	s_add_i32 s68, 0, 0x18000
	v_add_u32_e32 v98, s68, v204
	s_barrier
	ds_read_b128 v[18:21], v98
	ds_read_b128 v[82:85], v98 offset:1024
	ds_read_b128 v[86:89], v98 offset:2048
	ds_read_b128 v[98:101], v98 offset:3072
	s_add_u32 s4, s44, 0x40000
	s_addc_u32 s5, s45, 0
	s_mov_b32 m0, s62
	v_lshl_add_u64 v[134:135], s[4:5], 0, v[184:185]
	ds_read_b128 v[102:105], v209 offset:32768
	ds_read_b128 v[114:117], v209 offset:33792
	ds_read_b128 v[118:121], v209 offset:34816
	ds_read_b128 v[130:133], v209 offset:35840
	ds_read_b128 v[178:181], v209 offset:36864
	ds_read_b128 v[190:193], v209 offset:37888
	ds_read_b128 v[200:203], v209 offset:38912
	ds_read_b128 v[222:225], v209 offset:39936
	v_lshl_add_u64 v[134:135], s[4:5], 0, v[182:183]
	s_mov_b32 m0, s63
	s_nop 0
	s_waitcnt lgkmcnt(8)
	s_barrier
	s_waitcnt lgkmcnt(0)
	s_setprio 1
	s_waitcnt lgkmcnt(0)
	v_mfma_f32_16x16x32_bf16 v[134:137], v[18:21], v[102:105], v[174:177]
	v_mfma_f32_16x16x32_bf16 v[174:177], v[82:85], v[114:117], v[134:137]
	v_mfma_f32_16x16x32_bf16 v[134:137], v[86:89], v[102:105], v[170:173]
	v_mfma_f32_16x16x32_bf16 v[170:173], v[98:101], v[114:117], v[134:137]
	v_mfma_f32_16x16x32_bf16 v[134:137], v[18:21], v[118:121], v[158:161]
	v_mfma_f32_16x16x32_bf16 v[158:161], v[82:85], v[130:133], v[134:137]
	v_mfma_f32_16x16x32_bf16 v[134:137], v[86:89], v[118:121], v[154:157]
	v_mfma_f32_16x16x32_bf16 v[154:157], v[98:101], v[130:133], v[134:137]
	v_mfma_f32_16x16x32_bf16 v[134:137], v[18:21], v[178:181], v[142:145]
	v_mfma_f32_16x16x32_bf16 v[142:145], v[82:85], v[190:193], v[134:137]
	v_mfma_f32_16x16x32_bf16 v[134:137], v[86:89], v[178:181], v[138:141]
	v_mfma_f32_16x16x32_bf16 v[126:129], v[18:21], v[200:203], v[126:129]
	v_mfma_f32_16x16x32_bf16 v[122:125], v[86:89], v[200:203], v[122:125]
	v_mfma_f32_16x16x32_bf16 v[138:141], v[98:101], v[190:193], v[134:137]
	v_mfma_f32_16x16x32_bf16 v[126:129], v[82:85], v[222:225], v[126:129]
	v_mfma_f32_16x16x32_bf16 v[122:125], v[98:101], v[222:225], v[122:125]
	s_setprio 0
	s_barrier
	s_add_i32 s44, 0, 0x1c000
	v_add_u32_e32 v134, s44, v204
	s_add_i32 s4, s68, s59
	ds_read_b128 v[226:229], v134
	ds_read_b128 v[230:233], v134 offset:1024
	ds_read_b128 v[234:237], v134 offset:2048
	ds_read_b128 v[238:241], v134 offset:3072
	v_lshl_add_u64 v[134:135], v[210:211], 0, s[22:23]
	s_mov_b32 m0, s4
	s_nop 0
	v_lshl_add_u64 v[134:135], v[214:215], 0, s[22:23]
	s_add_i32 m0, s4, 0x2000
	s_nop 0
	s_barrier
	s_waitcnt lgkmcnt(0)
	s_setprio 1
	s_waitcnt lgkmcnt(0)
	v_mfma_f32_16x16x32_bf16 v[38:41], v[234:237], v[102:105], v[38:41]
	v_mfma_f32_16x16x32_bf16 v[162:165], v[238:241], v[114:117], v[38:41]
	v_mfma_f32_16x16x32_bf16 v[38:41], v[226:229], v[118:121], v[42:45]
	v_mfma_f32_16x16x32_bf16 v[150:153], v[230:233], v[130:133], v[38:41]
	v_mfma_f32_16x16x32_bf16 v[38:41], v[234:237], v[118:121], v[46:49]
	v_mfma_f32_16x16x32_bf16 v[134:137], v[226:229], v[102:105], v[166:169]
	v_mfma_f32_16x16x32_bf16 v[146:149], v[238:241], v[130:133], v[38:41]
	v_mfma_f32_16x16x32_bf16 v[38:41], v[226:229], v[178:181], v[54:57]
	v_mfma_f32_16x16x32_bf16 v[166:169], v[230:233], v[114:117], v[134:137]
	v_mfma_f32_16x16x32_bf16 v[134:137], v[230:233], v[190:193], v[38:41]
	v_mfma_f32_16x16x32_bf16 v[38:41], v[234:237], v[178:181], v[58:61]
	v_mfma_f32_16x16x32_bf16 v[130:133], v[238:241], v[190:193], v[38:41]
	v_mfma_f32_16x16x32_bf16 v[38:41], v[226:229], v[200:203], v[62:65]
	v_mfma_f32_16x16x32_bf16 v[118:121], v[230:233], v[222:225], v[38:41]
	v_mfma_f32_16x16x32_bf16 v[38:41], v[234:237], v[200:203], v[66:69]
	v_mfma_f32_16x16x32_bf16 v[114:117], v[238:241], v[222:225], v[38:41]
	s_setprio 0
	s_mov_b32 m0, s64
	v_lshl_add_u64 v[102:103], v[242:243], 0, s[22:23]
	s_barrier
	s_nop 2
	ds_read_b128 v[38:41], v209 offset:49152
	ds_read_b128 v[42:45], v209 offset:50176
	ds_read_b128 v[46:49], v209 offset:51200
	ds_read_b128 v[54:57], v209 offset:52224
	ds_read_b128 v[58:61], v209 offset:53248
	ds_read_b128 v[62:65], v209 offset:54272
	ds_read_b128 v[66:69], v209 offset:55296
	ds_read_b128 v[178:181], v209 offset:56320
	v_lshl_add_u64 v[102:103], v[244:245], 0, s[22:23]
	s_mov_b32 m0, s65
	s_nop 0
	s_barrier
	s_waitcnt lgkmcnt(0)
	s_setprio 1
	s_waitcnt lgkmcnt(0)
	v_mfma_f32_16x16x32_bf16 v[102:105], v[18:21], v[38:41], v[110:113]
	v_mfma_f32_16x16x32_bf16 v[110:113], v[82:85], v[42:45], v[102:105]
	v_mfma_f32_16x16x32_bf16 v[102:105], v[86:89], v[38:41], v[106:109]
	v_mfma_f32_16x16x32_bf16 v[94:97], v[18:21], v[46:49], v[94:97]
	v_mfma_f32_16x16x32_bf16 v[90:93], v[86:89], v[46:49], v[90:93]
	v_mfma_f32_16x16x32_bf16 v[78:81], v[18:21], v[58:61], v[78:81]
	v_mfma_f32_16x16x32_bf16 v[74:77], v[86:89], v[58:61], v[74:77]
	v_mfma_f32_16x16x32_bf16 v[14:17], v[18:21], v[66:69], v[14:17]
	v_mfma_f32_16x16x32_bf16 v[10:13], v[86:89], v[66:69], v[10:13]
	v_mfma_f32_16x16x32_bf16 v[106:109], v[98:101], v[42:45], v[102:105]
	v_mfma_f32_16x16x32_bf16 v[94:97], v[82:85], v[54:57], v[94:97]
	v_mfma_f32_16x16x32_bf16 v[90:93], v[98:101], v[54:57], v[90:93]
	v_mfma_f32_16x16x32_bf16 v[78:81], v[82:85], v[62:65], v[78:81]
	v_mfma_f32_16x16x32_bf16 v[74:77], v[98:101], v[62:65], v[74:77]
	v_mfma_f32_16x16x32_bf16 v[18:21], v[82:85], v[178:181], v[14:17]
	v_mfma_f32_16x16x32_bf16 v[10:13], v[98:101], v[178:181], v[10:13]
	s_setprio 0
	s_barrier
	s_add_u32 s4, s42, 0x40080
	s_addc_u32 s5, s43, 0
	s_add_i32 s42, s44, s59
	v_lshl_add_u64 v[14:15], s[4:5], 0, v[184:185]
	s_mov_b32 m0, s42
	s_nop 0
	v_lshl_add_u64 v[14:15], s[4:5], 0, v[182:183]
	s_add_i32 m0, s42, 0x2000
	s_nop 0
	s_barrier
	s_setprio 1
	v_mfma_f32_16x16x32_bf16 v[14:17], v[226:229], v[38:41], v[22:25]
	v_mfma_f32_16x16x32_bf16 v[102:105], v[230:233], v[42:45], v[14:17]
	v_mfma_f32_16x16x32_bf16 v[14:17], v[234:237], v[38:41], v[26:29]
	v_mfma_f32_16x16x32_bf16 v[98:101], v[238:241], v[42:45], v[14:17]
	v_mfma_f32_16x16x32_bf16 v[14:17], v[226:229], v[46:49], v[30:33]
	v_mfma_f32_16x16x32_bf16 v[86:89], v[230:233], v[54:57], v[14:17]
	v_mfma_f32_16x16x32_bf16 v[14:17], v[234:237], v[46:49], v[70:73]
	v_mfma_f32_16x16x32_bf16 v[82:85], v[238:241], v[54:57], v[14:17]
	v_mfma_f32_16x16x32_bf16 v[14:17], v[226:229], v[58:61], v[50:53]
	v_mfma_f32_16x16x32_bf16 v[50:53], v[230:233], v[62:65], v[14:17]
	v_mfma_f32_16x16x32_bf16 v[14:17], v[234:237], v[58:61], v[34:37]
	v_mfma_f32_16x16x32_bf16 v[6:9], v[226:229], v[66:69], v[6:9]
	v_mfma_f32_16x16x32_bf16 v[2:5], v[234:237], v[66:69], v[2:5]
	v_mfma_f32_16x16x32_bf16 v[34:37], v[238:241], v[62:65], v[14:17]
	v_mfma_f32_16x16x32_bf16 v[6:9], v[230:233], v[178:181], v[6:9]
	v_mfma_f32_16x16x32_bf16 v[2:5], v[238:241], v[178:181], v[2:5]
	s_setprio 0
	s_add_i32 s57, s57, 2
	s_add_u32 s55, s55, 0x100
	s_addc_u32 s56, s56, 0
	s_cmp_gt_u32 s57, 13
	s_mov_b64 s[4:5], s[36:37]
	s_barrier

.LBB0_1098:
	s_add_i32 s76, s76, 1
	s_mov_b64 s[62:63], s[54:55]
	s_mul_i32 s54, s76, s26
	s_add_i32 s64, s54, s2
	s_cmpk_gt_i32 s64, 0x57f
	s_cselect_b64 s[60:61], -1, 0
	s_cselect_b32 s32, 11, 13
	s_lshl_b32 s54, s64, 3
	s_and_b32 s54, s54, 56
	s_bfe_u32 s55, s64, 0x30003
	s_or_b32 s77, s54, s55
	s_ashr_i32 s58, s64, 6
	s_lshl_b32 s54, s77, 19
	s_mov_b64 s[36:37], s[56:57]
	s_add_u32 s56, s52, s54
	s_addc_u32 s57, s53, 0
	s_ashr_i32 s59, s58, 31
	s_lshl_b64 s[54:55], s[58:59], 19
	s_add_u32 s54, s4, s54
	s_addc_u32 s55, s5, s55
	s_cmpk_lt_i32 s64, 0x580
	s_cselect_b32 s59, s57, s37
	s_cselect_b32 s78, s56, s36
	s_cselect_b32 s79, s55, s63
	s_cselect_b32 s80, s54, s62
	s_add_u32 s81, s62, 0x100
	s_addc_u32 s82, s63, 0
	s_mov_b32 s83, -2
	s_add_u32 s62, s36, 0x100
	s_addc_u32 s63, s37, 0
	s_add_i32 s84, 0, 0x10000
	v_add_u32_e32 v70, s84, v170
	ds_read_b128 v[58:61], v70
	ds_read_b128 v[62:65], v70 offset:1024
	ds_read_b128 v[66:69], v70 offset:2048
	ds_read_b128 v[70:73], v70 offset:3072
	s_cmp_eq_u32 s83, 12
	s_cselect_b32 s67, s59, s63
	s_cselect_b32 s66, s78, s62
	s_cselect_b32 s65, s79, s82
	s_cselect_b32 s64, s80, s81
	v_lshl_add_u64 v[192:193], s[36:37], 0, v[168:169]
	s_add_i32 m0, s69, 0xc000
	ds_read_b128 v[78:81], v175
	ds_read_b128 v[86:89], v175 offset:1024
	ds_read_b128 v[90:93], v175 offset:2048
	ds_read_b128 v[94:97], v175 offset:3072
	ds_read_b128 v[176:179], v175 offset:4096
	ds_read_b128 v[180:183], v175 offset:5120
	ds_read_b128 v[184:187], v175 offset:6144
	ds_read_b128 v[188:191], v175 offset:7168
	global_load_lds_dwordx4 v[192:193], off
	v_lshl_add_u64 v[192:193], s[36:37], 0, v[166:167]
	s_add_i32 m0, s69, 0xe000
	s_nop 0
	global_load_lds_dwordx4 v[192:193], off
	s_waitcnt lgkmcnt(8)
	s_barrier
	s_waitcnt lgkmcnt(0)
	s_setprio 1
	s_waitcnt lgkmcnt(0)
	v_mfma_f32_16x16x32_bf16 v[158:161], v[58:61], v[78:81], 0
	v_mfma_f32_16x16x32_bf16 v[150:153], v[66:69], v[78:81], 0
	v_mfma_f32_16x16x32_bf16 v[142:145], v[58:61], v[90:93], 0
	v_mfma_f32_16x16x32_bf16 v[134:137], v[66:69], v[90:93], 0
	v_mfma_f32_16x16x32_bf16 v[126:129], v[58:61], v[176:179], 0
	v_mfma_f32_16x16x32_bf16 v[118:121], v[66:69], v[176:179], 0
	v_mfma_f32_16x16x32_bf16 v[110:113], v[58:61], v[184:187], 0
	v_mfma_f32_16x16x32_bf16 v[102:105], v[66:69], v[184:187], 0
	v_mfma_f32_16x16x32_bf16 v[158:161], v[62:65], v[86:89], v[158:161]
	v_mfma_f32_16x16x32_bf16 v[150:153], v[70:73], v[86:89], v[150:153]
	v_mfma_f32_16x16x32_bf16 v[142:145], v[62:65], v[94:97], v[142:145]
	v_mfma_f32_16x16x32_bf16 v[134:137], v[70:73], v[94:97], v[134:137]
	v_mfma_f32_16x16x32_bf16 v[126:129], v[62:65], v[180:183], v[126:129]
	v_mfma_f32_16x16x32_bf16 v[118:121], v[70:73], v[180:183], v[118:121]
	v_mfma_f32_16x16x32_bf16 v[110:113], v[62:65], v[188:191], v[110:113]
	v_mfma_f32_16x16x32_bf16 v[102:105], v[70:73], v[188:191], v[102:105]
	s_setprio 0
	s_barrier
	s_add_i32 s85, 0, 0x14000
	v_add_u32_e32 v192, s85, v170
	s_add_i32 s36, s84, s68
	ds_read_b128 v[200:203], v192
	ds_read_b128 v[204:207], v192 offset:1024
	ds_read_b128 v[208:211], v192 offset:2048
	ds_read_b128 v[222:225], v192 offset:3072
	v_lshl_add_u64 v[192:193], s[64:65], 0, v[164:165]
	s_mov_b32 m0, s36
	v_lshl_add_u64 v[214:215], s[64:65], 0, v[162:163]
	global_load_lds_dwordx4 v[192:193], off
	s_add_i32 m0, s36, 0x2000
	s_nop 0
	global_load_lds_dwordx4 v[214:215], off
	s_barrier
	s_waitcnt lgkmcnt(0)
	s_setprio 1
	s_waitcnt lgkmcnt(0)
	v_mfma_f32_16x16x32_bf16 v[154:157], v[200:203], v[78:81], 0
	v_mfma_f32_16x16x32_bf16 v[78:81], v[208:211], v[78:81], 0
	v_mfma_f32_16x16x32_bf16 v[154:157], v[204:207], v[86:89], v[154:157]
	v_mfma_f32_16x16x32_bf16 v[78:81], v[222:225], v[86:89], v[78:81]
	v_mfma_f32_16x16x32_bf16 v[86:89], v[200:203], v[90:93], 0
	v_mfma_f32_16x16x32_bf16 v[90:93], v[208:211], v[90:93], 0
	v_mfma_f32_16x16x32_bf16 v[114:117], v[208:211], v[176:179], 0
	v_mfma_f32_16x16x32_bf16 v[106:109], v[200:203], v[184:187], 0
	v_mfma_f32_16x16x32_bf16 v[98:101], v[208:211], v[184:187], 0
	v_mfma_f32_16x16x32_bf16 v[86:89], v[204:207], v[94:97], v[86:89]
	v_mfma_f32_16x16x32_bf16 v[90:93], v[222:225], v[94:97], v[90:93]
	v_mfma_f32_16x16x32_bf16 v[94:97], v[200:203], v[176:179], 0
	v_mfma_f32_16x16x32_bf16 v[114:117], v[222:225], v[180:183], v[114:117]
	v_mfma_f32_16x16x32_bf16 v[106:109], v[204:207], v[188:191], v[106:109]
	v_mfma_f32_16x16x32_bf16 v[98:101], v[222:225], v[188:191], v[98:101]
	v_mfma_f32_16x16x32_bf16 v[94:97], v[204:207], v[180:183], v[94:97]
	s_setprio 0
	s_mov_b32 m0, s69
	v_lshl_add_u64 v[234:235], s[66:67], 0, v[164:165]
	s_barrier
	ds_read_b128 v[122:125], v175 offset:16384
	ds_read_b128 v[130:133], v175 offset:17408
	ds_read_b128 v[138:141], v175 offset:18432
	ds_read_b128 v[146:149], v175 offset:19456
	ds_read_b128 v[176:179], v175 offset:20480
	ds_read_b128 v[180:183], v175 offset:21504
	ds_read_b128 v[184:187], v175 offset:22528
	ds_read_b128 v[188:191], v175 offset:23552
	global_load_lds_dwordx4 v[234:235], off
	v_lshl_add_u64 v[236:237], s[66:67], 0, v[162:163]
	s_mov_b32 m0, s70
	s_nop 0
	global_load_lds_dwordx4 v[236:237], off
	s_barrier
	s_waitcnt lgkmcnt(0)
	s_setprio 1
	s_waitcnt lgkmcnt(0)
	v_mfma_f32_16x16x32_bf16 v[82:85], v[58:61], v[122:125], 0
	v_mfma_f32_16x16x32_bf16 v[54:57], v[66:69], v[122:125], 0
	v_mfma_f32_16x16x32_bf16 v[46:49], v[58:61], v[138:141], 0
	v_mfma_f32_16x16x32_bf16 v[38:41], v[66:69], v[138:141], 0
	v_mfma_f32_16x16x32_bf16 v[30:33], v[58:61], v[176:179], 0
	v_mfma_f32_16x16x32_bf16 v[22:25], v[66:69], v[176:179], 0
	v_mfma_f32_16x16x32_bf16 v[14:17], v[58:61], v[184:187], 0
	v_mfma_f32_16x16x32_bf16 v[6:9], v[66:69], v[184:187], 0
	v_mfma_f32_16x16x32_bf16 v[82:85], v[62:65], v[130:133], v[82:85]
	v_mfma_f32_16x16x32_bf16 v[54:57], v[70:73], v[130:133], v[54:57]
	v_mfma_f32_16x16x32_bf16 v[46:49], v[62:65], v[146:149], v[46:49]
	v_mfma_f32_16x16x32_bf16 v[38:41], v[70:73], v[146:149], v[38:41]
	v_mfma_f32_16x16x32_bf16 v[30:33], v[62:65], v[180:183], v[30:33]
	v_mfma_f32_16x16x32_bf16 v[22:25], v[70:73], v[180:183], v[22:25]
	v_mfma_f32_16x16x32_bf16 v[14:17], v[62:65], v[188:191], v[14:17]
	v_mfma_f32_16x16x32_bf16 v[6:9], v[70:73], v[188:191], v[6:9]
	s_setprio 0
	s_barrier
	s_add_u32 s36, s64, 0x40000
	s_addc_u32 s37, s65, 0
	s_add_i32 s84, s85, s68
	v_lshl_add_u64 v[58:59], s[36:37], 0, v[164:165]
	s_mov_b32 m0, s84
	s_nop 0
	global_load_lds_dwordx4 v[58:59], off
	v_lshl_add_u64 v[58:59], s[36:37], 0, v[162:163]
	s_add_i32 m0, s84, 0x2000
	s_nop 0
	global_load_lds_dwordx4 v[58:59], off
	s_waitcnt vmcnt(6)
	s_barrier
	s_setprio 1
	v_mfma_f32_16x16x32_bf16 v[50:53], v[208:211], v[122:125], 0
	v_mfma_f32_16x16x32_bf16 v[42:45], v[200:203], v[138:141], 0
	v_mfma_f32_16x16x32_bf16 v[34:37], v[208:211], v[138:141], 0
	v_mfma_f32_16x16x32_bf16 v[26:29], v[200:203], v[176:179], 0
	v_mfma_f32_16x16x32_bf16 v[18:21], v[208:211], v[176:179], 0
	v_mfma_f32_16x16x32_bf16 v[10:13], v[200:203], v[184:187], 0
	v_mfma_f32_16x16x32_bf16 v[2:5], v[208:211], v[184:187], 0
	v_mfma_f32_16x16x32_bf16 v[58:61], v[200:203], v[122:125], 0
	v_mfma_f32_16x16x32_bf16 v[50:53], v[222:225], v[130:133], v[50:53]
	v_mfma_f32_16x16x32_bf16 v[42:45], v[204:207], v[146:149], v[42:45]
	v_mfma_f32_16x16x32_bf16 v[34:37], v[222:225], v[146:149], v[34:37]
	v_mfma_f32_16x16x32_bf16 v[26:29], v[204:207], v[180:183], v[26:29]
	v_mfma_f32_16x16x32_bf16 v[18:21], v[222:225], v[180:183], v[18:21]
	v_mfma_f32_16x16x32_bf16 v[10:13], v[204:207], v[188:191], v[10:13]
	v_mfma_f32_16x16x32_bf16 v[2:5], v[222:225], v[188:191], v[2:5]
	v_mfma_f32_16x16x32_bf16 v[58:61], v[204:207], v[130:133], v[58:61]
	s_setprio 0
	s_add_i32 s84, 0, 0x18000
	v_add_u32_e32 v74, s84, v170
	s_barrier
	ds_read_b128 v[62:65], v74
	ds_read_b128 v[66:69], v74 offset:1024
	ds_read_b128 v[70:73], v74 offset:2048
	ds_read_b128 v[74:77], v74 offset:3072
	s_add_u32 s36, s66, 0x40000
	s_addc_u32 s37, s67, 0
	s_mov_b32 m0, s71
	v_lshl_add_u64 v[138:139], s[36:37], 0, v[164:165]
	ds_read_b128 v[122:125], v175 offset:32768
	ds_read_b128 v[130:133], v175 offset:33792
	ds_read_b128 v[176:179], v175 offset:34816
	ds_read_b128 v[180:183], v175 offset:35840
	ds_read_b128 v[184:187], v175 offset:36864
	ds_read_b128 v[188:191], v175 offset:37888
	ds_read_b128 v[200:203], v175 offset:38912
	ds_read_b128 v[204:207], v175 offset:39936
	global_load_lds_dwordx4 v[138:139], off
	v_lshl_add_u64 v[138:139], s[36:37], 0, v[162:163]
	s_mov_b32 m0, s72
	s_nop 0
	global_load_lds_dwordx4 v[138:139], off
	s_waitcnt lgkmcnt(8)
	s_barrier
	s_waitcnt lgkmcnt(0)
	s_setprio 1
	s_waitcnt lgkmcnt(0)
	v_mfma_f32_16x16x32_bf16 v[138:141], v[62:65], v[122:125], v[158:161]
	v_mfma_f32_16x16x32_bf16 v[158:161], v[66:69], v[130:133], v[138:141]
	v_mfma_f32_16x16x32_bf16 v[138:141], v[70:73], v[122:125], v[150:153]
	v_mfma_f32_16x16x32_bf16 v[150:153], v[74:77], v[130:133], v[138:141]
	v_mfma_f32_16x16x32_bf16 v[138:141], v[62:65], v[176:179], v[142:145]
	v_mfma_f32_16x16x32_bf16 v[134:137], v[70:73], v[176:179], v[134:137]
	v_mfma_f32_16x16x32_bf16 v[126:129], v[62:65], v[184:187], v[126:129]
	v_mfma_f32_16x16x32_bf16 v[118:121], v[70:73], v[184:187], v[118:121]
	v_mfma_f32_16x16x32_bf16 v[110:113], v[62:65], v[200:203], v[110:113]
	v_mfma_f32_16x16x32_bf16 v[102:105], v[70:73], v[200:203], v[102:105]
	v_mfma_f32_16x16x32_bf16 v[142:145], v[66:69], v[180:183], v[138:141]
	v_mfma_f32_16x16x32_bf16 v[134:137], v[74:77], v[180:183], v[134:137]
	v_mfma_f32_16x16x32_bf16 v[126:129], v[66:69], v[188:191], v[126:129]
	v_mfma_f32_16x16x32_bf16 v[118:121], v[74:77], v[188:191], v[118:121]
	v_mfma_f32_16x16x32_bf16 v[110:113], v[66:69], v[204:207], v[110:113]
	v_mfma_f32_16x16x32_bf16 v[102:105], v[74:77], v[204:207], v[102:105]
	s_setprio 0
	s_barrier
	s_add_i32 s66, 0, 0x1c000
	v_add_u32_e32 v138, s66, v170
	s_add_i32 s36, s84, s68
	ds_read_b128 v[208:211], v138
	ds_read_b128 v[222:225], v138 offset:1024
	ds_read_b128 v[226:229], v138 offset:2048
	ds_read_b128 v[230:233], v138 offset:3072
	v_lshl_add_u64 v[138:139], v[192:193], 0, s[22:23]
	s_mov_b32 m0, s36
	s_nop 0
	global_load_lds_dwordx4 v[138:139], off
	v_lshl_add_u64 v[138:139], v[214:215], 0, s[22:23]
	s_add_i32 m0, s36, 0x2000
	s_nop 0
	global_load_lds_dwordx4 v[138:139], off
	s_barrier
	s_waitcnt lgkmcnt(0)
	s_setprio 1
	s_waitcnt lgkmcnt(0)
	v_mfma_f32_16x16x32_bf16 v[78:81], v[226:229], v[122:125], v[78:81]
	v_mfma_f32_16x16x32_bf16 v[138:141], v[208:211], v[122:125], v[154:157]
	v_mfma_f32_16x16x32_bf16 v[146:149], v[230:233], v[130:133], v[78:81]
	v_mfma_f32_16x16x32_bf16 v[78:81], v[208:211], v[176:179], v[86:89]
	v_mfma_f32_16x16x32_bf16 v[154:157], v[222:225], v[130:133], v[138:141]
	v_mfma_f32_16x16x32_bf16 v[138:141], v[222:225], v[180:183], v[78:81]
	v_mfma_f32_16x16x32_bf16 v[78:81], v[226:229], v[176:179], v[90:93]
	v_mfma_f32_16x16x32_bf16 v[130:133], v[230:233], v[180:183], v[78:81]
	v_mfma_f32_16x16x32_bf16 v[78:81], v[208:211], v[184:187], v[94:97]
	v_mfma_f32_16x16x32_bf16 v[122:125], v[222:225], v[188:191], v[78:81]
	v_mfma_f32_16x16x32_bf16 v[78:81], v[226:229], v[184:187], v[114:117]
	v_mfma_f32_16x16x32_bf16 v[114:117], v[230:233], v[188:191], v[78:81]
	v_mfma_f32_16x16x32_bf16 v[78:81], v[208:211], v[200:203], v[106:109]
	v_mfma_f32_16x16x32_bf16 v[106:109], v[222:225], v[204:207], v[78:81]
	v_mfma_f32_16x16x32_bf16 v[78:81], v[226:229], v[200:203], v[98:101]
	v_mfma_f32_16x16x32_bf16 v[98:101], v[230:233], v[204:207], v[78:81]
	s_setprio 0
	s_mov_b32 m0, s73
	v_lshl_add_u64 v[192:193], v[234:235], 0, s[22:23]
	s_barrier
	s_nop 2
	ds_read_b128 v[78:81], v175 offset:49152
	ds_read_b128 v[86:89], v175 offset:50176
	ds_read_b128 v[90:93], v175 offset:51200
	ds_read_b128 v[94:97], v175 offset:52224
	ds_read_b128 v[176:179], v175 offset:53248
	ds_read_b128 v[180:183], v175 offset:54272
	ds_read_b128 v[184:187], v175 offset:55296
	ds_read_b128 v[188:191], v175 offset:56320
	global_load_lds_dwordx4 v[192:193], off
	v_lshl_add_u64 v[192:193], v[236:237], 0, s[22:23]
	s_mov_b32 m0, s75
	s_nop 0
	global_load_lds_dwordx4 v[192:193], off
	s_barrier
	s_waitcnt lgkmcnt(0)
	s_setprio 1
	s_waitcnt lgkmcnt(0)
	v_mfma_f32_16x16x32_bf16 v[82:85], v[62:65], v[78:81], v[82:85]
	v_mfma_f32_16x16x32_bf16 v[54:57], v[70:73], v[78:81], v[54:57]
	v_mfma_f32_16x16x32_bf16 v[46:49], v[62:65], v[90:93], v[46:49]
	v_mfma_f32_16x16x32_bf16 v[38:41], v[70:73], v[90:93], v[38:41]
	v_mfma_f32_16x16x32_bf16 v[30:33], v[62:65], v[176:179], v[30:33]
	v_mfma_f32_16x16x32_bf16 v[22:25], v[70:73], v[176:179], v[22:25]
	v_mfma_f32_16x16x32_bf16 v[14:17], v[62:65], v[184:187], v[14:17]
	v_mfma_f32_16x16x32_bf16 v[6:9], v[70:73], v[184:187], v[6:9]
	v_mfma_f32_16x16x32_bf16 v[82:85], v[66:69], v[86:89], v[82:85]
	v_mfma_f32_16x16x32_bf16 v[54:57], v[74:77], v[86:89], v[54:57]
	v_mfma_f32_16x16x32_bf16 v[46:49], v[66:69], v[94:97], v[46:49]
	v_mfma_f32_16x16x32_bf16 v[38:41], v[74:77], v[94:97], v[38:41]
	v_mfma_f32_16x16x32_bf16 v[30:33], v[66:69], v[180:183], v[30:33]
	v_mfma_f32_16x16x32_bf16 v[22:25], v[74:77], v[180:183], v[22:25]
	v_mfma_f32_16x16x32_bf16 v[14:17], v[66:69], v[188:191], v[14:17]
	v_mfma_f32_16x16x32_bf16 v[6:9], v[74:77], v[188:191], v[6:9]
	s_setprio 0
	s_barrier
	s_add_u32 s36, s64, 0x40080
	s_addc_u32 s37, s65, 0
	s_add_i32 s64, s66, s68
	v_lshl_add_u64 v[62:63], s[36:37], 0, v[164:165]
	s_mov_b32 m0, s64
	s_nop 0
	global_load_lds_dwordx4 v[62:63], off
	v_lshl_add_u64 v[62:63], s[36:37], 0, v[162:163]
	s_add_i32 m0, s64, 0x2000
	s_nop 0
	global_load_lds_dwordx4 v[62:63], off
	s_waitcnt vmcnt(6)
	s_barrier
	s_setprio 1
	v_mfma_f32_16x16x32_bf16 v[58:61], v[208:211], v[78:81], v[58:61]
	v_mfma_f32_16x16x32_bf16 v[50:53], v[226:229], v[78:81], v[50:53]
	v_mfma_f32_16x16x32_bf16 v[42:45], v[208:211], v[90:93], v[42:45]
	v_mfma_f32_16x16x32_bf16 v[34:37], v[226:229], v[90:93], v[34:37]
	v_mfma_f32_16x16x32_bf16 v[26:29], v[208:211], v[176:179], v[26:29]
	v_mfma_f32_16x16x32_bf16 v[18:21], v[226:229], v[176:179], v[18:21]
	v_mfma_f32_16x16x32_bf16 v[10:13], v[208:211], v[184:187], v[10:13]
	v_mfma_f32_16x16x32_bf16 v[2:5], v[226:229], v[184:187], v[2:5]
	v_mfma_f32_16x16x32_bf16 v[74:77], v[222:225], v[86:89], v[58:61]
	v_mfma_f32_16x16x32_bf16 v[50:53], v[230:233], v[86:89], v[50:53]
	v_mfma_f32_16x16x32_bf16 v[42:45], v[222:225], v[94:97], v[42:45]
	v_mfma_f32_16x16x32_bf16 v[34:37], v[230:233], v[94:97], v[34:37]
	v_mfma_f32_16x16x32_bf16 v[26:29], v[222:225], v[180:183], v[26:29]
	v_mfma_f32_16x16x32_bf16 v[18:21], v[230:233], v[180:183], v[18:21]
	v_mfma_f32_16x16x32_bf16 v[10:13], v[222:225], v[188:191], v[10:13]
	v_mfma_f32_16x16x32_bf16 v[2:5], v[230:233], v[188:191], v[2:5]
	s_setprio 0
	s_add_i32 s83, s83, 2
	s_add_u32 s81, s81, 0x100
	s_addc_u32 s82, s82, 0
	s_cmp_gt_u32 s83, 13
	s_mov_b64 s[36:37], s[62:63]
	s_barrier
.LBB0_1099:
	s_add_u32 s62, s36, 0x100
	s_addc_u32 s63, s37, 0
	s_add_i32 s84, 0, 0x10000
	v_add_u32_e32 v70, s84, v170
	ds_read_b128 v[58:61], v70
	ds_read_b128 v[62:65], v70 offset:1024
	ds_read_b128 v[66:69], v70 offset:2048
	ds_read_b128 v[70:73], v70 offset:3072
	s_cmp_eq_u32 s83, 12
	s_cselect_b32 s67, s59, s63
	s_cselect_b32 s66, s78, s62
	s_cselect_b32 s65, s79, s82
	s_cselect_b32 s64, s80, s81
	v_lshl_add_u64 v[192:193], s[36:37], 0, v[168:169]
	s_add_i32 m0, s69, 0xc000
	ds_read_b128 v[78:81], v175
	ds_read_b128 v[86:89], v175 offset:1024
	ds_read_b128 v[90:93], v175 offset:2048
	ds_read_b128 v[94:97], v175 offset:3072
	ds_read_b128 v[176:179], v175 offset:4096
	ds_read_b128 v[180:183], v175 offset:5120
	ds_read_b128 v[184:187], v175 offset:6144
	ds_read_b128 v[188:191], v175 offset:7168
	global_load_lds_dwordx4 v[192:193], off
	v_lshl_add_u64 v[192:193], s[36:37], 0, v[166:167]
	s_add_i32 m0, s69, 0xe000
	s_nop 0
	global_load_lds_dwordx4 v[192:193], off
	s_waitcnt lgkmcnt(8)
	s_barrier
	s_waitcnt lgkmcnt(0)
	s_setprio 1
	s_waitcnt lgkmcnt(0)
	v_mfma_f32_16x16x32_bf16 v[158:161], v[58:61], v[78:81], v[158:161]
	v_mfma_f32_16x16x32_bf16 v[150:153], v[66:69], v[78:81], v[150:153]
	v_mfma_f32_16x16x32_bf16 v[142:145], v[58:61], v[90:93], v[142:145]
	v_mfma_f32_16x16x32_bf16 v[134:137], v[66:69], v[90:93], v[134:137]
	v_mfma_f32_16x16x32_bf16 v[126:129], v[58:61], v[176:179], v[126:129]
	v_mfma_f32_16x16x32_bf16 v[118:121], v[66:69], v[176:179], v[118:121]
	v_mfma_f32_16x16x32_bf16 v[110:113], v[58:61], v[184:187], v[110:113]
	v_mfma_f32_16x16x32_bf16 v[102:105], v[66:69], v[184:187], v[102:105]
	v_mfma_f32_16x16x32_bf16 v[158:161], v[62:65], v[86:89], v[158:161]
	v_mfma_f32_16x16x32_bf16 v[150:153], v[70:73], v[86:89], v[150:153]
	v_mfma_f32_16x16x32_bf16 v[142:145], v[62:65], v[94:97], v[142:145]
	v_mfma_f32_16x16x32_bf16 v[134:137], v[70:73], v[94:97], v[134:137]
	v_mfma_f32_16x16x32_bf16 v[126:129], v[62:65], v[180:183], v[126:129]
	v_mfma_f32_16x16x32_bf16 v[118:121], v[70:73], v[180:183], v[118:121]
	v_mfma_f32_16x16x32_bf16 v[110:113], v[62:65], v[188:191], v[110:113]
	v_mfma_f32_16x16x32_bf16 v[102:105], v[70:73], v[188:191], v[102:105]
	s_setprio 0
	s_barrier
	s_add_i32 s85, 0, 0x14000
	v_add_u32_e32 v192, s85, v170
	s_add_i32 s36, s84, s68
	ds_read_b128 v[200:203], v192
	ds_read_b128 v[204:207], v192 offset:1024
	ds_read_b128 v[208:211], v192 offset:2048
	ds_read_b128 v[222:225], v192 offset:3072
	v_lshl_add_u64 v[192:193], s[64:65], 0, v[164:165]
	s_mov_b32 m0, s36
	v_lshl_add_u64 v[214:215], s[64:65], 0, v[162:163]
	global_load_lds_dwordx4 v[192:193], off
	s_add_i32 m0, s36, 0x2000
	s_nop 0
	global_load_lds_dwordx4 v[214:215], off
	s_barrier
	s_waitcnt lgkmcnt(0)
	s_setprio 1
	s_waitcnt lgkmcnt(0)
	v_mfma_f32_16x16x32_bf16 v[154:157], v[200:203], v[78:81], v[154:157]
	v_mfma_f32_16x16x32_bf16 v[78:81], v[208:211], v[78:81], v[146:149]
	v_mfma_f32_16x16x32_bf16 v[154:157], v[204:207], v[86:89], v[154:157]
	v_mfma_f32_16x16x32_bf16 v[78:81], v[222:225], v[86:89], v[78:81]
	v_mfma_f32_16x16x32_bf16 v[86:89], v[200:203], v[90:93], v[138:141]
	v_mfma_f32_16x16x32_bf16 v[90:93], v[208:211], v[90:93], v[130:133]
	v_mfma_f32_16x16x32_bf16 v[114:117], v[208:211], v[176:179], v[114:117]
	v_mfma_f32_16x16x32_bf16 v[106:109], v[200:203], v[184:187], v[106:109]
	v_mfma_f32_16x16x32_bf16 v[98:101], v[208:211], v[184:187], v[98:101]
	v_mfma_f32_16x16x32_bf16 v[86:89], v[204:207], v[94:97], v[86:89]
	v_mfma_f32_16x16x32_bf16 v[90:93], v[222:225], v[94:97], v[90:93]
	v_mfma_f32_16x16x32_bf16 v[94:97], v[200:203], v[176:179], v[122:125]
	v_mfma_f32_16x16x32_bf16 v[114:117], v[222:225], v[180:183], v[114:117]
	v_mfma_f32_16x16x32_bf16 v[106:109], v[204:207], v[188:191], v[106:109]
	v_mfma_f32_16x16x32_bf16 v[98:101], v[222:225], v[188:191], v[98:101]
	v_mfma_f32_16x16x32_bf16 v[94:97], v[204:207], v[180:183], v[94:97]
	s_setprio 0
	s_mov_b32 m0, s69
	v_lshl_add_u64 v[234:235], s[66:67], 0, v[164:165]
	s_barrier
	ds_read_b128 v[122:125], v175 offset:16384
	ds_read_b128 v[130:133], v175 offset:17408
	ds_read_b128 v[138:141], v175 offset:18432
	ds_read_b128 v[146:149], v175 offset:19456
	ds_read_b128 v[176:179], v175 offset:20480
	ds_read_b128 v[180:183], v175 offset:21504
	ds_read_b128 v[184:187], v175 offset:22528
	ds_read_b128 v[188:191], v175 offset:23552
	global_load_lds_dwordx4 v[234:235], off
	v_lshl_add_u64 v[236:237], s[66:67], 0, v[162:163]
	s_mov_b32 m0, s70
	s_nop 0
	global_load_lds_dwordx4 v[236:237], off
	s_barrier
	s_waitcnt lgkmcnt(0)
	s_setprio 1
	s_waitcnt lgkmcnt(0)
	v_mfma_f32_16x16x32_bf16 v[82:85], v[58:61], v[122:125], v[82:85]
	v_mfma_f32_16x16x32_bf16 v[54:57], v[66:69], v[122:125], v[54:57]
	v_mfma_f32_16x16x32_bf16 v[46:49], v[58:61], v[138:141], v[46:49]
	v_mfma_f32_16x16x32_bf16 v[38:41], v[66:69], v[138:141], v[38:41]
	v_mfma_f32_16x16x32_bf16 v[30:33], v[58:61], v[176:179], v[30:33]
	v_mfma_f32_16x16x32_bf16 v[22:25], v[66:69], v[176:179], v[22:25]
	v_mfma_f32_16x16x32_bf16 v[14:17], v[58:61], v[184:187], v[14:17]
	v_mfma_f32_16x16x32_bf16 v[6:9], v[66:69], v[184:187], v[6:9]
	v_mfma_f32_16x16x32_bf16 v[82:85], v[62:65], v[130:133], v[82:85]
	v_mfma_f32_16x16x32_bf16 v[54:57], v[70:73], v[130:133], v[54:57]
	v_mfma_f32_16x16x32_bf16 v[46:49], v[62:65], v[146:149], v[46:49]
	v_mfma_f32_16x16x32_bf16 v[38:41], v[70:73], v[146:149], v[38:41]
	v_mfma_f32_16x16x32_bf16 v[30:33], v[62:65], v[180:183], v[30:33]
	v_mfma_f32_16x16x32_bf16 v[22:25], v[70:73], v[180:183], v[22:25]
	v_mfma_f32_16x16x32_bf16 v[14:17], v[62:65], v[188:191], v[14:17]
	v_mfma_f32_16x16x32_bf16 v[6:9], v[70:73], v[188:191], v[6:9]
	s_setprio 0
	s_barrier
	s_add_u32 s36, s64, 0x40000
	s_addc_u32 s37, s65, 0
	s_add_i32 s84, s85, s68
	v_lshl_add_u64 v[58:59], s[36:37], 0, v[164:165]
	s_mov_b32 m0, s84
	s_nop 0
	global_load_lds_dwordx4 v[58:59], off
	v_lshl_add_u64 v[58:59], s[36:37], 0, v[162:163]
	s_add_i32 m0, s84, 0x2000
	s_nop 0
	global_load_lds_dwordx4 v[58:59], off
	s_waitcnt vmcnt(6)
	s_barrier
	s_setprio 1
	v_mfma_f32_16x16x32_bf16 v[50:53], v[208:211], v[122:125], v[50:53]
	v_mfma_f32_16x16x32_bf16 v[42:45], v[200:203], v[138:141], v[42:45]
	v_mfma_f32_16x16x32_bf16 v[34:37], v[208:211], v[138:141], v[34:37]
	v_mfma_f32_16x16x32_bf16 v[26:29], v[200:203], v[176:179], v[26:29]
	v_mfma_f32_16x16x32_bf16 v[18:21], v[208:211], v[176:179], v[18:21]
	v_mfma_f32_16x16x32_bf16 v[10:13], v[200:203], v[184:187], v[10:13]
	v_mfma_f32_16x16x32_bf16 v[2:5], v[208:211], v[184:187], v[2:5]
	v_mfma_f32_16x16x32_bf16 v[58:61], v[200:203], v[122:125], v[74:77]
	v_mfma_f32_16x16x32_bf16 v[50:53], v[222:225], v[130:133], v[50:53]
	v_mfma_f32_16x16x32_bf16 v[42:45], v[204:207], v[146:149], v[42:45]
	v_mfma_f32_16x16x32_bf16 v[34:37], v[222:225], v[146:149], v[34:37]
	v_mfma_f32_16x16x32_bf16 v[26:29], v[204:207], v[180:183], v[26:29]
	v_mfma_f32_16x16x32_bf16 v[18:21], v[222:225], v[180:183], v[18:21]
	v_mfma_f32_16x16x32_bf16 v[10:13], v[204:207], v[188:191], v[10:13]
	v_mfma_f32_16x16x32_bf16 v[2:5], v[222:225], v[188:191], v[2:5]
	v_mfma_f32_16x16x32_bf16 v[58:61], v[204:207], v[130:133], v[58:61]
	s_setprio 0
	s_add_i32 s84, 0, 0x18000
	v_add_u32_e32 v74, s84, v170
	s_barrier
	ds_read_b128 v[62:65], v74
	ds_read_b128 v[66:69], v74 offset:1024
	ds_read_b128 v[70:73], v74 offset:2048
	ds_read_b128 v[74:77], v74 offset:3072
	s_add_u32 s36, s66, 0x40000
	s_addc_u32 s37, s67, 0
	s_mov_b32 m0, s71
	v_lshl_add_u64 v[138:139], s[36:37], 0, v[164:165]
	ds_read_b128 v[122:125], v175 offset:32768
	ds_read_b128 v[130:133], v175 offset:33792
	ds_read_b128 v[176:179], v175 offset:34816
	ds_read_b128 v[180:183], v175 offset:35840
	ds_read_b128 v[184:187], v175 offset:36864
	ds_read_b128 v[188:191], v175 offset:37888
	ds_read_b128 v[200:203], v175 offset:38912
	ds_read_b128 v[204:207], v175 offset:39936
	global_load_lds_dwordx4 v[138:139], off
	v_lshl_add_u64 v[138:139], s[36:37], 0, v[162:163]
	s_mov_b32 m0, s72
	s_nop 0
	global_load_lds_dwordx4 v[138:139], off
	s_waitcnt lgkmcnt(8)
	s_barrier
	s_waitcnt lgkmcnt(0)
	s_setprio 1
	s_waitcnt lgkmcnt(0)
	v_mfma_f32_16x16x32_bf16 v[138:141], v[62:65], v[122:125], v[158:161]
	v_mfma_f32_16x16x32_bf16 v[158:161], v[66:69], v[130:133], v[138:141]
	v_mfma_f32_16x16x32_bf16 v[138:141], v[70:73], v[122:125], v[150:153]
	v_mfma_f32_16x16x32_bf16 v[150:153], v[74:77], v[130:133], v[138:141]
	v_mfma_f32_16x16x32_bf16 v[138:141], v[62:65], v[176:179], v[142:145]
	v_mfma_f32_16x16x32_bf16 v[134:137], v[70:73], v[176:179], v[134:137]
	v_mfma_f32_16x16x32_bf16 v[126:129], v[62:65], v[184:187], v[126:129]
	v_mfma_f32_16x16x32_bf16 v[118:121], v[70:73], v[184:187], v[118:121]
	v_mfma_f32_16x16x32_bf16 v[110:113], v[62:65], v[200:203], v[110:113]
	v_mfma_f32_16x16x32_bf16 v[102:105], v[70:73], v[200:203], v[102:105]
	v_mfma_f32_16x16x32_bf16 v[142:145], v[66:69], v[180:183], v[138:141]
	v_mfma_f32_16x16x32_bf16 v[134:137], v[74:77], v[180:183], v[134:137]
	v_mfma_f32_16x16x32_bf16 v[126:129], v[66:69], v[188:191], v[126:129]
	v_mfma_f32_16x16x32_bf16 v[118:121], v[74:77], v[188:191], v[118:121]
	v_mfma_f32_16x16x32_bf16 v[110:113], v[66:69], v[204:207], v[110:113]
	v_mfma_f32_16x16x32_bf16 v[102:105], v[74:77], v[204:207], v[102:105]
	s_setprio 0
	s_barrier
	s_add_i32 s66, 0, 0x1c000
	v_add_u32_e32 v138, s66, v170
	s_add_i32 s36, s84, s68
	ds_read_b128 v[208:211], v138
	ds_read_b128 v[222:225], v138 offset:1024
	ds_read_b128 v[226:229], v138 offset:2048
	ds_read_b128 v[230:233], v138 offset:3072
	v_lshl_add_u64 v[138:139], v[192:193], 0, s[22:23]
	s_mov_b32 m0, s36
	s_nop 0
	global_load_lds_dwordx4 v[138:139], off
	v_lshl_add_u64 v[138:139], v[214:215], 0, s[22:23]
	s_add_i32 m0, s36, 0x2000
	s_nop 0
	global_load_lds_dwordx4 v[138:139], off
	s_barrier
	s_waitcnt lgkmcnt(0)
	s_setprio 1
	s_waitcnt lgkmcnt(0)
	v_mfma_f32_16x16x32_bf16 v[78:81], v[226:229], v[122:125], v[78:81]
	v_mfma_f32_16x16x32_bf16 v[138:141], v[208:211], v[122:125], v[154:157]
	v_mfma_f32_16x16x32_bf16 v[146:149], v[230:233], v[130:133], v[78:81]
	v_mfma_f32_16x16x32_bf16 v[78:81], v[208:211], v[176:179], v[86:89]
	v_mfma_f32_16x16x32_bf16 v[154:157], v[222:225], v[130:133], v[138:141]
	v_mfma_f32_16x16x32_bf16 v[138:141], v[222:225], v[180:183], v[78:81]
	v_mfma_f32_16x16x32_bf16 v[78:81], v[226:229], v[176:179], v[90:93]
	v_mfma_f32_16x16x32_bf16 v[130:133], v[230:233], v[180:183], v[78:81]
	v_mfma_f32_16x16x32_bf16 v[78:81], v[208:211], v[184:187], v[94:97]
	v_mfma_f32_16x16x32_bf16 v[122:125], v[222:225], v[188:191], v[78:81]
	v_mfma_f32_16x16x32_bf16 v[78:81], v[226:229], v[184:187], v[114:117]
	v_mfma_f32_16x16x32_bf16 v[114:117], v[230:233], v[188:191], v[78:81]
	v_mfma_f32_16x16x32_bf16 v[78:81], v[208:211], v[200:203], v[106:109]
	v_mfma_f32_16x16x32_bf16 v[106:109], v[222:225], v[204:207], v[78:81]
	v_mfma_f32_16x16x32_bf16 v[78:81], v[226:229], v[200:203], v[98:101]
	v_mfma_f32_16x16x32_bf16 v[98:101], v[230:233], v[204:207], v[78:81]
	s_setprio 0
	s_mov_b32 m0, s73
	v_lshl_add_u64 v[192:193], v[234:235], 0, s[22:23]
	s_barrier
	s_nop 2
	ds_read_b128 v[78:81], v175 offset:49152
	ds_read_b128 v[86:89], v175 offset:50176
	ds_read_b128 v[90:93], v175 offset:51200
	ds_read_b128 v[94:97], v175 offset:52224
	ds_read_b128 v[176:179], v175 offset:53248
	ds_read_b128 v[180:183], v175 offset:54272
	ds_read_b128 v[184:187], v175 offset:55296
	ds_read_b128 v[188:191], v175 offset:56320
	global_load_lds_dwordx4 v[192:193], off
	v_lshl_add_u64 v[192:193], v[236:237], 0, s[22:23]
	s_mov_b32 m0, s75
	s_nop 0
	global_load_lds_dwordx4 v[192:193], off
	s_barrier
	s_waitcnt lgkmcnt(0)
	s_setprio 1
	s_waitcnt lgkmcnt(0)
	v_mfma_f32_16x16x32_bf16 v[82:85], v[62:65], v[78:81], v[82:85]
	v_mfma_f32_16x16x32_bf16 v[54:57], v[70:73], v[78:81], v[54:57]
	v_mfma_f32_16x16x32_bf16 v[46:49], v[62:65], v[90:93], v[46:49]
	v_mfma_f32_16x16x32_bf16 v[38:41], v[70:73], v[90:93], v[38:41]
	v_mfma_f32_16x16x32_bf16 v[30:33], v[62:65], v[176:179], v[30:33]
	v_mfma_f32_16x16x32_bf16 v[22:25], v[70:73], v[176:179], v[22:25]
	v_mfma_f32_16x16x32_bf16 v[14:17], v[62:65], v[184:187], v[14:17]
	v_mfma_f32_16x16x32_bf16 v[6:9], v[70:73], v[184:187], v[6:9]
	v_mfma_f32_16x16x32_bf16 v[82:85], v[66:69], v[86:89], v[82:85]
	v_mfma_f32_16x16x32_bf16 v[54:57], v[74:77], v[86:89], v[54:57]
	v_mfma_f32_16x16x32_bf16 v[46:49], v[66:69], v[94:97], v[46:49]
	v_mfma_f32_16x16x32_bf16 v[38:41], v[74:77], v[94:97], v[38:41]
	v_mfma_f32_16x16x32_bf16 v[30:33], v[66:69], v[180:183], v[30:33]
	v_mfma_f32_16x16x32_bf16 v[22:25], v[74:77], v[180:183], v[22:25]
	v_mfma_f32_16x16x32_bf16 v[14:17], v[66:69], v[188:191], v[14:17]
	v_mfma_f32_16x16x32_bf16 v[6:9], v[74:77], v[188:191], v[6:9]
	s_setprio 0
	s_barrier
	s_add_u32 s36, s64, 0x40080
	s_addc_u32 s37, s65, 0
	s_add_i32 s64, s66, s68
	v_lshl_add_u64 v[62:63], s[36:37], 0, v[164:165]
	s_mov_b32 m0, s64
	s_nop 0
	global_load_lds_dwordx4 v[62:63], off
	v_lshl_add_u64 v[62:63], s[36:37], 0, v[162:163]
	s_add_i32 m0, s64, 0x2000
	s_nop 0
	global_load_lds_dwordx4 v[62:63], off
	s_waitcnt vmcnt(6)
	s_barrier
	s_setprio 1
	v_mfma_f32_16x16x32_bf16 v[58:61], v[208:211], v[78:81], v[58:61]
	v_mfma_f32_16x16x32_bf16 v[50:53], v[226:229], v[78:81], v[50:53]
	v_mfma_f32_16x16x32_bf16 v[42:45], v[208:211], v[90:93], v[42:45]
	v_mfma_f32_16x16x32_bf16 v[34:37], v[226:229], v[90:93], v[34:37]
	v_mfma_f32_16x16x32_bf16 v[26:29], v[208:211], v[176:179], v[26:29]
	v_mfma_f32_16x16x32_bf16 v[18:21], v[226:229], v[176:179], v[18:21]
	v_mfma_f32_16x16x32_bf16 v[10:13], v[208:211], v[184:187], v[10:13]
	v_mfma_f32_16x16x32_bf16 v[2:5], v[226:229], v[184:187], v[2:5]
	v_mfma_f32_16x16x32_bf16 v[74:77], v[222:225], v[86:89], v[58:61]
	v_mfma_f32_16x16x32_bf16 v[50:53], v[230:233], v[86:89], v[50:53]
	v_mfma_f32_16x16x32_bf16 v[42:45], v[222:225], v[94:97], v[42:45]
	v_mfma_f32_16x16x32_bf16 v[34:37], v[230:233], v[94:97], v[34:37]
	v_mfma_f32_16x16x32_bf16 v[26:29], v[222:225], v[180:183], v[26:29]
	v_mfma_f32_16x16x32_bf16 v[18:21], v[230:233], v[180:183], v[18:21]
	v_mfma_f32_16x16x32_bf16 v[10:13], v[222:225], v[188:191], v[10:13]
	v_mfma_f32_16x16x32_bf16 v[2:5], v[230:233], v[188:191], v[2:5]
	s_setprio 0
	s_add_i32 s83, s83, 2
	s_add_u32 s81, s81, 0x100
	s_addc_u32 s82, s82, 0
	s_cmp_gt_u32 s83, s32
	s_mov_b64 s[36:37], s[62:63]
	s_barrier
	s_cbranch_scc0 .LBB0_1099
	s_cmp_eq_u32 s32, 13
	s_cbranch_scc1 .Ltail_done_2
	s_add_u32 s62, s36, 0x100
	s_addc_u32 s63, s37, 0
	s_add_i32 s84, 0, 0x10000
	v_add_u32_e32 v70, s84, v170
	ds_read_b128 v[58:61], v70
	ds_read_b128 v[62:65], v70 offset:1024
	ds_read_b128 v[66:69], v70 offset:2048
	ds_read_b128 v[70:73], v70 offset:3072
	s_cmp_eq_u32 s83, 12
	s_cselect_b32 s67, s59, s63
	s_cselect_b32 s66, s78, s62
	s_cselect_b32 s65, s79, s82
	s_cselect_b32 s64, s80, s81
	v_lshl_add_u64 v[192:193], s[36:37], 0, v[168:169]
	s_add_i32 m0, s69, 0xc000
	ds_read_b128 v[78:81], v175
	ds_read_b128 v[86:89], v175 offset:1024
	ds_read_b128 v[90:93], v175 offset:2048
	ds_read_b128 v[94:97], v175 offset:3072
	ds_read_b128 v[176:179], v175 offset:4096
	ds_read_b128 v[180:183], v175 offset:5120
	ds_read_b128 v[184:187], v175 offset:6144
	ds_read_b128 v[188:191], v175 offset:7168
	global_load_lds_dwordx4 v[192:193], off
	v_lshl_add_u64 v[192:193], s[36:37], 0, v[166:167]
	s_add_i32 m0, s69, 0xe000
	s_nop 0
	global_load_lds_dwordx4 v[192:193], off
	s_waitcnt lgkmcnt(8)
	s_barrier
	s_waitcnt lgkmcnt(0)
	s_setprio 1
	s_waitcnt lgkmcnt(0)
	v_mfma_f32_16x16x32_bf16 v[158:161], v[58:61], v[78:81], v[158:161]
	v_mfma_f32_16x16x32_bf16 v[150:153], v[66:69], v[78:81], v[150:153]
	v_mfma_f32_16x16x32_bf16 v[142:145], v[58:61], v[90:93], v[142:145]
	v_mfma_f32_16x16x32_bf16 v[134:137], v[66:69], v[90:93], v[134:137]
	v_mfma_f32_16x16x32_bf16 v[126:129], v[58:61], v[176:179], v[126:129]
	v_mfma_f32_16x16x32_bf16 v[118:121], v[66:69], v[176:179], v[118:121]
	v_mfma_f32_16x16x32_bf16 v[110:113], v[58:61], v[184:187], v[110:113]
	v_mfma_f32_16x16x32_bf16 v[102:105], v[66:69], v[184:187], v[102:105]
	v_mfma_f32_16x16x32_bf16 v[158:161], v[62:65], v[86:89], v[158:161]
	v_mfma_f32_16x16x32_bf16 v[150:153], v[70:73], v[86:89], v[150:153]
	v_mfma_f32_16x16x32_bf16 v[142:145], v[62:65], v[94:97], v[142:145]
	v_mfma_f32_16x16x32_bf16 v[134:137], v[70:73], v[94:97], v[134:137]
	v_mfma_f32_16x16x32_bf16 v[126:129], v[62:65], v[180:183], v[126:129]
	v_mfma_f32_16x16x32_bf16 v[118:121], v[70:73], v[180:183], v[118:121]
	v_mfma_f32_16x16x32_bf16 v[110:113], v[62:65], v[188:191], v[110:113]
	v_mfma_f32_16x16x32_bf16 v[102:105], v[70:73], v[188:191], v[102:105]
	s_setprio 0
	s_barrier
	s_add_i32 s85, 0, 0x14000
	v_add_u32_e32 v192, s85, v170
	s_add_i32 s36, s84, s68
	ds_read_b128 v[200:203], v192
	ds_read_b128 v[204:207], v192 offset:1024
	ds_read_b128 v[208:211], v192 offset:2048
	ds_read_b128 v[222:225], v192 offset:3072
	v_lshl_add_u64 v[192:193], s[64:65], 0, v[164:165]
	s_mov_b32 m0, s36
	v_lshl_add_u64 v[214:215], s[64:65], 0, v[162:163]
	s_add_i32 m0, s36, 0x2000
	s_nop 0
	s_barrier
	s_waitcnt lgkmcnt(0)
	s_setprio 1
	s_waitcnt lgkmcnt(0)
	v_mfma_f32_16x16x32_bf16 v[154:157], v[200:203], v[78:81], v[154:157]
	v_mfma_f32_16x16x32_bf16 v[78:81], v[208:211], v[78:81], v[146:149]
	v_mfma_f32_16x16x32_bf16 v[154:157], v[204:207], v[86:89], v[154:157]
	v_mfma_f32_16x16x32_bf16 v[78:81], v[222:225], v[86:89], v[78:81]
	v_mfma_f32_16x16x32_bf16 v[86:89], v[200:203], v[90:93], v[138:141]
	v_mfma_f32_16x16x32_bf16 v[90:93], v[208:211], v[90:93], v[130:133]
	v_mfma_f32_16x16x32_bf16 v[114:117], v[208:211], v[176:179], v[114:117]
	v_mfma_f32_16x16x32_bf16 v[106:109], v[200:203], v[184:187], v[106:109]
	v_mfma_f32_16x16x32_bf16 v[98:101], v[208:211], v[184:187], v[98:101]
	v_mfma_f32_16x16x32_bf16 v[86:89], v[204:207], v[94:97], v[86:89]
	v_mfma_f32_16x16x32_bf16 v[90:93], v[222:225], v[94:97], v[90:93]
	v_mfma_f32_16x16x32_bf16 v[94:97], v[200:203], v[176:179], v[122:125]
	v_mfma_f32_16x16x32_bf16 v[114:117], v[222:225], v[180:183], v[114:117]
	v_mfma_f32_16x16x32_bf16 v[106:109], v[204:207], v[188:191], v[106:109]
	v_mfma_f32_16x16x32_bf16 v[98:101], v[222:225], v[188:191], v[98:101]
	v_mfma_f32_16x16x32_bf16 v[94:97], v[204:207], v[180:183], v[94:97]
	s_setprio 0
	s_mov_b32 m0, s69
	v_lshl_add_u64 v[234:235], s[66:67], 0, v[164:165]
	s_barrier
	ds_read_b128 v[122:125], v175 offset:16384
	ds_read_b128 v[130:133], v175 offset:17408
	ds_read_b128 v[138:141], v175 offset:18432
	ds_read_b128 v[146:149], v175 offset:19456
	ds_read_b128 v[176:179], v175 offset:20480
	ds_read_b128 v[180:183], v175 offset:21504
	ds_read_b128 v[184:187], v175 offset:22528
	ds_read_b128 v[188:191], v175 offset:23552
	v_lshl_add_u64 v[236:237], s[66:67], 0, v[162:163]
	s_mov_b32 m0, s70
	s_nop 0
	s_barrier
	s_waitcnt lgkmcnt(0)
	s_setprio 1
	s_waitcnt lgkmcnt(0)
	v_mfma_f32_16x16x32_bf16 v[82:85], v[58:61], v[122:125], v[82:85]
	v_mfma_f32_16x16x32_bf16 v[54:57], v[66:69], v[122:125], v[54:57]
	v_mfma_f32_16x16x32_bf16 v[46:49], v[58:61], v[138:141], v[46:49]
	v_mfma_f32_16x16x32_bf16 v[38:41], v[66:69], v[138:141], v[38:41]
	v_mfma_f32_16x16x32_bf16 v[30:33], v[58:61], v[176:179], v[30:33]
	v_mfma_f32_16x16x32_bf16 v[22:25], v[66:69], v[176:179], v[22:25]
	v_mfma_f32_16x16x32_bf16 v[14:17], v[58:61], v[184:187], v[14:17]
	v_mfma_f32_16x16x32_bf16 v[6:9], v[66:69], v[184:187], v[6:9]
	v_mfma_f32_16x16x32_bf16 v[82:85], v[62:65], v[130:133], v[82:85]
	v_mfma_f32_16x16x32_bf16 v[54:57], v[70:73], v[130:133], v[54:57]
	v_mfma_f32_16x16x32_bf16 v[46:49], v[62:65], v[146:149], v[46:49]
	v_mfma_f32_16x16x32_bf16 v[38:41], v[70:73], v[146:149], v[38:41]
	v_mfma_f32_16x16x32_bf16 v[30:33], v[62:65], v[180:183], v[30:33]
	v_mfma_f32_16x16x32_bf16 v[22:25], v[70:73], v[180:183], v[22:25]
	v_mfma_f32_16x16x32_bf16 v[14:17], v[62:65], v[188:191], v[14:17]
	v_mfma_f32_16x16x32_bf16 v[6:9], v[70:73], v[188:191], v[6:9]
	s_setprio 0
	s_barrier
	s_add_u32 s36, s64, 0x40000
	s_addc_u32 s37, s65, 0
	s_add_i32 s84, s85, s68
	v_lshl_add_u64 v[58:59], s[36:37], 0, v[164:165]
	s_mov_b32 m0, s84
	s_nop 0
	v_lshl_add_u64 v[58:59], s[36:37], 0, v[162:163]
	s_add_i32 m0, s84, 0x2000
	s_nop 0
	s_waitcnt vmcnt(0)
	s_barrier
	s_setprio 1
	v_mfma_f32_16x16x32_bf16 v[50:53], v[208:211], v[122:125], v[50:53]
	v_mfma_f32_16x16x32_bf16 v[42:45], v[200:203], v[138:141], v[42:45]
	v_mfma_f32_16x16x32_bf16 v[34:37], v[208:211], v[138:141], v[34:37]
	v_mfma_f32_16x16x32_bf16 v[26:29], v[200:203], v[176:179], v[26:29]
	v_mfma_f32_16x16x32_bf16 v[18:21], v[208:211], v[176:179], v[18:21]
	v_mfma_f32_16x16x32_bf16 v[10:13], v[200:203], v[184:187], v[10:13]
	v_mfma_f32_16x16x32_bf16 v[2:5], v[208:211], v[184:187], v[2:5]
	v_mfma_f32_16x16x32_bf16 v[58:61], v[200:203], v[122:125], v[74:77]
	v_mfma_f32_16x16x32_bf16 v[50:53], v[222:225], v[130:133], v[50:53]
	v_mfma_f32_16x16x32_bf16 v[42:45], v[204:207], v[146:149], v[42:45]
	v_mfma_f32_16x16x32_bf16 v[34:37], v[222:225], v[146:149], v[34:37]
	v_mfma_f32_16x16x32_bf16 v[26:29], v[204:207], v[180:183], v[26:29]
	v_mfma_f32_16x16x32_bf16 v[18:21], v[222:225], v[180:183], v[18:21]
	v_mfma_f32_16x16x32_bf16 v[10:13], v[204:207], v[188:191], v[10:13]
	v_mfma_f32_16x16x32_bf16 v[2:5], v[222:225], v[188:191], v[2:5]
	v_mfma_f32_16x16x32_bf16 v[58:61], v[204:207], v[130:133], v[58:61]
	s_setprio 0
	s_add_i32 s84, 0, 0x18000
	v_add_u32_e32 v74, s84, v170
	s_barrier
	ds_read_b128 v[62:65], v74
	ds_read_b128 v[66:69], v74 offset:1024
	ds_read_b128 v[70:73], v74 offset:2048
	ds_read_b128 v[74:77], v74 offset:3072
	s_add_u32 s36, s66, 0x40000
	s_addc_u32 s37, s67, 0
	s_mov_b32 m0, s71
	v_lshl_add_u64 v[138:139], s[36:37], 0, v[164:165]
	ds_read_b128 v[122:125], v175 offset:32768
	ds_read_b128 v[130:133], v175 offset:33792
	ds_read_b128 v[176:179], v175 offset:34816
	ds_read_b128 v[180:183], v175 offset:35840
	ds_read_b128 v[184:187], v175 offset:36864
	ds_read_b128 v[188:191], v175 offset:37888
	ds_read_b128 v[200:203], v175 offset:38912
	ds_read_b128 v[204:207], v175 offset:39936
	v_lshl_add_u64 v[138:139], s[36:37], 0, v[162:163]
	s_mov_b32 m0, s72
	s_nop 0
	s_waitcnt lgkmcnt(8)
	s_barrier
	s_waitcnt lgkmcnt(0)
	s_setprio 1
	s_waitcnt lgkmcnt(0)
	v_mfma_f32_16x16x32_bf16 v[138:141], v[62:65], v[122:125], v[158:161]
	v_mfma_f32_16x16x32_bf16 v[158:161], v[66:69], v[130:133], v[138:141]
	v_mfma_f32_16x16x32_bf16 v[138:141], v[70:73], v[122:125], v[150:153]
	v_mfma_f32_16x16x32_bf16 v[150:153], v[74:77], v[130:133], v[138:141]
	v_mfma_f32_16x16x32_bf16 v[138:141], v[62:65], v[176:179], v[142:145]
	v_mfma_f32_16x16x32_bf16 v[134:137], v[70:73], v[176:179], v[134:137]
	v_mfma_f32_16x16x32_bf16 v[126:129], v[62:65], v[184:187], v[126:129]
	v_mfma_f32_16x16x32_bf16 v[118:121], v[70:73], v[184:187], v[118:121]
	v_mfma_f32_16x16x32_bf16 v[110:113], v[62:65], v[200:203], v[110:113]
	v_mfma_f32_16x16x32_bf16 v[102:105], v[70:73], v[200:203], v[102:105]
	v_mfma_f32_16x16x32_bf16 v[142:145], v[66:69], v[180:183], v[138:141]
	v_mfma_f32_16x16x32_bf16 v[134:137], v[74:77], v[180:183], v[134:137]
	v_mfma_f32_16x16x32_bf16 v[126:129], v[66:69], v[188:191], v[126:129]
	v_mfma_f32_16x16x32_bf16 v[118:121], v[74:77], v[188:191], v[118:121]
	v_mfma_f32_16x16x32_bf16 v[110:113], v[66:69], v[204:207], v[110:113]
	v_mfma_f32_16x16x32_bf16 v[102:105], v[74:77], v[204:207], v[102:105]
	s_setprio 0
	s_barrier
	s_add_i32 s66, 0, 0x1c000
	v_add_u32_e32 v138, s66, v170
	s_add_i32 s36, s84, s68
	ds_read_b128 v[208:211], v138
	ds_read_b128 v[222:225], v138 offset:1024
	ds_read_b128 v[226:229], v138 offset:2048
	ds_read_b128 v[230:233], v138 offset:3072
	v_lshl_add_u64 v[138:139], v[192:193], 0, s[22:23]
	s_mov_b32 m0, s36
	s_nop 0
	v_lshl_add_u64 v[138:139], v[214:215], 0, s[22:23]
	s_add_i32 m0, s36, 0x2000
	s_nop 0
	s_barrier
	s_waitcnt lgkmcnt(0)
	s_setprio 1
	s_waitcnt lgkmcnt(0)
	v_mfma_f32_16x16x32_bf16 v[78:81], v[226:229], v[122:125], v[78:81]
	v_mfma_f32_16x16x32_bf16 v[138:141], v[208:211], v[122:125], v[154:157]
	v_mfma_f32_16x16x32_bf16 v[146:149], v[230:233], v[130:133], v[78:81]
	v_mfma_f32_16x16x32_bf16 v[78:81], v[208:211], v[176:179], v[86:89]
	v_mfma_f32_16x16x32_bf16 v[154:157], v[222:225], v[130:133], v[138:141]
	v_mfma_f32_16x16x32_bf16 v[138:141], v[222:225], v[180:183], v[78:81]
	v_mfma_f32_16x16x32_bf16 v[78:81], v[226:229], v[176:179], v[90:93]
	v_mfma_f32_16x16x32_bf16 v[130:133], v[230:233], v[180:183], v[78:81]
	v_mfma_f32_16x16x32_bf16 v[78:81], v[208:211], v[184:187], v[94:97]
	v_mfma_f32_16x16x32_bf16 v[122:125], v[222:225], v[188:191], v[78:81]
	v_mfma_f32_16x16x32_bf16 v[78:81], v[226:229], v[184:187], v[114:117]
	v_mfma_f32_16x16x32_bf16 v[114:117], v[230:233], v[188:191], v[78:81]
	v_mfma_f32_16x16x32_bf16 v[78:81], v[208:211], v[200:203], v[106:109]
	v_mfma_f32_16x16x32_bf16 v[106:109], v[222:225], v[204:207], v[78:81]
	v_mfma_f32_16x16x32_bf16 v[78:81], v[226:229], v[200:203], v[98:101]
	v_mfma_f32_16x16x32_bf16 v[98:101], v[230:233], v[204:207], v[78:81]
	s_setprio 0
	s_mov_b32 m0, s73
	v_lshl_add_u64 v[192:193], v[234:235], 0, s[22:23]
	s_barrier
	s_nop 2
	ds_read_b128 v[78:81], v175 offset:49152
	ds_read_b128 v[86:89], v175 offset:50176
	ds_read_b128 v[90:93], v175 offset:51200
	ds_read_b128 v[94:97], v175 offset:52224
	ds_read_b128 v[176:179], v175 offset:53248
	ds_read_b128 v[180:183], v175 offset:54272
	ds_read_b128 v[184:187], v175 offset:55296
	ds_read_b128 v[188:191], v175 offset:56320
	v_lshl_add_u64 v[192:193], v[236:237], 0, s[22:23]
	s_mov_b32 m0, s75
	s_nop 0
	s_barrier
	s_waitcnt lgkmcnt(0)
	s_setprio 1
	s_waitcnt lgkmcnt(0)
	v_mfma_f32_16x16x32_bf16 v[82:85], v[62:65], v[78:81], v[82:85]
	v_mfma_f32_16x16x32_bf16 v[54:57], v[70:73], v[78:81], v[54:57]
	v_mfma_f32_16x16x32_bf16 v[46:49], v[62:65], v[90:93], v[46:49]
	v_mfma_f32_16x16x32_bf16 v[38:41], v[70:73], v[90:93], v[38:41]
	v_mfma_f32_16x16x32_bf16 v[30:33], v[62:65], v[176:179], v[30:33]
	v_mfma_f32_16x16x32_bf16 v[22:25], v[70:73], v[176:179], v[22:25]
	v_mfma_f32_16x16x32_bf16 v[14:17], v[62:65], v[184:187], v[14:17]
	v_mfma_f32_16x16x32_bf16 v[6:9], v[70:73], v[184:187], v[6:9]
	v_mfma_f32_16x16x32_bf16 v[82:85], v[66:69], v[86:89], v[82:85]
	v_mfma_f32_16x16x32_bf16 v[54:57], v[74:77], v[86:89], v[54:57]
	v_mfma_f32_16x16x32_bf16 v[46:49], v[66:69], v[94:97], v[46:49]
	v_mfma_f32_16x16x32_bf16 v[38:41], v[74:77], v[94:97], v[38:41]
	v_mfma_f32_16x16x32_bf16 v[30:33], v[66:69], v[180:183], v[30:33]
	v_mfma_f32_16x16x32_bf16 v[22:25], v[74:77], v[180:183], v[22:25]
	v_mfma_f32_16x16x32_bf16 v[14:17], v[66:69], v[188:191], v[14:17]
	v_mfma_f32_16x16x32_bf16 v[6:9], v[74:77], v[188:191], v[6:9]
	s_setprio 0
	s_barrier
	s_add_u32 s36, s64, 0x40080
	s_addc_u32 s37, s65, 0
	s_add_i32 s64, s66, s68
	v_lshl_add_u64 v[62:63], s[36:37], 0, v[164:165]
	s_mov_b32 m0, s64
	s_nop 0
	v_lshl_add_u64 v[62:63], s[36:37], 0, v[162:163]
	s_add_i32 m0, s64, 0x2000
	s_nop 0
	s_barrier
	s_setprio 1
	v_mfma_f32_16x16x32_bf16 v[58:61], v[208:211], v[78:81], v[58:61]
	v_mfma_f32_16x16x32_bf16 v[50:53], v[226:229], v[78:81], v[50:53]
	v_mfma_f32_16x16x32_bf16 v[42:45], v[208:211], v[90:93], v[42:45]
	v_mfma_f32_16x16x32_bf16 v[34:37], v[226:229], v[90:93], v[34:37]
	v_mfma_f32_16x16x32_bf16 v[26:29], v[208:211], v[176:179], v[26:29]
	v_mfma_f32_16x16x32_bf16 v[18:21], v[226:229], v[176:179], v[18:21]
	v_mfma_f32_16x16x32_bf16 v[10:13], v[208:211], v[184:187], v[10:13]
	v_mfma_f32_16x16x32_bf16 v[2:5], v[226:229], v[184:187], v[2:5]
	v_mfma_f32_16x16x32_bf16 v[74:77], v[222:225], v[86:89], v[58:61]
	v_mfma_f32_16x16x32_bf16 v[50:53], v[230:233], v[86:89], v[50:53]
	v_mfma_f32_16x16x32_bf16 v[42:45], v[222:225], v[94:97], v[42:45]
	v_mfma_f32_16x16x32_bf16 v[34:37], v[230:233], v[94:97], v[34:37]
	v_mfma_f32_16x16x32_bf16 v[26:29], v[222:225], v[180:183], v[26:29]
	v_mfma_f32_16x16x32_bf16 v[18:21], v[230:233], v[180:183], v[18:21]
	v_mfma_f32_16x16x32_bf16 v[10:13], v[222:225], v[188:191], v[10:13]
	v_mfma_f32_16x16x32_bf16 v[2:5], v[230:233], v[188:191], v[2:5]
	s_setprio 0
	s_add_i32 s83, s83, 2
	s_add_u32 s81, s81, 0x100
	s_addc_u32 s82, s82, 0
	s_cmp_gt_u32 s83, 13
	s_mov_b64 s[36:37], s[62:63]
	s_barrier

.LBB0_1174:
	s_add_i32 s89, s89, 1
	s_mul_i32 s27, s89, s26
	s_add_i32 s27, s27, s2
	s_cmpk_lt_i32 s27, 0x100
	s_cselect_b64 s[70:71], -1, 0
	s_cmpk_gt_i32 s27, 0xff
	s_cselect_b64 s[68:69], -1, 0
	s_cselect_b32 s32, s88, s84
	s_lshl_b32 s5, s27, 3
	s_and_b32 s5, s5, 56
	s_bfe_u32 s72, s27, 0x30003
	s_or_b32 s5, s5, s72
	s_and_b64 vcc, exec, s[68:69]
	s_cbranch_vccnz .LBB0_1176
	s_mul_i32 s66, s77, s5
	s_add_u32 s66, s62, s66
	s_addc_u32 s67, s63, 0

.LBB0_1179:
	s_add_i32 s92, s42, 2
	s_add_u32 s72, s36, 0x80
	s_addc_u32 s43, s37, 0
	s_add_i32 s93, 0, 0x10000
	v_add_u32_e32 v1, s93, v223
	ds_read_b128 v[50:53], v1
	ds_read_b128 v[54:57], v1 offset:1024
	ds_read_b128 v[58:61], v1 offset:2048
	ds_read_b128 v[62:65], v1 offset:3072
	s_cmp_eq_u32 s88, s42
	s_cselect_b32 s42, s66, s72
	s_cselect_b32 s43, s67, s43
	s_cselect_b32 s73, s71, s91
	s_cselect_b32 s72, s70, s27
	v_lshl_add_u64 v[178:179], s[36:37], 0, v[206:207]
	s_add_i32 m0, s79, 0xc000
	ds_read_b128 v[66:69], v230
	ds_read_b128 v[70:73], v230 offset:1024
	ds_read_b128 v[74:77], v230 offset:2048
	ds_read_b128 v[78:81], v230 offset:3072
	ds_read_b128 v[146:149], v230 offset:4096
	ds_read_b128 v[154:157], v230 offset:5120
	ds_read_b128 v[170:173], v230 offset:6144
	ds_read_b128 v[174:177], v230 offset:7168
	global_load_lds_dwordx4 v[178:179], off
	v_lshl_add_u64 v[178:179], s[36:37], 0, v[204:205]
	s_add_i32 m0, s79, 0xe000
	s_nop 0
	global_load_lds_dwordx4 v[178:179], off
	s_waitcnt lgkmcnt(8)
	s_barrier
	s_waitcnt lgkmcnt(0)
	s_setprio 1
	s_waitcnt lgkmcnt(0)
	v_mfma_f32_16x16x32_bf16 v[166:169], v[50:53], v[66:69], v[166:169]
	v_mfma_f32_16x16x32_bf16 v[162:165], v[58:61], v[66:69], v[162:165]
	v_mfma_f32_16x16x32_bf16 v[142:145], v[50:53], v[74:77], v[142:145]
	v_mfma_f32_16x16x32_bf16 v[138:141], v[58:61], v[74:77], v[138:141]
	v_mfma_f32_16x16x32_bf16 v[126:129], v[50:53], v[146:149], v[126:129]
	v_mfma_f32_16x16x32_bf16 v[122:125], v[58:61], v[146:149], v[122:125]
	v_mfma_f32_16x16x32_bf16 v[110:113], v[50:53], v[170:173], v[110:113]
	v_mfma_f32_16x16x32_bf16 v[106:109], v[58:61], v[170:173], v[106:109]
	v_mfma_f32_16x16x32_bf16 v[166:169], v[54:57], v[70:73], v[166:169]
	v_mfma_f32_16x16x32_bf16 v[162:165], v[62:65], v[70:73], v[162:165]
	v_mfma_f32_16x16x32_bf16 v[142:145], v[54:57], v[78:81], v[142:145]
	v_mfma_f32_16x16x32_bf16 v[138:141], v[62:65], v[78:81], v[138:141]
	v_mfma_f32_16x16x32_bf16 v[126:129], v[54:57], v[154:157], v[126:129]
	v_mfma_f32_16x16x32_bf16 v[122:125], v[62:65], v[154:157], v[122:125]
	v_mfma_f32_16x16x32_bf16 v[110:113], v[54:57], v[174:177], v[110:113]
	v_mfma_f32_16x16x32_bf16 v[106:109], v[62:65], v[174:177], v[106:109]
	s_setprio 0
	s_barrier
	s_add_i32 s94, 0, 0x14000
	s_add_i32 s93, s93, s78
	v_add_u32_e32 v1, s94, v223
	v_lshl_add_u64 v[214:215], s[72:73], 0, v[202:203]
	s_mov_b32 m0, s93
	ds_read_b128 v[178:181], v1
	ds_read_b128 v[182:185], v1 offset:1024
	ds_read_b128 v[186:189], v1 offset:2048
	ds_read_b128 v[190:193], v1 offset:3072
	global_load_lds_dwordx4 v[214:215], off
	v_lshl_add_u64 v[236:237], s[72:73], 0, v[200:201]
	s_add_i32 m0, s93, 0x2000
	s_nop 0
	global_load_lds_dwordx4 v[236:237], off
	s_barrier
	s_waitcnt lgkmcnt(0)
	s_setprio 1
	s_waitcnt lgkmcnt(0)
	v_mfma_f32_16x16x32_bf16 v[158:161], v[178:181], v[66:69], v[158:161]
	v_mfma_f32_16x16x32_bf16 v[66:69], v[186:189], v[66:69], v[150:153]
	v_mfma_f32_16x16x32_bf16 v[158:161], v[182:185], v[70:73], v[158:161]
	v_mfma_f32_16x16x32_bf16 v[66:69], v[190:193], v[70:73], v[66:69]
	v_mfma_f32_16x16x32_bf16 v[70:73], v[178:181], v[74:77], v[134:137]
	v_mfma_f32_16x16x32_bf16 v[74:77], v[186:189], v[74:77], v[130:133]
	v_mfma_f32_16x16x32_bf16 v[114:117], v[186:189], v[146:149], v[114:117]
	v_mfma_f32_16x16x32_bf16 v[102:105], v[178:181], v[170:173], v[102:105]
	v_mfma_f32_16x16x32_bf16 v[98:101], v[186:189], v[170:173], v[98:101]
	v_mfma_f32_16x16x32_bf16 v[70:73], v[182:185], v[78:81], v[70:73]
	v_mfma_f32_16x16x32_bf16 v[74:77], v[190:193], v[78:81], v[74:77]
	v_mfma_f32_16x16x32_bf16 v[78:81], v[178:181], v[146:149], v[118:121]
	v_mfma_f32_16x16x32_bf16 v[114:117], v[190:193], v[154:157], v[114:117]
	v_mfma_f32_16x16x32_bf16 v[102:105], v[182:185], v[174:177], v[102:105]
	v_mfma_f32_16x16x32_bf16 v[98:101], v[190:193], v[174:177], v[98:101]
	v_mfma_f32_16x16x32_bf16 v[78:81], v[182:185], v[154:157], v[78:81]
	s_setprio 0
	s_mov_b32 m0, s79
	v_lshl_add_u64 v[238:239], s[42:43], 0, v[202:203]
	s_barrier
	ds_read_b128 v[118:121], v230 offset:16384
	ds_read_b128 v[130:133], v230 offset:17408
	ds_read_b128 v[134:137], v230 offset:18432
	ds_read_b128 v[146:149], v230 offset:19456
	ds_read_b128 v[150:153], v230 offset:20480
	ds_read_b128 v[154:157], v230 offset:21504
	ds_read_b128 v[170:173], v230 offset:22528
	ds_read_b128 v[174:177], v230 offset:23552
	global_load_lds_dwordx4 v[238:239], off
	v_lshl_add_u64 v[240:241], s[42:43], 0, v[200:201]
	s_mov_b32 m0, s80
	s_nop 0
	global_load_lds_dwordx4 v[240:241], off
	s_barrier
	s_waitcnt lgkmcnt(0)
	s_setprio 1
	s_waitcnt lgkmcnt(0)
	v_mfma_f32_16x16x32_bf16 v[94:97], v[50:53], v[118:121], v[94:97]
	v_mfma_f32_16x16x32_bf16 v[90:93], v[58:61], v[118:121], v[90:93]
	v_mfma_f32_16x16x32_bf16 v[46:49], v[50:53], v[134:137], v[46:49]
	v_mfma_f32_16x16x32_bf16 v[42:45], v[58:61], v[134:137], v[42:45]
	v_mfma_f32_16x16x32_bf16 v[30:33], v[50:53], v[150:153], v[30:33]
	v_mfma_f32_16x16x32_bf16 v[26:29], v[58:61], v[150:153], v[26:29]
	v_mfma_f32_16x16x32_bf16 v[14:17], v[50:53], v[170:173], v[14:17]
	v_mfma_f32_16x16x32_bf16 v[10:13], v[58:61], v[170:173], v[10:13]
	v_mfma_f32_16x16x32_bf16 v[94:97], v[54:57], v[130:133], v[94:97]
	v_mfma_f32_16x16x32_bf16 v[90:93], v[62:65], v[130:133], v[90:93]
	v_mfma_f32_16x16x32_bf16 v[46:49], v[54:57], v[146:149], v[46:49]
	v_mfma_f32_16x16x32_bf16 v[42:45], v[62:65], v[146:149], v[42:45]
	v_mfma_f32_16x16x32_bf16 v[30:33], v[54:57], v[154:157], v[30:33]
	v_mfma_f32_16x16x32_bf16 v[26:29], v[62:65], v[154:157], v[26:29]
	v_mfma_f32_16x16x32_bf16 v[14:17], v[54:57], v[174:177], v[14:17]
	v_mfma_f32_16x16x32_bf16 v[10:13], v[62:65], v[174:177], v[10:13]
	s_setprio 0
	s_barrier
	s_add_u32 s72, s72, s4
	s_addc_u32 s73, s73, 0
	s_add_i32 s93, s94, s78
	v_lshl_add_u64 v[242:243], s[72:73], 0, v[202:203]
	s_mov_b32 m0, s93
	v_lshl_add_u64 v[244:245], s[72:73], 0, v[200:201]
	global_load_lds_dwordx4 v[242:243], off
	s_add_i32 m0, s93, 0x2000
	s_nop 0
	global_load_lds_dwordx4 v[244:245], off
	s_waitcnt vmcnt(6)
	s_barrier
	s_setprio 1
	v_mfma_f32_16x16x32_bf16 v[38:41], v[178:181], v[134:137], v[38:41]
	v_mfma_f32_16x16x32_bf16 v[34:37], v[186:189], v[134:137], v[34:37]
	v_mfma_f32_16x16x32_bf16 v[22:25], v[178:181], v[150:153], v[22:25]
	v_mfma_f32_16x16x32_bf16 v[18:21], v[186:189], v[150:153], v[18:21]
	v_mfma_f32_16x16x32_bf16 v[6:9], v[178:181], v[170:173], v[6:9]
	v_mfma_f32_16x16x32_bf16 v[2:5], v[186:189], v[170:173], v[2:5]
	v_mfma_f32_16x16x32_bf16 v[50:53], v[178:181], v[118:121], v[86:89]
	v_mfma_f32_16x16x32_bf16 v[54:57], v[186:189], v[118:121], v[82:85]
	v_mfma_f32_16x16x32_bf16 v[38:41], v[182:185], v[146:149], v[38:41]
	v_mfma_f32_16x16x32_bf16 v[34:37], v[190:193], v[146:149], v[34:37]
	v_mfma_f32_16x16x32_bf16 v[22:25], v[182:185], v[154:157], v[22:25]
	v_mfma_f32_16x16x32_bf16 v[18:21], v[190:193], v[154:157], v[18:21]
	v_mfma_f32_16x16x32_bf16 v[6:9], v[182:185], v[174:177], v[6:9]
	v_mfma_f32_16x16x32_bf16 v[2:5], v[190:193], v[174:177], v[2:5]
	v_mfma_f32_16x16x32_bf16 v[50:53], v[182:185], v[130:133], v[50:53]
	v_mfma_f32_16x16x32_bf16 v[54:57], v[190:193], v[130:133], v[54:57]
	s_setprio 0
	s_add_i32 s72, 0, 0x18000
	v_add_u32_e32 v1, s72, v223
	s_barrier
	ds_read_b128 v[58:61], v1
	ds_read_b128 v[62:65], v1 offset:1024
	ds_read_b128 v[82:85], v1 offset:2048
	ds_read_b128 v[86:89], v1 offset:3072
	s_add_u32 s42, s42, s4
	s_addc_u32 s43, s43, 0
	s_mov_b32 m0, s81
	v_lshl_add_u64 v[134:135], s[42:43], 0, v[202:203]
	ds_read_b128 v[118:121], v230 offset:32768
	ds_read_b128 v[130:133], v230 offset:33792
	ds_read_b128 v[146:149], v230 offset:34816
	ds_read_b128 v[154:157], v230 offset:35840
	ds_read_b128 v[170:173], v230 offset:36864
	ds_read_b128 v[174:177], v230 offset:37888
	ds_read_b128 v[178:181], v230 offset:38912
	ds_read_b128 v[182:185], v230 offset:39936
	global_load_lds_dwordx4 v[134:135], off
	v_lshl_add_u64 v[134:135], s[42:43], 0, v[200:201]
	s_mov_b32 m0, s82
	s_nop 0
	global_load_lds_dwordx4 v[134:135], off
	s_waitcnt lgkmcnt(8)
	s_barrier
	s_waitcnt lgkmcnt(0)
	s_setprio 1
	s_waitcnt lgkmcnt(0)
	v_mfma_f32_16x16x32_bf16 v[134:137], v[58:61], v[118:121], v[166:169]
	v_mfma_f32_16x16x32_bf16 v[166:169], v[62:65], v[130:133], v[134:137]
	v_mfma_f32_16x16x32_bf16 v[134:137], v[82:85], v[118:121], v[162:165]
	v_mfma_f32_16x16x32_bf16 v[162:165], v[86:89], v[130:133], v[134:137]
	v_mfma_f32_16x16x32_bf16 v[134:137], v[58:61], v[146:149], v[142:145]
	v_mfma_f32_16x16x32_bf16 v[142:145], v[62:65], v[154:157], v[134:137]
	v_mfma_f32_16x16x32_bf16 v[134:137], v[82:85], v[146:149], v[138:141]
	v_mfma_f32_16x16x32_bf16 v[126:129], v[58:61], v[170:173], v[126:129]
	v_mfma_f32_16x16x32_bf16 v[122:125], v[82:85], v[170:173], v[122:125]
	v_mfma_f32_16x16x32_bf16 v[110:113], v[58:61], v[178:181], v[110:113]
	v_mfma_f32_16x16x32_bf16 v[106:109], v[82:85], v[178:181], v[106:109]
	v_mfma_f32_16x16x32_bf16 v[138:141], v[86:89], v[154:157], v[134:137]
	v_mfma_f32_16x16x32_bf16 v[126:129], v[62:65], v[174:177], v[126:129]
	v_mfma_f32_16x16x32_bf16 v[122:125], v[86:89], v[174:177], v[122:125]
	v_mfma_f32_16x16x32_bf16 v[110:113], v[62:65], v[182:185], v[110:113]
	v_mfma_f32_16x16x32_bf16 v[106:109], v[86:89], v[182:185], v[106:109]
	s_setprio 0
	s_barrier
	s_add_i32 s42, 0, 0x1c000
	s_add_i32 s43, s72, s78
	v_add_u32_e32 v1, s42, v223
	v_lshl_add_u64 v[134:135], v[214:215], 0, s[22:23]
	s_mov_b32 m0, s43
	ds_read_b128 v[186:189], v1
	ds_read_b128 v[190:193], v1 offset:1024
	ds_read_b128 v[208:211], v1 offset:2048
	ds_read_b128 v[232:235], v1 offset:3072
	global_load_lds_dwordx4 v[134:135], off
	v_lshl_add_u64 v[134:135], v[236:237], 0, s[22:23]
	s_add_i32 m0, s43, 0x2000
	s_nop 0
	global_load_lds_dwordx4 v[134:135], off
	s_barrier
	s_waitcnt lgkmcnt(0)
	s_setprio 1
	s_waitcnt lgkmcnt(0)
	v_mfma_f32_16x16x32_bf16 v[66:69], v[208:211], v[118:121], v[66:69]
	v_mfma_f32_16x16x32_bf16 v[134:137], v[186:189], v[118:121], v[158:161]
	v_mfma_f32_16x16x32_bf16 v[150:153], v[232:235], v[130:133], v[66:69]
	v_mfma_f32_16x16x32_bf16 v[66:69], v[186:189], v[146:149], v[70:73]
	v_mfma_f32_16x16x32_bf16 v[158:161], v[190:193], v[130:133], v[134:137]
	v_mfma_f32_16x16x32_bf16 v[134:137], v[190:193], v[154:157], v[66:69]
	v_mfma_f32_16x16x32_bf16 v[66:69], v[208:211], v[146:149], v[74:77]
	v_mfma_f32_16x16x32_bf16 v[130:133], v[232:235], v[154:157], v[66:69]
	v_mfma_f32_16x16x32_bf16 v[66:69], v[186:189], v[170:173], v[78:81]
	v_mfma_f32_16x16x32_bf16 v[118:121], v[190:193], v[174:177], v[66:69]
	v_mfma_f32_16x16x32_bf16 v[66:69], v[208:211], v[170:173], v[114:117]
	v_mfma_f32_16x16x32_bf16 v[114:117], v[232:235], v[174:177], v[66:69]
	v_mfma_f32_16x16x32_bf16 v[66:69], v[186:189], v[178:181], v[102:105]
	v_mfma_f32_16x16x32_bf16 v[102:105], v[190:193], v[182:185], v[66:69]
	v_mfma_f32_16x16x32_bf16 v[66:69], v[208:211], v[178:181], v[98:101]
	v_mfma_f32_16x16x32_bf16 v[98:101], v[232:235], v[182:185], v[66:69]
	s_setprio 0
	s_mov_b32 m0, s86
	v_lshl_add_u64 v[178:179], v[238:239], 0, s[22:23]
	s_barrier
	s_nop 2
	ds_read_b128 v[66:69], v230 offset:49152
	ds_read_b128 v[70:73], v230 offset:50176
	ds_read_b128 v[74:77], v230 offset:51200
	ds_read_b128 v[78:81], v230 offset:52224
	ds_read_b128 v[146:149], v230 offset:53248
	ds_read_b128 v[154:157], v230 offset:54272
	ds_read_b128 v[170:173], v230 offset:55296
	ds_read_b128 v[174:177], v230 offset:56320
	global_load_lds_dwordx4 v[178:179], off
	v_lshl_add_u64 v[178:179], v[240:241], 0, s[22:23]
	s_mov_b32 m0, s87
	s_nop 0
	global_load_lds_dwordx4 v[178:179], off
	s_barrier
	s_waitcnt lgkmcnt(0)
	s_setprio 1
	s_waitcnt lgkmcnt(0)
	v_mfma_f32_16x16x32_bf16 v[94:97], v[58:61], v[66:69], v[94:97]
	v_mfma_f32_16x16x32_bf16 v[90:93], v[82:85], v[66:69], v[90:93]
	v_mfma_f32_16x16x32_bf16 v[46:49], v[58:61], v[74:77], v[46:49]
	v_mfma_f32_16x16x32_bf16 v[42:45], v[82:85], v[74:77], v[42:45]
	v_mfma_f32_16x16x32_bf16 v[30:33], v[58:61], v[146:149], v[30:33]
	v_mfma_f32_16x16x32_bf16 v[26:29], v[82:85], v[146:149], v[26:29]
	v_mfma_f32_16x16x32_bf16 v[14:17], v[58:61], v[170:173], v[14:17]
	v_mfma_f32_16x16x32_bf16 v[10:13], v[82:85], v[170:173], v[10:13]
	v_mfma_f32_16x16x32_bf16 v[94:97], v[62:65], v[70:73], v[94:97]
	v_mfma_f32_16x16x32_bf16 v[90:93], v[86:89], v[70:73], v[90:93]
	v_mfma_f32_16x16x32_bf16 v[46:49], v[62:65], v[78:81], v[46:49]
	v_mfma_f32_16x16x32_bf16 v[42:45], v[86:89], v[78:81], v[42:45]
	v_mfma_f32_16x16x32_bf16 v[30:33], v[62:65], v[154:157], v[30:33]
	v_mfma_f32_16x16x32_bf16 v[26:29], v[86:89], v[154:157], v[26:29]
	v_mfma_f32_16x16x32_bf16 v[14:17], v[62:65], v[174:177], v[14:17]
	v_mfma_f32_16x16x32_bf16 v[10:13], v[86:89], v[174:177], v[10:13]
	s_setprio 0
	s_barrier
	s_add_i32 s42, s42, s78
	v_lshl_add_u64 v[58:59], v[242:243], 0, s[22:23]
	s_mov_b32 m0, s42
	s_nop 0
	global_load_lds_dwordx4 v[58:59], off
	v_lshl_add_u64 v[58:59], v[244:245], 0, s[22:23]
	s_add_i32 m0, s42, 0x2000
	s_nop 0
	global_load_lds_dwordx4 v[58:59], off
	s_waitcnt vmcnt(6)
	s_barrier
	s_setprio 1
	v_mfma_f32_16x16x32_bf16 v[50:53], v[186:189], v[66:69], v[50:53]
	v_mfma_f32_16x16x32_bf16 v[86:89], v[190:193], v[70:73], v[50:53]
	v_mfma_f32_16x16x32_bf16 v[50:53], v[208:211], v[66:69], v[54:57]
	v_mfma_f32_16x16x32_bf16 v[38:41], v[186:189], v[74:77], v[38:41]
	v_mfma_f32_16x16x32_bf16 v[34:37], v[208:211], v[74:77], v[34:37]
	v_mfma_f32_16x16x32_bf16 v[22:25], v[186:189], v[146:149], v[22:25]
	v_mfma_f32_16x16x32_bf16 v[18:21], v[208:211], v[146:149], v[18:21]
	v_mfma_f32_16x16x32_bf16 v[6:9], v[186:189], v[170:173], v[6:9]
	v_mfma_f32_16x16x32_bf16 v[2:5], v[208:211], v[170:173], v[2:5]
	v_mfma_f32_16x16x32_bf16 v[82:85], v[232:235], v[70:73], v[50:53]
	v_mfma_f32_16x16x32_bf16 v[38:41], v[190:193], v[78:81], v[38:41]
	v_mfma_f32_16x16x32_bf16 v[34:37], v[232:235], v[78:81], v[34:37]
	v_mfma_f32_16x16x32_bf16 v[22:25], v[190:193], v[154:157], v[22:25]
	v_mfma_f32_16x16x32_bf16 v[18:21], v[232:235], v[154:157], v[18:21]
	v_mfma_f32_16x16x32_bf16 v[6:9], v[190:193], v[174:177], v[6:9]
	v_mfma_f32_16x16x32_bf16 v[2:5], v[232:235], v[174:177], v[2:5]
	s_setprio 0
	s_add_u32 s27, s27, 0x100
	s_addc_u32 s91, s91, 0
	s_add_u32 s36, s36, 0x100
	s_addc_u32 s37, s37, 0
	s_cmp_ge_u32 s92, s32
	s_mov_b32 s42, s92
	s_barrier
	s_cbranch_scc0 .LBB0_1179
	s_cmp_eq_u32 s32, s84
	s_cbranch_scc1 .Ltail_done_1
	s_add_i32 s92, s42, 2
	s_add_u32 s72, s36, 0x80
	s_addc_u32 s43, s37, 0
	s_add_i32 s93, 0, 0x10000
	v_add_u32_e32 v1, s93, v223
	ds_read_b128 v[50:53], v1
	ds_read_b128 v[54:57], v1 offset:1024
	ds_read_b128 v[58:61], v1 offset:2048
	ds_read_b128 v[62:65], v1 offset:3072
	s_cmp_eq_u32 s88, s42
	s_cselect_b32 s42, s66, s72
	s_cselect_b32 s43, s67, s43
	s_cselect_b32 s73, s71, s91
	s_cselect_b32 s72, s70, s27
	v_lshl_add_u64 v[178:179], s[36:37], 0, v[206:207]
	s_add_i32 m0, s79, 0xc000
	ds_read_b128 v[66:69], v230
	ds_read_b128 v[70:73], v230 offset:1024
	ds_read_b128 v[74:77], v230 offset:2048
	ds_read_b128 v[78:81], v230 offset:3072
	ds_read_b128 v[146:149], v230 offset:4096
	ds_read_b128 v[154:157], v230 offset:5120
	ds_read_b128 v[170:173], v230 offset:6144
	ds_read_b128 v[174:177], v230 offset:7168
	global_load_lds_dwordx4 v[178:179], off
	v_lshl_add_u64 v[178:179], s[36:37], 0, v[204:205]
	s_add_i32 m0, s79, 0xe000
	s_nop 0
	global_load_lds_dwordx4 v[178:179], off
	s_waitcnt lgkmcnt(8)
	s_barrier
	s_waitcnt lgkmcnt(0)
	s_setprio 1
	s_waitcnt lgkmcnt(0)
	v_mfma_f32_16x16x32_bf16 v[166:169], v[50:53], v[66:69], v[166:169]
	v_mfma_f32_16x16x32_bf16 v[162:165], v[58:61], v[66:69], v[162:165]
	v_mfma_f32_16x16x32_bf16 v[142:145], v[50:53], v[74:77], v[142:145]
	v_mfma_f32_16x16x32_bf16 v[138:141], v[58:61], v[74:77], v[138:141]
	v_mfma_f32_16x16x32_bf16 v[126:129], v[50:53], v[146:149], v[126:129]
	v_mfma_f32_16x16x32_bf16 v[122:125], v[58:61], v[146:149], v[122:125]
	v_mfma_f32_16x16x32_bf16 v[110:113], v[50:53], v[170:173], v[110:113]
	v_mfma_f32_16x16x32_bf16 v[106:109], v[58:61], v[170:173], v[106:109]
	v_mfma_f32_16x16x32_bf16 v[166:169], v[54:57], v[70:73], v[166:169]
	v_mfma_f32_16x16x32_bf16 v[162:165], v[62:65], v[70:73], v[162:165]
	v_mfma_f32_16x16x32_bf16 v[142:145], v[54:57], v[78:81], v[142:145]
	v_mfma_f32_16x16x32_bf16 v[138:141], v[62:65], v[78:81], v[138:141]
	v_mfma_f32_16x16x32_bf16 v[126:129], v[54:57], v[154:157], v[126:129]
	v_mfma_f32_16x16x32_bf16 v[122:125], v[62:65], v[154:157], v[122:125]
	v_mfma_f32_16x16x32_bf16 v[110:113], v[54:57], v[174:177], v[110:113]
	v_mfma_f32_16x16x32_bf16 v[106:109], v[62:65], v[174:177], v[106:109]
	s_setprio 0
	s_barrier
	s_add_i32 s94, 0, 0x14000
	s_add_i32 s93, s93, s78
	v_add_u32_e32 v1, s94, v223
	v_lshl_add_u64 v[214:215], s[72:73], 0, v[202:203]
	s_mov_b32 m0, s93
	ds_read_b128 v[178:181], v1
	ds_read_b128 v[182:185], v1 offset:1024
	ds_read_b128 v[186:189], v1 offset:2048
	ds_read_b128 v[190:193], v1 offset:3072
	v_lshl_add_u64 v[236:237], s[72:73], 0, v[200:201]
	s_add_i32 m0, s93, 0x2000
	s_nop 0
	s_barrier
	s_waitcnt lgkmcnt(0)
	s_setprio 1
	s_waitcnt lgkmcnt(0)
	v_mfma_f32_16x16x32_bf16 v[158:161], v[178:181], v[66:69], v[158:161]
	v_mfma_f32_16x16x32_bf16 v[66:69], v[186:189], v[66:69], v[150:153]
	v_mfma_f32_16x16x32_bf16 v[158:161], v[182:185], v[70:73], v[158:161]
	v_mfma_f32_16x16x32_bf16 v[66:69], v[190:193], v[70:73], v[66:69]
	v_mfma_f32_16x16x32_bf16 v[70:73], v[178:181], v[74:77], v[134:137]
	v_mfma_f32_16x16x32_bf16 v[74:77], v[186:189], v[74:77], v[130:133]
	v_mfma_f32_16x16x32_bf16 v[114:117], v[186:189], v[146:149], v[114:117]
	v_mfma_f32_16x16x32_bf16 v[102:105], v[178:181], v[170:173], v[102:105]
	v_mfma_f32_16x16x32_bf16 v[98:101], v[186:189], v[170:173], v[98:101]
	v_mfma_f32_16x16x32_bf16 v[70:73], v[182:185], v[78:81], v[70:73]
	v_mfma_f32_16x16x32_bf16 v[74:77], v[190:193], v[78:81], v[74:77]
	v_mfma_f32_16x16x32_bf16 v[78:81], v[178:181], v[146:149], v[118:121]
	v_mfma_f32_16x16x32_bf16 v[114:117], v[190:193], v[154:157], v[114:117]
	v_mfma_f32_16x16x32_bf16 v[102:105], v[182:185], v[174:177], v[102:105]
	v_mfma_f32_16x16x32_bf16 v[98:101], v[190:193], v[174:177], v[98:101]
	v_mfma_f32_16x16x32_bf16 v[78:81], v[182:185], v[154:157], v[78:81]
	s_setprio 0
	s_mov_b32 m0, s79
	v_lshl_add_u64 v[238:239], s[42:43], 0, v[202:203]
	s_barrier
	ds_read_b128 v[118:121], v230 offset:16384
	ds_read_b128 v[130:133], v230 offset:17408
	ds_read_b128 v[134:137], v230 offset:18432
	ds_read_b128 v[146:149], v230 offset:19456
	ds_read_b128 v[150:153], v230 offset:20480
	ds_read_b128 v[154:157], v230 offset:21504
	ds_read_b128 v[170:173], v230 offset:22528
	ds_read_b128 v[174:177], v230 offset:23552
	v_lshl_add_u64 v[240:241], s[42:43], 0, v[200:201]
	s_mov_b32 m0, s80
	s_nop 0
	s_barrier
	s_waitcnt lgkmcnt(0)
	s_setprio 1
	s_waitcnt lgkmcnt(0)
	v_mfma_f32_16x16x32_bf16 v[94:97], v[50:53], v[118:121], v[94:97]
	v_mfma_f32_16x16x32_bf16 v[90:93], v[58:61], v[118:121], v[90:93]
	v_mfma_f32_16x16x32_bf16 v[46:49], v[50:53], v[134:137], v[46:49]
	v_mfma_f32_16x16x32_bf16 v[42:45], v[58:61], v[134:137], v[42:45]
	v_mfma_f32_16x16x32_bf16 v[30:33], v[50:53], v[150:153], v[30:33]
	v_mfma_f32_16x16x32_bf16 v[26:29], v[58:61], v[150:153], v[26:29]
	v_mfma_f32_16x16x32_bf16 v[14:17], v[50:53], v[170:173], v[14:17]
	v_mfma_f32_16x16x32_bf16 v[10:13], v[58:61], v[170:173], v[10:13]
	v_mfma_f32_16x16x32_bf16 v[94:97], v[54:57], v[130:133], v[94:97]
	v_mfma_f32_16x16x32_bf16 v[90:93], v[62:65], v[130:133], v[90:93]
	v_mfma_f32_16x16x32_bf16 v[46:49], v[54:57], v[146:149], v[46:49]
	v_mfma_f32_16x16x32_bf16 v[42:45], v[62:65], v[146:149], v[42:45]
	v_mfma_f32_16x16x32_bf16 v[30:33], v[54:57], v[154:157], v[30:33]
	v_mfma_f32_16x16x32_bf16 v[26:29], v[62:65], v[154:157], v[26:29]
	v_mfma_f32_16x16x32_bf16 v[14:17], v[54:57], v[174:177], v[14:17]
	v_mfma_f32_16x16x32_bf16 v[10:13], v[62:65], v[174:177], v[10:13]
	s_setprio 0
	s_barrier
	s_add_u32 s72, s72, s4
	s_addc_u32 s73, s73, 0
	s_add_i32 s93, s94, s78
	v_lshl_add_u64 v[242:243], s[72:73], 0, v[202:203]
	s_mov_b32 m0, s93
	v_lshl_add_u64 v[244:245], s[72:73], 0, v[200:201]
	s_add_i32 m0, s93, 0x2000
	s_nop 0
	s_waitcnt vmcnt(0)
	s_barrier
	s_setprio 1
	v_mfma_f32_16x16x32_bf16 v[38:41], v[178:181], v[134:137], v[38:41]
	v_mfma_f32_16x16x32_bf16 v[34:37], v[186:189], v[134:137], v[34:37]
	v_mfma_f32_16x16x32_bf16 v[22:25], v[178:181], v[150:153], v[22:25]
	v_mfma_f32_16x16x32_bf16 v[18:21], v[186:189], v[150:153], v[18:21]
	v_mfma_f32_16x16x32_bf16 v[6:9], v[178:181], v[170:173], v[6:9]
	v_mfma_f32_16x16x32_bf16 v[2:5], v[186:189], v[170:173], v[2:5]
	v_mfma_f32_16x16x32_bf16 v[50:53], v[178:181], v[118:121], v[86:89]
	v_mfma_f32_16x16x32_bf16 v[54:57], v[186:189], v[118:121], v[82:85]
	v_mfma_f32_16x16x32_bf16 v[38:41], v[182:185], v[146:149], v[38:41]
	v_mfma_f32_16x16x32_bf16 v[34:37], v[190:193], v[146:149], v[34:37]
	v_mfma_f32_16x16x32_bf16 v[22:25], v[182:185], v[154:157], v[22:25]
	v_mfma_f32_16x16x32_bf16 v[18:21], v[190:193], v[154:157], v[18:21]
	v_mfma_f32_16x16x32_bf16 v[6:9], v[182:185], v[174:177], v[6:9]
	v_mfma_f32_16x16x32_bf16 v[2:5], v[190:193], v[174:177], v[2:5]
	v_mfma_f32_16x16x32_bf16 v[50:53], v[182:185], v[130:133], v[50:53]
	v_mfma_f32_16x16x32_bf16 v[54:57], v[190:193], v[130:133], v[54:57]
	s_setprio 0
	s_add_i32 s72, 0, 0x18000
	v_add_u32_e32 v1, s72, v223
	s_barrier
	ds_read_b128 v[58:61], v1
	ds_read_b128 v[62:65], v1 offset:1024
	ds_read_b128 v[82:85], v1 offset:2048
	ds_read_b128 v[86:89], v1 offset:3072
	s_add_u32 s42, s42, s4
	s_addc_u32 s43, s43, 0
	s_mov_b32 m0, s81
	v_lshl_add_u64 v[134:135], s[42:43], 0, v[202:203]
	ds_read_b128 v[118:121], v230 offset:32768
	ds_read_b128 v[130:133], v230 offset:33792
	ds_read_b128 v[146:149], v230 offset:34816
	ds_read_b128 v[154:157], v230 offset:35840
	ds_read_b128 v[170:173], v230 offset:36864
	ds_read_b128 v[174:177], v230 offset:37888
	ds_read_b128 v[178:181], v230 offset:38912
	ds_read_b128 v[182:185], v230 offset:39936
	v_lshl_add_u64 v[134:135], s[42:43], 0, v[200:201]
	s_mov_b32 m0, s82
	s_nop 0
	s_waitcnt lgkmcnt(8)
	s_barrier
	s_waitcnt lgkmcnt(0)
	s_setprio 1
	s_waitcnt lgkmcnt(0)
	v_mfma_f32_16x16x32_bf16 v[134:137], v[58:61], v[118:121], v[166:169]
	v_mfma_f32_16x16x32_bf16 v[166:169], v[62:65], v[130:133], v[134:137]
	v_mfma_f32_16x16x32_bf16 v[134:137], v[82:85], v[118:121], v[162:165]
	v_mfma_f32_16x16x32_bf16 v[162:165], v[86:89], v[130:133], v[134:137]
	v_mfma_f32_16x16x32_bf16 v[134:137], v[58:61], v[146:149], v[142:145]
	v_mfma_f32_16x16x32_bf16 v[142:145], v[62:65], v[154:157], v[134:137]
	v_mfma_f32_16x16x32_bf16 v[134:137], v[82:85], v[146:149], v[138:141]
	v_mfma_f32_16x16x32_bf16 v[126:129], v[58:61], v[170:173], v[126:129]
	v_mfma_f32_16x16x32_bf16 v[122:125], v[82:85], v[170:173], v[122:125]
	v_mfma_f32_16x16x32_bf16 v[110:113], v[58:61], v[178:181], v[110:113]
	v_mfma_f32_16x16x32_bf16 v[106:109], v[82:85], v[178:181], v[106:109]
	v_mfma_f32_16x16x32_bf16 v[138:141], v[86:89], v[154:157], v[134:137]
	v_mfma_f32_16x16x32_bf16 v[126:129], v[62:65], v[174:177], v[126:129]
	v_mfma_f32_16x16x32_bf16 v[122:125], v[86:89], v[174:177], v[122:125]
	v_mfma_f32_16x16x32_bf16 v[110:113], v[62:65], v[182:185], v[110:113]
	v_mfma_f32_16x16x32_bf16 v[106:109], v[86:89], v[182:185], v[106:109]
	s_setprio 0
	s_barrier
	s_add_i32 s42, 0, 0x1c000
	s_add_i32 s43, s72, s78
	v_add_u32_e32 v1, s42, v223
	v_lshl_add_u64 v[134:135], v[214:215], 0, s[22:23]
	s_mov_b32 m0, s43
	ds_read_b128 v[186:189], v1
	ds_read_b128 v[190:193], v1 offset:1024
	ds_read_b128 v[208:211], v1 offset:2048
	ds_read_b128 v[232:235], v1 offset:3072
	v_lshl_add_u64 v[134:135], v[236:237], 0, s[22:23]
	s_add_i32 m0, s43, 0x2000
	s_nop 0
	s_barrier
	s_waitcnt lgkmcnt(0)
	s_setprio 1
	s_waitcnt lgkmcnt(0)
	v_mfma_f32_16x16x32_bf16 v[66:69], v[208:211], v[118:121], v[66:69]
	v_mfma_f32_16x16x32_bf16 v[134:137], v[186:189], v[118:121], v[158:161]
	v_mfma_f32_16x16x32_bf16 v[150:153], v[232:235], v[130:133], v[66:69]
	v_mfma_f32_16x16x32_bf16 v[66:69], v[186:189], v[146:149], v[70:73]
	v_mfma_f32_16x16x32_bf16 v[158:161], v[190:193], v[130:133], v[134:137]
	v_mfma_f32_16x16x32_bf16 v[134:137], v[190:193], v[154:157], v[66:69]
	v_mfma_f32_16x16x32_bf16 v[66:69], v[208:211], v[146:149], v[74:77]
	v_mfma_f32_16x16x32_bf16 v[130:133], v[232:235], v[154:157], v[66:69]
	v_mfma_f32_16x16x32_bf16 v[66:69], v[186:189], v[170:173], v[78:81]
	v_mfma_f32_16x16x32_bf16 v[118:121], v[190:193], v[174:177], v[66:69]
	v_mfma_f32_16x16x32_bf16 v[66:69], v[208:211], v[170:173], v[114:117]
	v_mfma_f32_16x16x32_bf16 v[114:117], v[232:235], v[174:177], v[66:69]
	v_mfma_f32_16x16x32_bf16 v[66:69], v[186:189], v[178:181], v[102:105]
	v_mfma_f32_16x16x32_bf16 v[102:105], v[190:193], v[182:185], v[66:69]
	v_mfma_f32_16x16x32_bf16 v[66:69], v[208:211], v[178:181], v[98:101]
	v_mfma_f32_16x16x32_bf16 v[98:101], v[232:235], v[182:185], v[66:69]
	s_setprio 0
	s_mov_b32 m0, s86
	v_lshl_add_u64 v[178:179], v[238:239], 0, s[22:23]
	s_barrier
	s_nop 2
	ds_read_b128 v[66:69], v230 offset:49152
	ds_read_b128 v[70:73], v230 offset:50176
	ds_read_b128 v[74:77], v230 offset:51200
	ds_read_b128 v[78:81], v230 offset:52224
	ds_read_b128 v[146:149], v230 offset:53248
	ds_read_b128 v[154:157], v230 offset:54272
	ds_read_b128 v[170:173], v230 offset:55296
	ds_read_b128 v[174:177], v230 offset:56320
	v_lshl_add_u64 v[178:179], v[240:241], 0, s[22:23]
	s_mov_b32 m0, s87
	s_nop 0
	s_barrier
	s_waitcnt lgkmcnt(0)
	s_setprio 1
	s_waitcnt lgkmcnt(0)
	v_mfma_f32_16x16x32_bf16 v[94:97], v[58:61], v[66:69], v[94:97]
	v_mfma_f32_16x16x32_bf16 v[90:93], v[82:85], v[66:69], v[90:93]
	v_mfma_f32_16x16x32_bf16 v[46:49], v[58:61], v[74:77], v[46:49]
	v_mfma_f32_16x16x32_bf16 v[42:45], v[82:85], v[74:77], v[42:45]
	v_mfma_f32_16x16x32_bf16 v[30:33], v[58:61], v[146:149], v[30:33]
	v_mfma_f32_16x16x32_bf16 v[26:29], v[82:85], v[146:149], v[26:29]
	v_mfma_f32_16x16x32_bf16 v[14:17], v[58:61], v[170:173], v[14:17]
	v_mfma_f32_16x16x32_bf16 v[10:13], v[82:85], v[170:173], v[10:13]
	v_mfma_f32_16x16x32_bf16 v[94:97], v[62:65], v[70:73], v[94:97]
	v_mfma_f32_16x16x32_bf16 v[90:93], v[86:89], v[70:73], v[90:93]
	v_mfma_f32_16x16x32_bf16 v[46:49], v[62:65], v[78:81], v[46:49]
	v_mfma_f32_16x16x32_bf16 v[42:45], v[86:89], v[78:81], v[42:45]
	v_mfma_f32_16x16x32_bf16 v[30:33], v[62:65], v[154:157], v[30:33]
	v_mfma_f32_16x16x32_bf16 v[26:29], v[86:89], v[154:157], v[26:29]
	v_mfma_f32_16x16x32_bf16 v[14:17], v[62:65], v[174:177], v[14:17]
	v_mfma_f32_16x16x32_bf16 v[10:13], v[86:89], v[174:177], v[10:13]
	s_setprio 0
	s_barrier
	s_add_i32 s42, s42, s78
	v_lshl_add_u64 v[58:59], v[242:243], 0, s[22:23]
	s_mov_b32 m0, s42
	s_nop 0
	v_lshl_add_u64 v[58:59], v[244:245], 0, s[22:23]
	s_add_i32 m0, s42, 0x2000
	s_nop 0
	s_barrier
	s_setprio 1
	v_mfma_f32_16x16x32_bf16 v[50:53], v[186:189], v[66:69], v[50:53]
	v_mfma_f32_16x16x32_bf16 v[86:89], v[190:193], v[70:73], v[50:53]
	v_mfma_f32_16x16x32_bf16 v[50:53], v[208:211], v[66:69], v[54:57]
	v_mfma_f32_16x16x32_bf16 v[38:41], v[186:189], v[74:77], v[38:41]
	v_mfma_f32_16x16x32_bf16 v[34:37], v[208:211], v[74:77], v[34:37]
	v_mfma_f32_16x16x32_bf16 v[22:25], v[186:189], v[146:149], v[22:25]
	v_mfma_f32_16x16x32_bf16 v[18:21], v[208:211], v[146:149], v[18:21]
	v_mfma_f32_16x16x32_bf16 v[6:9], v[186:189], v[170:173], v[6:9]
	v_mfma_f32_16x16x32_bf16 v[2:5], v[208:211], v[170:173], v[2:5]
	v_mfma_f32_16x16x32_bf16 v[82:85], v[232:235], v[70:73], v[50:53]
	v_mfma_f32_16x16x32_bf16 v[38:41], v[190:193], v[78:81], v[38:41]
	v_mfma_f32_16x16x32_bf16 v[34:37], v[232:235], v[78:81], v[34:37]
	v_mfma_f32_16x16x32_bf16 v[22:25], v[190:193], v[154:157], v[22:25]
	v_mfma_f32_16x16x32_bf16 v[18:21], v[232:235], v[154:157], v[18:21]
	v_mfma_f32_16x16x32_bf16 v[6:9], v[190:193], v[174:177], v[6:9]
	v_mfma_f32_16x16x32_bf16 v[2:5], v[232:235], v[174:177], v[2:5]
	s_setprio 0
	s_add_u32 s27, s27, 0x100
	s_addc_u32 s91, s91, 0
	s_add_u32 s36, s36, 0x100
	s_addc_u32 s37, s37, 0
	s_cmp_ge_u32 s92, s84
	s_mov_b32 s42, s92
	s_barrier
.Ltail_done_1:
	s_lshl_b32 s3, s3, 8
	s_add_i32 s27, s3, s85
	v_lshl_or_b32 v210, s38, 8, v224
	v_or_b32_e32 v146, s27, v221
	v_ashrrev_i32_e32 v147, 31, v146
	v_ashrrev_i32_e32 v211, 31, v210
	v_lshlrev_b64 v[50:51], 2, v[210:211]
	v_lshl_add_u64 v[208:209], v[210:211], 1, s[48:49]
	v_lshlrev_b64 v[148:149], 11, v[146:147]
	v_lshl_add_u64 v[52:53], s[52:53], 0, v[50:51]
	v_lshl_add_u64 v[54:55], s[54:55], 0, v[50:51]
	v_lshl_add_u64 v[148:149], v[208:209], 0, v[148:149]
	global_load_dwordx4 v[74:77], v[52:53], off
	global_load_dwordx4 v[66:69], v[52:53], off offset:16
	global_load_dwordx4 v[78:81], v[54:55], off
	global_load_dwordx4 v[70:73], v[54:55], off offset:16
	global_load_dwordx4 v[58:61], v[52:53], off offset:512
	s_nop 0
	global_load_dwordx4 v[50:53], v[52:53], off offset:528
	s_nop 0
	global_load_dwordx4 v[62:65], v[54:55], off offset:512
	s_nop 0
	global_load_dwordx4 v[54:57], v[54:55], off offset:528
	global_load_dwordx4 v[190:193], v[148:149], off
	global_load_dwordx4 v[186:189], v[148:149], off offset:256
	v_or_b32_e32 v148, 16, v146
	v_ashrrev_i32_e32 v149, 31, v148
	v_lshlrev_b64 v[148:149], 11, v[148:149]
	v_lshl_add_u64 v[148:149], v[208:209], 0, v[148:149]
	global_load_dwordx4 v[182:185], v[148:149], off
	global_load_dwordx4 v[178:181], v[148:149], off offset:256
	v_or_b32_e32 v148, 32, v146
	v_or_b32_e32 v146, 48, v146
	v_ashrrev_i32_e32 v149, 31, v148
	v_ashrrev_i32_e32 v147, 31, v146
	v_lshlrev_b64 v[148:149], 11, v[148:149]
	v_lshlrev_b64 v[146:147], 11, v[146:147]
	v_mov_b32_e32 v1, v222
	v_lshl_add_u64 v[148:149], v[208:209], 0, v[148:149]
	v_lshl_add_u64 v[146:147], v[208:209], 0, v[146:147]
	global_load_dwordx4 v[174:177], v[148:149], off
	global_load_dwordx4 v[170:173], v[148:149], off offset:256
	global_load_dwordx4 v[154:157], v[146:147], off
	s_nop 0
	global_load_dwordx4 v[146:149], v[146:147], off offset:256
	v_cndmask_b32_e64 v211, 0, 1, s[56:57]
	v_cmp_ne_u32_e64 s[42:43], 1, v211
	s_andn2_b64 vcc, exec, s[56:57]
	v_lshl_add_u32 v231, v1, 3, s33
	s_cbranch_vccnz .LBB0_1182
	ds_read_b64 v[214:215], v231
	s_waitcnt lgkmcnt(0)
	v_mov_b32_e32 v212, v215
	s_branch .LBB0_1183
